# A6 forward substitution rewritten by hand: right-looking row-split form on waves 0-3, N stored in a column-major per-lane layout by A4
# speedup vs baseline: 1.0222x; 1.0222x over previous
; #define LAS __attribute__((address_space(3)))
; __device__ __forceinline__ u32x2 pack4(float a, float b, float c, float d) { u32x2 o; o.x = pk2(a, b); o.y = pk2(c, d); return o; }
; #define MFMA16(a, b, c) __builtin_amdgcn_mfma_f32_16x16x32_bf16(a, b, c, 0, 0, 0)
; __device__ __forceinline__ void chunkA_item(const Args& A, LAS unsigned char* lds, int tid, int lane, int wave, int ci, int ci_next, HeadConstA& H) {
;     ...
;     {
;         const int og = wave >> 2, ms = wave & 3;
;         const LAS unsigned char* Bsrc = lds + (og == 0 ? CA_KKT : CA_RT);
;         bf16x8 aB[2], aK[2];
; #pragma unroll
;         for (int ks = 0; ks < 2; ++ks) { aB[ks] = ldsfrag(lds + CA_BT, ms * 16 + fr, ks * 32 + q4 * 8); aK[ks] = ldsfrag(lds + CA_KT, ms * 16 + fr, ks * 32 + q4 * 8); }
;         LAS unsigned char* O1 = lds + (og == 0 ? CA_MAK : CA_MRK);
; #pragma unroll
;         for (int nt = 0; nt < 4; ++nt) {
;             const int t = nt * 16 + fr, s0 = ms * 16 + q4 * 4;
;             if (nt < ms) {
;                 *(LAS u32x2*)(O1 + t * 144 + s0 * 2) = (u32x2){0u, 0u};
;                 if (og == 1) *(LAS u32x2*)(lds + CA_NMRB + t * 144 + s0 * 2) = (u32x2){0u, 0u};
;             } else {
;                 f32x4 acc1 = {0.f, 0.f, 0.f, 0.f}, acc2 = {0.f, 0.f, 0.f, 0.f};
; #pragma unroll
;                 for (int ks = 0; ks < 2; ++ks) { const bf16x8 bb = ldsfrag(Bsrc, t, ks * 32 + q4 * 8); acc1 = MFMA16(aB[ks], bb, acc1); acc2 = MFMA16(aK[ks], bb, acc2); }
;                 float v1[4], v2[4];
; #pragma unroll
;                 for (int jj = 0; jj < 4; ++jj) { const int s = s0 + jj; const bool ok = og == 0 ? (s < t) : (s <= t); v1[jj] = ok ? acc1[jj] : 0.f; v2[jj] = ok ? acc2[jj] : 0.f; }
;                 *(LAS u32x2*)(O1 + t * 144 + s0 * 2) = pack4(v2[0], v2[1], v2[2], v2[3]);
;                 if (og == 0) {
; #pragma unroll
;                     for (int jj = 0; jj < 4; ++jj) ((LAS float*)(lds + CA_N))[t * 64 + jj * 16 + ms * 4 + q4] = v1[jj];
;                 } else *(LAS u32x2*)(lds + CA_NMRB + t * 144 + s0 * 2) = pack4(-v1[0], -v1[1], -v1[2], -v1[3]);
;             }
;         }
;     }
; __global__ void __launch_bounds__(512, 2) hymba_fwd(Args A) {
;     ...
;         { HeadConstA HC; HC.h = -1;
;           for (int it = blockIdx.x; it < N_CH; it += gridDim.x) chunkA_item(A, lds, tid, lane, wave, it, it + (int)gridDim.x, HC); }
.LBB0_143:
	s_or_b64 exec, exec, s[4:5]
	s_add_u32 s4, s96, 0xd80000
	s_addc_u32 s5, s97, 0
	v_writelane_b32 v249, s4, 32
	v_lshrrev_b32_e32 v0, 2, v144
	v_lshlrev_b32_e32 v137, 2, v145
	v_writelane_b32 v249, s5, 33
	s_add_u32 s4, s96, 0xda0000
	s_addc_u32 s5, s97, 0
	v_writelane_b32 v249, s4, 34
	s_cmpk_gt_i32 s2, 0xfff
	v_and_b32_e32 v89, 48, v144
	v_cmp_eq_u32_e64 s[82:83], 0, v145
	v_or_b32_e32 v88, 48, v145
	v_writelane_b32 v249, s5, 35
	s_barrier
	s_cbranch_scc1 .LBB0_261
	v_mov_b32_e32 v73, 0
	v_readlane_b32 s4, v249, 32
	s_add_i32 s3, 0, 0x18800
	v_mov_b32_e32 v135, v73
	v_readlane_b32 s5, v249, 33
	v_readlane_b32 s10, v249, 3
	v_add_u32_e32 v79, s3, v137
	v_lshl_add_u64 v[74:75], s[4:5], 0, v[134:135]
	v_readlane_b32 s4, v249, 34
	s_lshl_b32 s3, s10, 3
	v_readlane_b32 s5, v249, 35
	s_and_b32 s91, s3, 0x1fffffe0
	v_lshlrev_b32_e32 v2, 5, v207
	v_lshl_add_u64 v[76:77], s[4:5], 0, v[134:135]
	s_or_b32 s4, s91, 16
	v_writelane_b32 v249, s4, 36
	v_or_b32_e32 v72, 0x1800, v2
	v_readlane_b32 s56, v249, 0
	s_bfe_u32 s13, s56, 0x20006
	s_lshl_b32 s5, s13, 4
	s_movk_i32 s4, 0x90
	v_lshl_add_u64 v[80:81], s[60:61], 0, v[72:73]
	v_or_b32_e32 v72, 0x1900, v2
	v_or_b32_e32 v2, s5, v132
	v_mad_u32_u24 v5, v2, s4, 0
	v_lshrrev_b32_e32 v2, 2, v145
	v_and_b32_e32 v2, 12, v2
	s_lshr_b32 s18, s56, 8
	v_or_b32_e32 v12, s5, v2
	v_lshl_or_b32 v6, s18, 5, v132
	v_lshlrev_b32_e32 v7, 6, v12
	v_add_lshl_u32 v8, v7, v6, 2
	s_add_i32 s6, 0, 0x10800
	s_add_i32 s7, 0, 0x14800
	v_add_u32_e32 v114, s6, v8
	v_add_u32_e32 v115, s7, v8
	v_or_b32_e32 v8, 64, v7
	v_add_lshl_u32 v9, v8, v6, 2
	v_add_u32_e32 v116, s6, v9
	v_add_u32_e32 v117, s7, v9
	v_or_b32_e32 v9, 0x80, v7
	v_add_lshl_u32 v10, v9, v6, 2
	v_add_u32_e32 v118, s6, v10
	v_add_u32_e32 v119, s7, v10
	v_or_b32_e32 v10, 0xc0, v7
	v_add_lshl_u32 v11, v10, v6, 2
	v_or_b32_e32 v6, 16, v6
	v_add_lshl_u32 v7, v7, v6, 2
	v_add_u32_e32 v122, s6, v7
	v_add_u32_e32 v123, s7, v7
	v_add_lshl_u32 v7, v8, v6, 2
	v_add_u32_e32 v124, s6, v7
	v_add_u32_e32 v125, s7, v7
	v_add_lshl_u32 v7, v9, v6, 2
	v_add_lshl_u32 v6, v10, v6, 2
	v_add_u32_e32 v135, s6, v6
	v_add_u32_e32 v139, s7, v6
	v_lshl_or_b32 v6, s10, 11, v137
	v_add_u32_e32 v126, s6, v7
	v_add_u32_e32 v127, s7, v7
	v_or_b32_e32 v7, 0x100, v6
	v_add_u32_e32 v149, s6, v7
	v_add_u32_e32 v150, s7, v7
	v_or_b32_e32 v7, 0x200, v6
	v_add_u32_e32 v151, s6, v7
	v_add_u32_e32 v152, s7, v7
	v_or_b32_e32 v7, 0x300, v6
	v_add_u32_e32 v153, s6, v7
	v_add_u32_e32 v154, s7, v7
	v_or_b32_e32 v7, 0x400, v6
	v_add_u32_e32 v155, s6, v7
	v_add_u32_e32 v156, s7, v7
	v_or_b32_e32 v7, 0x500, v6
	v_add_u32_e32 v141, s6, v6
	v_add_u32_e32 v143, 0, v6
	v_add_u32_e32 v148, s7, v6
	v_add_u32_e32 v157, s6, v7
	v_add_u32_e32 v158, s7, v7
	v_or_b32_e32 v7, 0x600, v6
	v_or_b32_e32 v6, 0x700, v6
	v_add_u32_e32 v120, s6, v11
	v_add_u32_e32 v159, s6, v7
	v_add_u32_e32 v161, s6, v6
	s_lshl_b32 s6, s10, 8
	s_cmp_lt_u32 s56, 64
	s_cselect_b64 s[14:15], -1, 0
	s_cmpk_gt_u32 s56, 0x7f
	v_add_u32_e32 v121, s7, v11
	v_add_u32_e32 v160, s7, v7
	v_add_u32_e32 v163, s7, v6
	v_writelane_b32 v249, s6, 37
	s_cselect_b64 s[6:7], -1, 0
	v_writelane_b32 v249, s6, 38
	s_cmpk_gt_u32 s56, 0xbf
	s_mov_b32 s11, 0x1d100
	v_writelane_b32 v249, s7, 39
	s_cselect_b64 s[6:7], -1, 0
	s_cmpk_gt_u32 s56, 0xff
	v_writelane_b32 v249, s6, 40
	s_cselect_b64 s[8:9], -1, 0
	s_cmpk_gt_u32 s56, 0x13f
	v_writelane_b32 v249, s7, 41
	s_cselect_b64 s[6:7], -1, 0
	v_writelane_b32 v249, s6, 42
	s_cmpk_gt_u32 s56, 0x17f
	v_lshlrev_b32_e32 v9, 1, v12
	v_writelane_b32 v249, s7, 43
	s_cselect_b64 s[6:7], -1, 0
	v_writelane_b32 v249, s6, 44
	s_cmpk_gt_u32 s56, 0x1bf
	v_cmp_le_u32_e64 s[20:21], v12, v132
	v_writelane_b32 v249, s7, 45
	s_cselect_b64 s[6:7], -1, 0
	v_writelane_b32 v249, s6, 46
	s_cmpk_gt_u32 s56, 0x1ff
	v_cndmask_b32_e64 v10, 0, 1, s[20:21]
	v_writelane_b32 v249, s7, 47
	s_cselect_b64 s[6:7], -1, 0
	v_writelane_b32 v249, s6, 48
	v_cmp_le_u32_e64 s[46:47], v12, v88
	s_movk_i32 s5, 0x100
	v_writelane_b32 v249, s7, 49
	s_add_u32 s6, s96, 0x1cb00000
	v_writelane_b32 v249, s6, 50
	s_addc_u32 s6, s97, 0
	v_writelane_b32 v249, s6, 51
	s_or_b32 s6, s3, 1
	s_mulk_i32 s6, 0x90
	s_lshl_b32 s12, s10, 5
	v_writelane_b32 v249, s6, 52
	s_lshl_b32 s79, s10, 4
	s_add_i32 s78, s12, 0
	s_add_i32 s6, 0, 0x19000
	s_cmpk_lt_u32 s56, 0x100
	s_cselect_b64 s[50:51], -1, 0
	s_and_b64 s[16:17], s[50:51], exec
	s_cselect_b32 s7, 0, 0x6c00
	s_cselect_b32 s11, s11, 0x21900
	s_add_i32 s7, s7, 0
	s_add_i32 s16, s11, 0
	s_add_i32 s11, 0, 0x19100
	s_add_i32 s17, s11, s79
	v_add_u32_e32 v166, s7, v89
	s_add_i32 s7, 0, 0x1f500
	s_cmp_eq_u32 s18, 1
	v_add_u32_e32 v7, s17, v2
	v_add_u32_e32 v167, s16, v9
	s_cselect_b64 s[16:17], -1, 0
	v_cmp_lt_u32_e64 s[18:19], v12, v132
	v_add_u32_e32 v168, s7, v9
	v_writelane_b32 v249, s16, 53
	s_cmp_lg_u32 s13, 0
	v_cndmask_b32_e64 v9, 0, 1, s[18:19]
	v_writelane_b32 v249, s17, 54
	s_cselect_b64 s[16:17], -1, 0
	v_cndmask_b32_e64 v9, v10, v9, s[50:51]
	v_writelane_b32 v249, s16, 55
	v_and_b32_e32 v9, 1, v9
	v_cndmask_b32_e64 v10, 0, 1, s[50:51]
	v_writelane_b32 v249, s17, 56
	v_cmp_eq_u32_e64 s[16:17], 1, v9
	v_or_b32_e32 v9, v2, v10
	s_cmp_lt_u32 s13, 2
	v_writelane_b32 v249, s16, 57
	v_add_u32_e32 v171, 0, v89
	s_movk_i32 s10, 0x110
	v_writelane_b32 v249, s17, 58
	v_cmp_gt_u32_e64 s[16:17], v132, v9
	v_or_b32_e32 v9, 2, v2
	v_cmp_lt_u32_e64 s[22:23], v9, v132
	v_cmp_le_u32_e64 s[24:25], v9, v132
	v_writelane_b32 v249, s16, 59
	v_cndmask_b32_e64 v9, 0, 1, s[22:23]
	v_cndmask_b32_e64 v11, 0, 1, s[24:25]
	v_cndmask_b32_e64 v9, v11, v9, s[50:51]
	v_and_b32_e32 v9, 1, v9
	v_writelane_b32 v249, s17, 60
	v_cmp_eq_u32_e64 s[16:17], 1, v9
; #define LAS __attribute__((address_space(3)))
; __device__ __forceinline__ u32x2 pack4(float a, float b, float c, float d) { u32x2 o; o.x = pk2(a, b); o.y = pk2(c, d); return o; }
; #define MFMA16(a, b, c) __builtin_amdgcn_mfma_f32_16x16x32_bf16(a, b, c, 0, 0, 0)
; __device__ __forceinline__ void chunkA_item(const Args& A, LAS unsigned char* lds, int tid, int lane, int wave, int ci, int ci_next, HeadConstA& H) {
;     ...
;             } else {
;                 f32x4 acc1 = {0.f, 0.f, 0.f, 0.f}, acc2 = {0.f, 0.f, 0.f, 0.f};
; #pragma unroll
;                 for (int ks = 0; ks < 2; ++ks) { const bf16x8 bb = ldsfrag(Bsrc, t, ks * 32 + q4 * 8); acc1 = MFMA16(aB[ks], bb, acc1); acc2 = MFMA16(aK[ks], bb, acc2); }
;                 float v1[4], v2[4];
; #pragma unroll
;                 for (int jj = 0; jj < 4; ++jj) { const int s = s0 + jj; const bool ok = og == 0 ? (s < t) : (s <= t); v1[jj] = ok ? acc1[jj] : 0.f; v2[jj] = ok ? acc2[jj] : 0.f; }
;                 *(LAS u32x2*)(O1 + t * 144 + s0 * 2) = pack4(v2[0], v2[1], v2[2], v2[3]);
;                 if (og == 0) {
; #pragma unroll
;                     for (int jj = 0; jj < 4; ++jj) ((LAS float*)(lds + CA_N))[t * 64 + jj * 16 + ms * 4 + q4] = v1[jj];
;                 } else *(LAS u32x2*)(lds + CA_NMRB + t * 144 + s0 * 2) = pack4(-v1[0], -v1[1], -v1[2], -v1[3]);
	v_or_b32_e32 v9, 3, v2
	v_cmp_lt_u32_e64 s[24:25], v9, v132
	v_cmp_le_u32_e64 s[26:27], v9, v132
	v_writelane_b32 v249, s16, 61
	v_cndmask_b32_e64 v9, 0, 1, s[24:25]
	v_cndmask_b32_e64 v11, 0, 1, s[26:27]
	v_cndmask_b32_e64 v9, v11, v9, s[50:51]
	v_and_b32_e32 v9, 1, v9
	v_or_b32_e32 v11, 16, v132
	v_writelane_b32 v249, s17, 62
	v_cmp_eq_u32_e64 s[16:17], 1, v9
	v_cmp_lt_u32_e64 s[26:27], v12, v11
	v_cmp_le_u32_e64 s[28:29], v12, v11
	v_writelane_b32 v249, s16, 63
	v_cndmask_b32_e64 v13, 0, 1, s[26:27]
	v_cndmask_b32_e64 v14, 0, 1, s[28:29]
	v_writelane_b32 v248, s17, 0
	s_cselect_b64 s[16:17], -1, 0
	v_cndmask_b32_e64 v13, v14, v13, s[50:51]
	v_writelane_b32 v248, s16, 1
	v_and_b32_e32 v13, 1, v13
	v_or_b32_e32 v14, 2, v12
	v_writelane_b32 v248, s17, 2
	v_cmp_eq_u32_e64 s[16:17], 1, v13
	v_cmp_lt_u32_e64 s[30:31], v14, v11
	v_cmp_le_u32_e64 s[34:35], v14, v11
	v_writelane_b32 v248, s16, 3
	v_or_b32_e32 v13, v12, v10
	v_cndmask_b32_e64 v10, 0, 1, s[30:31]
	v_cndmask_b32_e64 v15, 0, 1, s[34:35]
	v_writelane_b32 v248, s17, 4
	v_cmp_gt_u32_e64 s[16:17], v11, v13
	v_cndmask_b32_e64 v10, v15, v10, s[50:51]
	v_or_b32_e32 v15, 3, v12
	v_writelane_b32 v248, s16, 5
	v_and_b32_e32 v10, 1, v10
	v_cmp_lt_u32_e64 s[34:35], v15, v11
	v_cmp_le_u32_e64 s[36:37], v15, v11
	v_writelane_b32 v248, s17, 6
	v_cmp_eq_u32_e64 s[16:17], 1, v10
	v_cndmask_b32_e64 v10, 0, 1, s[34:35]
	v_cndmask_b32_e64 v16, 0, 1, s[36:37]
	v_cndmask_b32_e64 v10, v16, v10, s[50:51]
	v_writelane_b32 v248, s16, 7
	v_and_b32_e32 v10, 1, v10
	s_cmp_lg_u32 s13, 3
	v_writelane_b32 v248, s17, 8
	v_cmp_eq_u32_e64 s[16:17], 1, v10
	v_lshlrev_b32_e32 v10, 8, v11
	v_or_b32_e32 v11, 32, v132
	v_cmp_lt_u32_e64 s[36:37], v12, v11
	v_cmp_le_u32_e64 s[38:39], v12, v11
	v_writelane_b32 v248, s16, 9
	v_cndmask_b32_e64 v16, 0, 1, s[36:37]
	v_cndmask_b32_e64 v17, 0, 1, s[38:39]
	v_writelane_b32 v248, s17, 10
	s_cselect_b64 s[16:17], -1, 0
	v_cndmask_b32_e64 v16, v17, v16, s[50:51]
	v_writelane_b32 v248, s16, 11
	v_and_b32_e32 v16, 1, v16
	v_cmp_lt_u32_e64 s[40:41], v14, v11
	v_writelane_b32 v248, s17, 12
	v_cmp_eq_u32_e64 s[16:17], 1, v16
	v_cmp_le_u32_e64 s[42:43], v14, v11
	v_cndmask_b32_e64 v16, 0, 1, s[40:41]
	v_writelane_b32 v248, s16, 13
	v_cndmask_b32_e64 v17, 0, 1, s[42:43]
	v_cndmask_b32_e64 v16, v17, v16, s[50:51]
	v_writelane_b32 v248, s17, 14
	v_cmp_gt_u32_e64 s[16:17], v11, v13
	v_and_b32_e32 v16, 1, v16
	v_cmp_lt_u32_e64 s[42:43], v15, v11
	v_writelane_b32 v248, s16, 15
	v_cmp_le_u32_e64 s[44:45], v15, v11
	v_cmp_lt_u32_e64 s[48:49], v14, v88
	v_writelane_b32 v248, s17, 16
	v_cmp_eq_u32_e64 s[16:17], 1, v16
	v_cndmask_b32_e64 v16, 0, 1, s[42:43]
	v_cndmask_b32_e64 v17, 0, 1, s[44:45]
	v_cndmask_b32_e64 v16, v17, v16, s[50:51]
	v_writelane_b32 v248, s16, 17
	v_and_b32_e32 v16, 1, v16
	v_cmp_lt_u32_e64 s[44:45], v12, v88
	v_writelane_b32 v248, s17, 18
	v_cmp_eq_u32_e64 s[16:17], 1, v16
	v_cndmask_b32_e64 v12, 0, 1, s[44:45]
	v_cndmask_b32_e64 v16, 0, 1, s[46:47]
	v_cndmask_b32_e64 v12, v16, v12, s[50:51]
	v_and_b32_e32 v12, 1, v12
	v_cmp_le_u32_e64 s[52:53], v14, v88
	v_cmp_eq_u32_e64 s[44:45], 1, v12
	v_cmp_gt_u32_e64 s[46:47], v88, v13
	v_cndmask_b32_e64 v12, 0, 1, s[48:49]
	v_cndmask_b32_e64 v13, 0, 1, s[52:53]
	v_cndmask_b32_e64 v12, v13, v12, s[50:51]
	v_writelane_b32 v248, s16, 19
	v_and_b32_e32 v12, 1, v12
	v_cmp_lt_u32_e64 s[52:53], v15, v88
	v_cmp_le_u32_e64 s[54:55], v15, v88
	s_lshr_b32 s13, s56, 7
	v_and_or_b32 v15, s12, 32, v132
	v_writelane_b32 v248, s17, 20
	v_cmp_eq_u32_e64 s[48:49], 1, v12
	v_cndmask_b32_e64 v12, 0, 1, s[52:53]
	s_lshl_b32 s16, s13, 4
	s_lshl_b32 s13, s13, 6
	v_mul_u32_u24_e32 v16, 0x110, v15
	v_subrev_co_u32_e64 v175, s[52:53], s5, v144
	v_add3_u32 v16, v171, s13, v16
	s_xor_b64 s[12:13], s[52:53], -1
	v_writelane_b32 v248, s12, 21
	s_movk_i32 s5, 0x245
	s_add_i32 s17, 0, 0x1d100
	v_writelane_b32 v248, s13, 22
; #define LAS __attribute__((address_space(3)))
; #define MFMA16(a, b, c) __builtin_amdgcn_mfma_f32_16x16x32_bf16(a, b, c, 0, 0, 0)
; __device__ __forceinline__ void chunkA_item(const Args& A, LAS unsigned char* lds, int tid, int lane, int wave, int ci, int ci_next, HeadConstA& H) {
;     ...
;     {
;         const int og = wave >> 2, ms = wave & 3;
;         const LAS unsigned char* Bsrc = lds + (og == 0 ? CA_KKT : CA_RT);
;         bf16x8 aB[2], aK[2];
; #pragma unroll
;         for (int ks = 0; ks < 2; ++ks) { aB[ks] = ldsfrag(lds + CA_BT, ms * 16 + fr, ks * 32 + q4 * 8); aK[ks] = ldsfrag(lds + CA_KT, ms * 16 + fr, ks * 32 + q4 * 8); }
;         LAS unsigned char* O1 = lds + (og == 0 ? CA_MAK : CA_MRK);
; #pragma unroll
;         for (int nt = 0; nt < 4; ++nt) {
;             const int t = nt * 16 + fr, s0 = ms * 16 + q4 * 4;
;             if (nt < ms) {
;                 *(LAS u32x2*)(O1 + t * 144 + s0 * 2) = (u32x2){0u, 0u};
;                 if (og == 1) *(LAS u32x2*)(lds + CA_NMRB + t * 144 + s0 * 2) = (u32x2){0u, 0u};
;             } else {
;                 f32x4 acc1 = {0.f, 0.f, 0.f, 0.f}, acc2 = {0.f, 0.f, 0.f, 0.f};
; #pragma unroll
;                 for (int ks = 0; ks < 2; ++ks) { const bf16x8 bb = ldsfrag(Bsrc, t, ks * 32 + q4 * 8); acc1 = MFMA16(aB[ks], bb, acc1); acc2 = MFMA16(aK[ks], bb, acc2); }
;                 float v1[4], v2[4];
; #pragma unroll
;                 for (int jj = 0; jj < 4; ++jj) { const int s = s0 + jj; const bool ok = og == 0 ? (s < t) : (s <= t); v1[jj] = ok ? acc1[jj] : 0.f; v2[jj] = ok ? acc2[jj] : 0.f; }
;                 *(LAS u32x2*)(O1 + t * 144 + s0 * 2) = pack4(v2[0], v2[1], v2[2], v2[3]);
;                 if (og == 0) {
; #pragma unroll
;                     for (int jj = 0; jj < 4; ++jj) ((LAS float*)(lds + CA_N))[t * 64 + jj * 16 + ms * 4 + q4] = v1[jj];
;                 } else *(LAS u32x2*)(lds + CA_NMRB + t * 144 + s0 * 2) = pack4(-v1[0], -v1[1], -v1[2], -v1[3]);
;             }
;         }
;     }
;     ...
;     if (tid < 256) {
;         const int cp = tid >> 2, q = tid & 3;
;         f32x2_t xa[8], xb[8];
; #pragma unroll
;         for (int m = 0; m < 8; ++m) { xa[m] = (f32x2_t){0.f, 0.f}; xb[m] = (f32x2_t){0.f, 0.f}; }
;         const LAS float* Np = (const LAS float*)(lds + CA_N) + q * 16;
;         const LAS float* Ra = (const LAS float*)(lds + CA_RHS) + cp * 68; const LAS float* Rb = Ra + 64 * 68;
	v_cmp_gt_u32_e64 s[12:13], s5, v144
	s_add_u32 s5, s96, 0x18b00000
	v_cndmask_b32_e64 v13, 0, 1, s[54:55]
	v_writelane_b32 v248, s12, 23
	v_mad_u32_u24 v177, v0, s10, 0
	v_lshlrev_b32_e32 v0, 7, v0
	v_writelane_b32 v248, s13, 24
	v_writelane_b32 v248, s5, 25
	s_addc_u32 s43, s97, 0
	s_add_i32 s5, s16, 64
	v_cndmask_b32_e64 v12, v13, v12, s[50:51]
	v_sub_u32_e32 v19, 0, v0
	v_or_b32_e32 v0, s5, v132
	v_and_b32_e32 v12, 1, v12
	v_mul_lo_u32 v0, v0, s4
	v_cmp_eq_u32_e64 s[50:51], 1, v12
	v_or_b32_e32 v12, s16, v132
	v_add_u32_e32 v20, 0, v0
	v_or_b32_e32 v0, s16, v2
	v_mul_lo_u32 v12, v12, s4
	v_add_u32_e32 v173, 0xfc00, v16
	v_mov_b32_e32 v18, 0x900
	v_add_u32_e32 v174, 0x10d00, v16
	v_and_b32_e32 v16, 3, v144
	v_mov_b32_e32 v2, s7
	s_add_i32 s12, 0, 0x21900
	v_lshlrev_b32_e32 v27, 6, v0
	v_add_u32_e32 v14, s17, v12
	v_or_b32_e32 v17, 16, v15
	v_mad_u32_u24 v18, v15, s4, v18
	v_lshl_add_u32 v176, v16, 6, s11
	v_cmp_eq_u32_e64 s[54:55], 0, v16
	v_cmp_eq_u32_e64 s[56:57], 1, v16
	v_cmp_eq_u32_e64 s[58:59], 2, v16
	v_cmp_eq_u32_e64 s[64:65], 3, v16
	v_add_u32_e32 v16, 0, v12
	v_or_b32_e32 v12, 1, v0
	v_or_b32_e32 v21, 3, v0
	v_or_b32_e32 v22, 2, v0
	v_mad_u32_u24 v25, v15, s4, v2
	v_mov_b32_e32 v2, s12
	v_or_b32_e32 v28, 64, v27
	v_or_b32_e32 v29, 0x80, v27
	v_or_b32_e32 v30, 0xc0, v27
	v_cmp_gt_u32_e32 vcc, 8, v144
	v_mad_u32_u24 v1, v147, s4, 0
	v_lshlrev_b32_e32 v3, 4, v207
	v_lshlrev_b32_e32 v4, 5, v144
	v_mad_u32_u24 v8, v145, s4, 0
	v_mul_u32_u24_e32 v6, 0x110, v145
	v_lshlrev_b32_e32 v9, 8, v132
	v_lshlrev_b32_e32 v11, 8, v11
	v_lshlrev_b32_e32 v13, 8, v88
	v_mul_u32_u24_e32 v172, 0x90, v15
	v_lshl_add_u32 v23, v0, 1, 0
	v_mad_u32_u24 v24, v15, s4, 0
	v_mad_u32_u24 v26, v15, s4, v2
	v_lshl_add_u32 v179, v15, 2, s6
	v_cmp_eq_u32_e64 s[20:21], v0, v15
	v_cmp_eq_u32_e64 s[10:11], v12, v15
	v_cmp_eq_u32_e64 s[52:53], v21, v15
	v_cmp_eq_u32_e64 s[4:5], v22, v15
	v_lshlrev_b32_e32 v2, 6, v15
	v_or_b32_e32 v84, v27, v15
	v_or_b32_e32 v86, v28, v15
	v_or_b32_e32 v90, v29, v15
	v_or_b32_e32 v92, v30, v15
	v_add_u32_e32 v15, 0, v18
	v_add_u32_e32 v31, s7, v18
	v_add_u32_e32 v18, s12, v18
	v_cmp_eq_u32_e64 s[12:13], v12, v17
	v_lshlrev_b32_e32 v12, 6, v17
	v_lshlrev_b32_e32 v78, 3, v207
	v_lshl_add_u64 v[82:83], s[60:61], 0, v[72:73]
	v_lshl_add_u32 v164, v145, 1, 0
	v_add_u32_e32 v165, s6, v137
	v_mul_u32_u24_e32 v169, 0x90, v132
	v_mul_u32_u24_e32 v170, 0x90, v88
	v_add_u32_e32 v178, 0xfc00, v177
	v_mov_b32_e32 v85, v73
	v_mov_b32_e32 v87, v73
	v_mov_b32_e32 v91, v73
	v_mov_b32_e32 v93, v73
	v_lshl_add_u32 v180, v17, 2, s6
	v_cmp_eq_u32_e64 s[6:7], v0, v17
	v_cmp_eq_u32_e64 s[16:17], v21, v17
	v_cmp_eq_u32_e64 s[18:19], v22, v17
	v_or_b32_e32 v94, v17, v27
	v_mov_b32_e32 v95, v73
	v_or_b32_e32 v96, v28, v17
	v_mov_b32_e32 v97, v73
	v_or_b32_e32 v98, v29, v17
	v_mov_b32_e32 v99, v73
	v_or_b32_e32 v100, v30, v17
	v_mov_b32_e32 v101, v73
	s_mov_b32 s29, -1
	s_xor_b64 s[26:27], vcc, -1
	s_movk_i32 s22, 0x1c00
	v_add_u32_e32 v181, s79, v8
	v_add_u32_e32 v182, s78, v6
	v_bfe_u32 v183, v144, 4, 4
	v_lshlrev_b32_e32 v183, 10, v183
	v_and_b32_e32 v184, 3, v144
	v_lshl_add_u32 v183, v184, 6, v183
	v_bfe_u32 v184, v144, 2, 2
	v_lshl_add_u32 v183, v184, 2, v183
	v_add_u32_e32 v183, 0x19100, v183
	v_add_u32_e32 v187, v14, v89
	v_add_u32_e32 v188, v16, v89
	v_add_u32_e32 v189, v20, v89
	v_lshlrev_b32_e32 v102, 1, v0
	v_add_u32_e32 v190, v24, v89
	v_add_u32_e32 v191, v25, v89
	v_add_u32_e32 v192, v26, v89
	v_lshlrev_b32_e32 v104, 1, v2
	v_add_u32_e32 v193, v23, v172
	v_add_u32_e32 v194, v15, v89
	v_add_u32_e32 v195, v31, v89
	v_add_u32_e32 v196, v18, v89
	v_lshlrev_b32_e32 v106, 1, v12
	v_add_u32_e32 v197, 0, v4
	v_add_u32_e32 v198, v1, v3
	v_add_u32_e32 v199, v5, v89
	v_mov_b32_e32 v224, v73
	v_mov_b32_e32 v225, v73
	v_mov_b32_e32 v200, 0x640
	v_mov_b32_e32 v201, 0x600
	v_add_u32_e32 v202, v177, v19
	s_mov_b32 s28, s2
	s_branch .LBB0_147

; #define LAS __attribute__((address_space(3)))
; __device__ __forceinline__ void chunkA_item(const Args& A, LAS unsigned char* lds, int tid, int lane, int wave, int ci, int ci_next, HeadConstA& H) {
;     ...
;                     for (int jj = 0; jj < 4; ++jj) ((LAS float*)(lds + CA_N))[t * 64 + jj * 16 + ms * 4 + q4] = v1[jj];
.LBB0_186:
	s_andn2_b64 vcc, exec, s[24:25]
	s_cbranch_vccnz .LBB0_188
	ds_write2_b32 v183, v50, v51 offset1:64
	ds_write2_b32 v183, v52, v53 offset0:128 offset1:192

; #define LAS __attribute__((address_space(3)))
; __device__ __forceinline__ void chunkA_item(const Args& A, LAS unsigned char* lds, int tid, int lane, int wave, int ci, int ci_next, HeadConstA& H) {
;     ...
;                     for (int jj = 0; jj < 4; ++jj) ((LAS float*)(lds + CA_N))[t * 64 + jj * 16 + ms * 4 + q4] = v1[jj];
.LBB0_191:
	s_andn2_b64 vcc, exec, s[24:25]
	s_cbranch_vccnz .LBB0_193
	ds_write2_b32 v183, v50, v51 offset0:4 offset1:68
	ds_write2_b32 v183, v52, v53 offset0:132 offset1:196

; #define LAS __attribute__((address_space(3)))
; __device__ __forceinline__ void chunkA_item(const Args& A, LAS unsigned char* lds, int tid, int lane, int wave, int ci, int ci_next, HeadConstA& H) {
;     ...
;                     for (int jj = 0; jj < 4; ++jj) ((LAS float*)(lds + CA_N))[t * 64 + jj * 16 + ms * 4 + q4] = v1[jj];
.LBB0_200:
	s_andn2_b64 vcc, exec, s[24:25]
	s_cbranch_vccnz .LBB0_202
	ds_write2_b32 v183, v49, v50 offset0:8 offset1:72
	ds_write2_b32 v183, v51, v52 offset0:136 offset1:200

; #define LAS __attribute__((address_space(3)))
; __device__ __forceinline__ void chunkA_item(const Args& A, LAS unsigned char* lds, int tid, int lane, int wave, int ci, int ci_next, HeadConstA& H) {
;     ...
;                     for (int jj = 0; jj < 4; ++jj) ((LAS float*)(lds + CA_N))[t * 64 + jj * 16 + ms * 4 + q4] = v1[jj];
.LBB0_208:
	s_andn2_b64 vcc, exec, s[24:25]
	s_cbranch_vccnz .LBB0_210
	ds_write2_b32 v183, v32, v33 offset0:12 offset1:76
	ds_write2_b32 v183, v34, v35 offset0:140 offset1:204

; #define LAS __attribute__((address_space(3)))
; template <int CTRL> __device__ __forceinline__ float dppf(float x) { return __builtin_bit_cast(float, __builtin_amdgcn_update_dpp(0, __builtin_bit_cast(int, x), CTRL, 0xf, 0xf, false)); }
; __device__ __forceinline__ u32x2 pack4(float a, float b, float c, float d) { u32x2 o; o.x = pk2(a, b); o.y = pk2(c, d); return o; }
; __device__ __forceinline__ void chunkA_item(const Args& A, LAS unsigned char* lds, int tid, int lane, int wave, int ci, int ci_next, HeadConstA& H) {
;     ...
;     if (tid < 256) {
;         const int cp = tid >> 2, q = tid & 3;
;         f32x2_t xa[8], xb[8];
; #pragma unroll
;         for (int m = 0; m < 8; ++m) { xa[m] = (f32x2_t){0.f, 0.f}; xb[m] = (f32x2_t){0.f, 0.f}; }
;         const LAS float* Np = (const LAS float*)(lds + CA_N) + q * 16;
;         const LAS float* Ra = (const LAS float*)(lds + CA_RHS) + cp * 68; const LAS float* Rb = Ra + 64 * 68;
;         float a4[4], b4[4];
; #pragma unroll
;         for (int t = 0; t < 64; ++t) {
;             f32x2_t sa = {0.f, 0.f}, sb = {0.f, 0.f};
; #pragma unroll
;             for (int p = 0; p < ((t + 3) / 4 + 1) / 2; ++p) { const f32x2_t nv = *(const LAS f32x2_t*)(Np + t * 64 + 2 * p); sa += nv * xa[p]; sb += nv * xb[p]; }
;             float ua = sa.x + sa.y, ub = sb.x + sb.y;
;             ua += dppf<0xB1>(ua); ub += dppf<0xB1>(ub); ua += dppf<0x4E>(ua); ub += dppf<0x4E>(ub);
;             const float xta = Ra[t] - ua, xtb = Rb[t] - ub;
;             if (q == (t & 3)) { if ((t >> 2) & 1) { xa[t >> 3].y = xta; xb[t >> 3].y = xtb; } else { xa[t >> 3].x = xta; xb[t >> 3].x = xtb; } }
;             a4[t & 3] = xta; b4[t & 3] = xtb;
;             if ((t & 3) == 3 && q == 0) { *(LAS u32x2*)(lds + CA_XT + cp * 144 + (t - 3) * 2) = pack4(a4[0], a4[1], a4[2], a4[3]);
;                 *(LAS u32x2*)(lds + CA_XT + (64 + cp) * 144 + (t - 3) * 2) = pack4(b4[0], b4[1], b4[2], b4[3]); }
;         }
.LBB0_228:
	s_andn2_saveexec_b64 s[78:79], s[78:79]
	s_cbranch_execz .LBB0_146
	v_and_b32_e32 v72, 3, v144
	v_lshl_add_u32 v222, v72, 2, v178
	v_lshl_add_u32 v72, v72, 2, v177
	ds_read_b32 v32, v72 offset:64512
	ds_read_b32 v33, v222 offset:17408
	ds_read_b32 v34, v72 offset:64528
	ds_read_b32 v35, v222 offset:17424
	ds_read_b32 v36, v72 offset:64544
	ds_read_b32 v37, v222 offset:17440
	ds_read_b32 v38, v72 offset:64560
	ds_read_b32 v39, v222 offset:17456
	ds_read_b32 v40, v72 offset:64576
	ds_read_b32 v41, v222 offset:17472
	ds_read_b32 v42, v72 offset:64592
	ds_read_b32 v43, v222 offset:17488
	ds_read_b32 v44, v72 offset:64608
	ds_read_b32 v45, v222 offset:17504
	ds_read_b32 v46, v72 offset:64624
	ds_read_b32 v47, v222 offset:17520
	ds_read_b32 v48, v72 offset:64640
	ds_read_b32 v49, v222 offset:17536
	ds_read_b32 v50, v72 offset:64656
	ds_read_b32 v51, v222 offset:17552
	ds_read_b32 v52, v72 offset:64672
	ds_read_b32 v53, v222 offset:17568
	ds_read_b32 v54, v72 offset:64688
	ds_read_b32 v55, v222 offset:17584
	ds_read_b32 v56, v72 offset:64704
	ds_read_b32 v57, v222 offset:17600
	ds_read_b32 v58, v72 offset:64720
	ds_read_b32 v59, v222 offset:17616
	ds_read_b32 v60, v72 offset:64736
	ds_read_b32 v61, v222 offset:17632
	ds_read_b32 v62, v72 offset:64752
	ds_read_b32 v63, v222 offset:17648
	ds_read_b128 v[64:67], v176 offset:0
	ds_read_b128 v[68:71], v176 offset:16
	ds_read_b128 v[108:111], v176 offset:32
	ds_read_b128 v[214:217], v176 offset:48
	ds_read_b128 v[218:221], v176 offset:256
	ds_read_b128 v[226:229], v176 offset:272
	s_waitcnt lgkmcnt(6)
	v_mov_b32_dpp v112, v32 quad_perm:[0,0,0,0] row_mask:0xf bank_mask:0xf
	v_mov_b32_dpp v113, v33 quad_perm:[0,0,0,0] row_mask:0xf bank_mask:0xf
	s_waitcnt lgkmcnt(5)
	v_pk_fma_f32 v[32:33], v[64:65], v[112:113], v[32:33] op_sel:[0,0,0] op_sel_hi:[0,1,1] neg_lo:[1,0,0] neg_hi:[1,0,0]
	v_pk_fma_f32 v[34:35], v[64:65], v[112:113], v[34:35] op_sel:[1,0,0] op_sel_hi:[1,1,1] neg_lo:[1,0,0] neg_hi:[1,0,0]
	v_pk_fma_f32 v[36:37], v[66:67], v[112:113], v[36:37] op_sel:[0,0,0] op_sel_hi:[0,1,1] neg_lo:[1,0,0] neg_hi:[1,0,0]
	v_pk_fma_f32 v[38:39], v[66:67], v[112:113], v[38:39] op_sel:[1,0,0] op_sel_hi:[1,1,1] neg_lo:[1,0,0] neg_hi:[1,0,0]
	ds_read_b128 v[230:233], v176 offset:288
	s_waitcnt lgkmcnt(5)
	v_pk_fma_f32 v[40:41], v[68:69], v[112:113], v[40:41] op_sel:[0,0,0] op_sel_hi:[0,1,1] neg_lo:[1,0,0] neg_hi:[1,0,0]
	v_pk_fma_f32 v[42:43], v[68:69], v[112:113], v[42:43] op_sel:[1,0,0] op_sel_hi:[1,1,1] neg_lo:[1,0,0] neg_hi:[1,0,0]
	v_pk_fma_f32 v[44:45], v[70:71], v[112:113], v[44:45] op_sel:[0,0,0] op_sel_hi:[0,1,1] neg_lo:[1,0,0] neg_hi:[1,0,0]
	v_pk_fma_f32 v[46:47], v[70:71], v[112:113], v[46:47] op_sel:[1,0,0] op_sel_hi:[1,1,1] neg_lo:[1,0,0] neg_hi:[1,0,0]
	ds_read_b128 v[64:67], v176 offset:304
	s_waitcnt lgkmcnt(5)
	v_pk_fma_f32 v[48:49], v[108:109], v[112:113], v[48:49] op_sel:[0,0,0] op_sel_hi:[0,1,1] neg_lo:[1,0,0] neg_hi:[1,0,0]
	v_pk_fma_f32 v[50:51], v[108:109], v[112:113], v[50:51] op_sel:[1,0,0] op_sel_hi:[1,1,1] neg_lo:[1,0,0] neg_hi:[1,0,0]
	v_pk_fma_f32 v[52:53], v[110:111], v[112:113], v[52:53] op_sel:[0,0,0] op_sel_hi:[0,1,1] neg_lo:[1,0,0] neg_hi:[1,0,0]
	v_pk_fma_f32 v[54:55], v[110:111], v[112:113], v[54:55] op_sel:[1,0,0] op_sel_hi:[1,1,1] neg_lo:[1,0,0] neg_hi:[1,0,0]
	ds_read_b128 v[68:71], v176 offset:512
	s_waitcnt lgkmcnt(5)
	v_pk_fma_f32 v[56:57], v[214:215], v[112:113], v[56:57] op_sel:[0,0,0] op_sel_hi:[0,1,1] neg_lo:[1,0,0] neg_hi:[1,0,0]
	v_pk_fma_f32 v[58:59], v[214:215], v[112:113], v[58:59] op_sel:[1,0,0] op_sel_hi:[1,1,1] neg_lo:[1,0,0] neg_hi:[1,0,0]
	v_pk_fma_f32 v[60:61], v[216:217], v[112:113], v[60:61] op_sel:[0,0,0] op_sel_hi:[0,1,1] neg_lo:[1,0,0] neg_hi:[1,0,0]
	v_pk_fma_f32 v[62:63], v[216:217], v[112:113], v[62:63] op_sel:[1,0,0] op_sel_hi:[1,1,1] neg_lo:[1,0,0] neg_hi:[1,0,0]
	ds_read_b128 v[108:111], v176 offset:528
	v_mov_b32_dpp v250, v32 quad_perm:[1,1,1,1] row_mask:0xf bank_mask:0xf
	v_mov_b32_dpp v251, v33 quad_perm:[1,1,1,1] row_mask:0xf bank_mask:0xf
	s_waitcnt lgkmcnt(5)
	v_pk_fma_f32 v[32:33], v[218:219], v[250:251], v[32:33] op_sel:[0,0,0] op_sel_hi:[0,1,1] neg_lo:[1,0,0] neg_hi:[1,0,0]
	v_pk_fma_f32 v[34:35], v[218:219], v[250:251], v[34:35] op_sel:[1,0,0] op_sel_hi:[1,1,1] neg_lo:[1,0,0] neg_hi:[1,0,0]
	v_pk_fma_f32 v[36:37], v[220:221], v[250:251], v[36:37] op_sel:[0,0,0] op_sel_hi:[0,1,1] neg_lo:[1,0,0] neg_hi:[1,0,0]
	v_pk_fma_f32 v[38:39], v[220:221], v[250:251], v[38:39] op_sel:[1,0,0] op_sel_hi:[1,1,1] neg_lo:[1,0,0] neg_hi:[1,0,0]
	ds_read_b128 v[214:217], v176 offset:544
	s_waitcnt lgkmcnt(5)
	v_pk_fma_f32 v[40:41], v[226:227], v[250:251], v[40:41] op_sel:[0,0,0] op_sel_hi:[0,1,1] neg_lo:[1,0,0] neg_hi:[1,0,0]
	v_pk_fma_f32 v[42:43], v[226:227], v[250:251], v[42:43] op_sel:[1,0,0] op_sel_hi:[1,1,1] neg_lo:[1,0,0] neg_hi:[1,0,0]
	v_pk_fma_f32 v[44:45], v[228:229], v[250:251], v[44:45] op_sel:[0,0,0] op_sel_hi:[0,1,1] neg_lo:[1,0,0] neg_hi:[1,0,0]
	v_pk_fma_f32 v[46:47], v[228:229], v[250:251], v[46:47] op_sel:[1,0,0] op_sel_hi:[1,1,1] neg_lo:[1,0,0] neg_hi:[1,0,0]
	ds_read_b128 v[218:221], v176 offset:560
	s_waitcnt lgkmcnt(5)
	v_pk_fma_f32 v[48:49], v[230:231], v[250:251], v[48:49] op_sel:[0,0,0] op_sel_hi:[0,1,1] neg_lo:[1,0,0] neg_hi:[1,0,0]
	v_pk_fma_f32 v[50:51], v[230:231], v[250:251], v[50:51] op_sel:[1,0,0] op_sel_hi:[1,1,1] neg_lo:[1,0,0] neg_hi:[1,0,0]
	v_pk_fma_f32 v[52:53], v[232:233], v[250:251], v[52:53] op_sel:[0,0,0] op_sel_hi:[0,1,1] neg_lo:[1,0,0] neg_hi:[1,0,0]
	v_pk_fma_f32 v[54:55], v[232:233], v[250:251], v[54:55] op_sel:[1,0,0] op_sel_hi:[1,1,1] neg_lo:[1,0,0] neg_hi:[1,0,0]
	ds_read_b128 v[226:229], v176 offset:768
	s_waitcnt lgkmcnt(5)
; #define LAS __attribute__((address_space(3)))
; template <int CTRL> __device__ __forceinline__ float dppf(float x) { return __builtin_bit_cast(float, __builtin_amdgcn_update_dpp(0, __builtin_bit_cast(int, x), CTRL, 0xf, 0xf, false)); }
; __device__ __forceinline__ u32x2 pack4(float a, float b, float c, float d) { u32x2 o; o.x = pk2(a, b); o.y = pk2(c, d); return o; }
; __device__ __forceinline__ void chunkA_item(const Args& A, LAS unsigned char* lds, int tid, int lane, int wave, int ci, int ci_next, HeadConstA& H) {
;     ...
;         for (int t = 0; t < 64; ++t) {
;             f32x2_t sa = {0.f, 0.f}, sb = {0.f, 0.f};
; #pragma unroll
;             for (int p = 0; p < ((t + 3) / 4 + 1) / 2; ++p) { const f32x2_t nv = *(const LAS f32x2_t*)(Np + t * 64 + 2 * p); sa += nv * xa[p]; sb += nv * xb[p]; }
;             float ua = sa.x + sa.y, ub = sb.x + sb.y;
;             ua += dppf<0xB1>(ua); ub += dppf<0xB1>(ub); ua += dppf<0x4E>(ua); ub += dppf<0x4E>(ub);
;             const float xta = Ra[t] - ua, xtb = Rb[t] - ub;
;             if (q == (t & 3)) { if ((t >> 2) & 1) { xa[t >> 3].y = xta; xb[t >> 3].y = xtb; } else { xa[t >> 3].x = xta; xb[t >> 3].x = xtb; } }
;             a4[t & 3] = xta; b4[t & 3] = xtb;
;             if ((t & 3) == 3 && q == 0) { *(LAS u32x2*)(lds + CA_XT + cp * 144 + (t - 3) * 2) = pack4(a4[0], a4[1], a4[2], a4[3]);
;                 *(LAS u32x2*)(lds + CA_XT + (64 + cp) * 144 + (t - 3) * 2) = pack4(b4[0], b4[1], b4[2], b4[3]); }
	v_pk_fma_f32 v[56:57], v[64:65], v[250:251], v[56:57] op_sel:[0,0,0] op_sel_hi:[0,1,1] neg_lo:[1,0,0] neg_hi:[1,0,0]
	v_pk_fma_f32 v[58:59], v[64:65], v[250:251], v[58:59] op_sel:[1,0,0] op_sel_hi:[1,1,1] neg_lo:[1,0,0] neg_hi:[1,0,0]
	v_pk_fma_f32 v[60:61], v[66:67], v[250:251], v[60:61] op_sel:[0,0,0] op_sel_hi:[0,1,1] neg_lo:[1,0,0] neg_hi:[1,0,0]
	v_pk_fma_f32 v[62:63], v[66:67], v[250:251], v[62:63] op_sel:[1,0,0] op_sel_hi:[1,1,1] neg_lo:[1,0,0] neg_hi:[1,0,0]
	ds_read_b128 v[230:233], v176 offset:784
	v_cvt_pk_bf16_f32 v252, v112, v250
	v_cvt_pk_bf16_f32 v254, v113, v251
	v_mov_b32_dpp v112, v32 quad_perm:[2,2,2,2] row_mask:0xf bank_mask:0xf
	v_mov_b32_dpp v113, v33 quad_perm:[2,2,2,2] row_mask:0xf bank_mask:0xf
	s_waitcnt lgkmcnt(5)
	v_pk_fma_f32 v[32:33], v[68:69], v[112:113], v[32:33] op_sel:[0,0,0] op_sel_hi:[0,1,1] neg_lo:[1,0,0] neg_hi:[1,0,0]
	v_pk_fma_f32 v[34:35], v[68:69], v[112:113], v[34:35] op_sel:[1,0,0] op_sel_hi:[1,1,1] neg_lo:[1,0,0] neg_hi:[1,0,0]
	v_pk_fma_f32 v[36:37], v[70:71], v[112:113], v[36:37] op_sel:[0,0,0] op_sel_hi:[0,1,1] neg_lo:[1,0,0] neg_hi:[1,0,0]
	v_pk_fma_f32 v[38:39], v[70:71], v[112:113], v[38:39] op_sel:[1,0,0] op_sel_hi:[1,1,1] neg_lo:[1,0,0] neg_hi:[1,0,0]
	ds_read_b128 v[64:67], v176 offset:800
	s_waitcnt lgkmcnt(5)
	v_pk_fma_f32 v[40:41], v[108:109], v[112:113], v[40:41] op_sel:[0,0,0] op_sel_hi:[0,1,1] neg_lo:[1,0,0] neg_hi:[1,0,0]
	v_pk_fma_f32 v[42:43], v[108:109], v[112:113], v[42:43] op_sel:[1,0,0] op_sel_hi:[1,1,1] neg_lo:[1,0,0] neg_hi:[1,0,0]
	v_pk_fma_f32 v[44:45], v[110:111], v[112:113], v[44:45] op_sel:[0,0,0] op_sel_hi:[0,1,1] neg_lo:[1,0,0] neg_hi:[1,0,0]
	v_pk_fma_f32 v[46:47], v[110:111], v[112:113], v[46:47] op_sel:[1,0,0] op_sel_hi:[1,1,1] neg_lo:[1,0,0] neg_hi:[1,0,0]
	ds_read_b128 v[68:71], v176 offset:816
	s_waitcnt lgkmcnt(5)
	v_pk_fma_f32 v[48:49], v[214:215], v[112:113], v[48:49] op_sel:[0,0,0] op_sel_hi:[0,1,1] neg_lo:[1,0,0] neg_hi:[1,0,0]
	v_pk_fma_f32 v[50:51], v[214:215], v[112:113], v[50:51] op_sel:[1,0,0] op_sel_hi:[1,1,1] neg_lo:[1,0,0] neg_hi:[1,0,0]
	v_pk_fma_f32 v[52:53], v[216:217], v[112:113], v[52:53] op_sel:[0,0,0] op_sel_hi:[0,1,1] neg_lo:[1,0,0] neg_hi:[1,0,0]
	v_pk_fma_f32 v[54:55], v[216:217], v[112:113], v[54:55] op_sel:[1,0,0] op_sel_hi:[1,1,1] neg_lo:[1,0,0] neg_hi:[1,0,0]
	ds_read_b128 v[108:111], v176 offset:1024
	s_waitcnt lgkmcnt(5)
	v_pk_fma_f32 v[56:57], v[218:219], v[112:113], v[56:57] op_sel:[0,0,0] op_sel_hi:[0,1,1] neg_lo:[1,0,0] neg_hi:[1,0,0]
	v_pk_fma_f32 v[58:59], v[218:219], v[112:113], v[58:59] op_sel:[1,0,0] op_sel_hi:[1,1,1] neg_lo:[1,0,0] neg_hi:[1,0,0]
	v_pk_fma_f32 v[60:61], v[220:221], v[112:113], v[60:61] op_sel:[0,0,0] op_sel_hi:[0,1,1] neg_lo:[1,0,0] neg_hi:[1,0,0]
	v_pk_fma_f32 v[62:63], v[220:221], v[112:113], v[62:63] op_sel:[1,0,0] op_sel_hi:[1,1,1] neg_lo:[1,0,0] neg_hi:[1,0,0]
	ds_read_b128 v[214:217], v176 offset:1040
	v_mov_b32_dpp v250, v32 quad_perm:[3,3,3,3] row_mask:0xf bank_mask:0xf
	v_mov_b32_dpp v251, v33 quad_perm:[3,3,3,3] row_mask:0xf bank_mask:0xf
	s_waitcnt lgkmcnt(5)
	v_pk_fma_f32 v[34:35], v[226:227], v[250:251], v[34:35] op_sel:[1,0,0] op_sel_hi:[1,1,1] neg_lo:[1,0,0] neg_hi:[1,0,0]
	v_pk_fma_f32 v[36:37], v[228:229], v[250:251], v[36:37] op_sel:[0,0,0] op_sel_hi:[0,1,1] neg_lo:[1,0,0] neg_hi:[1,0,0]
	v_pk_fma_f32 v[38:39], v[228:229], v[250:251], v[38:39] op_sel:[1,0,0] op_sel_hi:[1,1,1] neg_lo:[1,0,0] neg_hi:[1,0,0]
	ds_read_b128 v[218:221], v176 offset:1056
	s_waitcnt lgkmcnt(5)
	v_pk_fma_f32 v[40:41], v[230:231], v[250:251], v[40:41] op_sel:[0,0,0] op_sel_hi:[0,1,1] neg_lo:[1,0,0] neg_hi:[1,0,0]
	v_pk_fma_f32 v[42:43], v[230:231], v[250:251], v[42:43] op_sel:[1,0,0] op_sel_hi:[1,1,1] neg_lo:[1,0,0] neg_hi:[1,0,0]
	v_pk_fma_f32 v[44:45], v[232:233], v[250:251], v[44:45] op_sel:[0,0,0] op_sel_hi:[0,1,1] neg_lo:[1,0,0] neg_hi:[1,0,0]
	v_pk_fma_f32 v[46:47], v[232:233], v[250:251], v[46:47] op_sel:[1,0,0] op_sel_hi:[1,1,1] neg_lo:[1,0,0] neg_hi:[1,0,0]
	ds_read_b128 v[226:229], v176 offset:1072
	s_waitcnt lgkmcnt(5)
	v_pk_fma_f32 v[48:49], v[64:65], v[250:251], v[48:49] op_sel:[0,0,0] op_sel_hi:[0,1,1] neg_lo:[1,0,0] neg_hi:[1,0,0]
	v_pk_fma_f32 v[50:51], v[64:65], v[250:251], v[50:51] op_sel:[1,0,0] op_sel_hi:[1,1,1] neg_lo:[1,0,0] neg_hi:[1,0,0]
	v_pk_fma_f32 v[52:53], v[66:67], v[250:251], v[52:53] op_sel:[0,0,0] op_sel_hi:[0,1,1] neg_lo:[1,0,0] neg_hi:[1,0,0]
	v_pk_fma_f32 v[54:55], v[66:67], v[250:251], v[54:55] op_sel:[1,0,0] op_sel_hi:[1,1,1] neg_lo:[1,0,0] neg_hi:[1,0,0]
	ds_read_b128 v[230:233], v176 offset:1280
	s_waitcnt lgkmcnt(5)
	v_pk_fma_f32 v[56:57], v[68:69], v[250:251], v[56:57] op_sel:[0,0,0] op_sel_hi:[0,1,1] neg_lo:[1,0,0] neg_hi:[1,0,0]
	v_pk_fma_f32 v[58:59], v[68:69], v[250:251], v[58:59] op_sel:[1,0,0] op_sel_hi:[1,1,1] neg_lo:[1,0,0] neg_hi:[1,0,0]
	v_pk_fma_f32 v[60:61], v[70:71], v[250:251], v[60:61] op_sel:[0,0,0] op_sel_hi:[0,1,1] neg_lo:[1,0,0] neg_hi:[1,0,0]
	v_pk_fma_f32 v[62:63], v[70:71], v[250:251], v[62:63] op_sel:[1,0,0] op_sel_hi:[1,1,1] neg_lo:[1,0,0] neg_hi:[1,0,0]
	ds_read_b128 v[64:67], v176 offset:1296
	v_cvt_pk_bf16_f32 v253, v112, v250
	v_cvt_pk_bf16_f32 v255, v113, v251
	s_mov_b64 exec, s[54:55]
	ds_write_b64 v202, v[252:253] offset:0
	ds_write_b64 v202, v[254:255] offset:9216
	s_mov_b64 exec, -1
	v_mov_b32_dpp v112, v34 quad_perm:[0,0,0,0] row_mask:0xf bank_mask:0xf
	v_mov_b32_dpp v113, v35 quad_perm:[0,0,0,0] row_mask:0xf bank_mask:0xf
	s_waitcnt lgkmcnt(7)
; #define LAS __attribute__((address_space(3)))
; template <int CTRL> __device__ __forceinline__ float dppf(float x) { return __builtin_bit_cast(float, __builtin_amdgcn_update_dpp(0, __builtin_bit_cast(int, x), CTRL, 0xf, 0xf, false)); }
; __device__ __forceinline__ u32x2 pack4(float a, float b, float c, float d) { u32x2 o; o.x = pk2(a, b); o.y = pk2(c, d); return o; }
; __device__ __forceinline__ void chunkA_item(const Args& A, LAS unsigned char* lds, int tid, int lane, int wave, int ci, int ci_next, HeadConstA& H) {
;     ...
;         for (int t = 0; t < 64; ++t) {
;             f32x2_t sa = {0.f, 0.f}, sb = {0.f, 0.f};
; #pragma unroll
;             for (int p = 0; p < ((t + 3) / 4 + 1) / 2; ++p) { const f32x2_t nv = *(const LAS f32x2_t*)(Np + t * 64 + 2 * p); sa += nv * xa[p]; sb += nv * xb[p]; }
;             float ua = sa.x + sa.y, ub = sb.x + sb.y;
;             ua += dppf<0xB1>(ua); ub += dppf<0xB1>(ub); ua += dppf<0x4E>(ua); ub += dppf<0x4E>(ub);
;             const float xta = Ra[t] - ua, xtb = Rb[t] - ub;
;             if (q == (t & 3)) { if ((t >> 2) & 1) { xa[t >> 3].y = xta; xb[t >> 3].y = xtb; } else { xa[t >> 3].x = xta; xb[t >> 3].x = xtb; } }
;             a4[t & 3] = xta; b4[t & 3] = xtb;
;             if ((t & 3) == 3 && q == 0) { *(LAS u32x2*)(lds + CA_XT + cp * 144 + (t - 3) * 2) = pack4(a4[0], a4[1], a4[2], a4[3]);
;                 *(LAS u32x2*)(lds + CA_XT + (64 + cp) * 144 + (t - 3) * 2) = pack4(b4[0], b4[1], b4[2], b4[3]); }
	v_pk_fma_f32 v[34:35], v[108:109], v[112:113], v[34:35] op_sel:[1,0,0] op_sel_hi:[1,1,1] neg_lo:[1,0,0] neg_hi:[1,0,0]
	v_pk_fma_f32 v[36:37], v[110:111], v[112:113], v[36:37] op_sel:[0,0,0] op_sel_hi:[0,1,1] neg_lo:[1,0,0] neg_hi:[1,0,0]
	v_pk_fma_f32 v[38:39], v[110:111], v[112:113], v[38:39] op_sel:[1,0,0] op_sel_hi:[1,1,1] neg_lo:[1,0,0] neg_hi:[1,0,0]
	ds_read_b128 v[68:71], v176 offset:1312
	s_waitcnt lgkmcnt(7)
	v_pk_fma_f32 v[40:41], v[214:215], v[112:113], v[40:41] op_sel:[0,0,0] op_sel_hi:[0,1,1] neg_lo:[1,0,0] neg_hi:[1,0,0]
	v_pk_fma_f32 v[42:43], v[214:215], v[112:113], v[42:43] op_sel:[1,0,0] op_sel_hi:[1,1,1] neg_lo:[1,0,0] neg_hi:[1,0,0]
	v_pk_fma_f32 v[44:45], v[216:217], v[112:113], v[44:45] op_sel:[0,0,0] op_sel_hi:[0,1,1] neg_lo:[1,0,0] neg_hi:[1,0,0]
	v_pk_fma_f32 v[46:47], v[216:217], v[112:113], v[46:47] op_sel:[1,0,0] op_sel_hi:[1,1,1] neg_lo:[1,0,0] neg_hi:[1,0,0]
	ds_read_b128 v[108:111], v176 offset:1328
	s_waitcnt lgkmcnt(7)
	v_pk_fma_f32 v[48:49], v[218:219], v[112:113], v[48:49] op_sel:[0,0,0] op_sel_hi:[0,1,1] neg_lo:[1,0,0] neg_hi:[1,0,0]
	v_pk_fma_f32 v[50:51], v[218:219], v[112:113], v[50:51] op_sel:[1,0,0] op_sel_hi:[1,1,1] neg_lo:[1,0,0] neg_hi:[1,0,0]
	v_pk_fma_f32 v[52:53], v[220:221], v[112:113], v[52:53] op_sel:[0,0,0] op_sel_hi:[0,1,1] neg_lo:[1,0,0] neg_hi:[1,0,0]
	v_pk_fma_f32 v[54:55], v[220:221], v[112:113], v[54:55] op_sel:[1,0,0] op_sel_hi:[1,1,1] neg_lo:[1,0,0] neg_hi:[1,0,0]
	ds_read_b128 v[214:217], v176 offset:1536
	s_waitcnt lgkmcnt(7)
	v_pk_fma_f32 v[56:57], v[226:227], v[112:113], v[56:57] op_sel:[0,0,0] op_sel_hi:[0,1,1] neg_lo:[1,0,0] neg_hi:[1,0,0]
	v_pk_fma_f32 v[58:59], v[226:227], v[112:113], v[58:59] op_sel:[1,0,0] op_sel_hi:[1,1,1] neg_lo:[1,0,0] neg_hi:[1,0,0]
	v_pk_fma_f32 v[60:61], v[228:229], v[112:113], v[60:61] op_sel:[0,0,0] op_sel_hi:[0,1,1] neg_lo:[1,0,0] neg_hi:[1,0,0]
	v_pk_fma_f32 v[62:63], v[228:229], v[112:113], v[62:63] op_sel:[1,0,0] op_sel_hi:[1,1,1] neg_lo:[1,0,0] neg_hi:[1,0,0]
	ds_read_b128 v[218:221], v176 offset:1552
	v_mov_b32_dpp v250, v34 quad_perm:[1,1,1,1] row_mask:0xf bank_mask:0xf
	v_mov_b32_dpp v251, v35 quad_perm:[1,1,1,1] row_mask:0xf bank_mask:0xf
	s_waitcnt lgkmcnt(7)
	v_pk_fma_f32 v[34:35], v[230:231], v[250:251], v[34:35] op_sel:[1,0,0] op_sel_hi:[1,1,1] neg_lo:[1,0,0] neg_hi:[1,0,0]
	v_pk_fma_f32 v[36:37], v[232:233], v[250:251], v[36:37] op_sel:[0,0,0] op_sel_hi:[0,1,1] neg_lo:[1,0,0] neg_hi:[1,0,0]
	v_pk_fma_f32 v[38:39], v[232:233], v[250:251], v[38:39] op_sel:[1,0,0] op_sel_hi:[1,1,1] neg_lo:[1,0,0] neg_hi:[1,0,0]
	ds_read_b128 v[226:229], v176 offset:1568
	s_waitcnt lgkmcnt(7)
	v_pk_fma_f32 v[40:41], v[64:65], v[250:251], v[40:41] op_sel:[0,0,0] op_sel_hi:[0,1,1] neg_lo:[1,0,0] neg_hi:[1,0,0]
	v_pk_fma_f32 v[42:43], v[64:65], v[250:251], v[42:43] op_sel:[1,0,0] op_sel_hi:[1,1,1] neg_lo:[1,0,0] neg_hi:[1,0,0]
	v_pk_fma_f32 v[44:45], v[66:67], v[250:251], v[44:45] op_sel:[0,0,0] op_sel_hi:[0,1,1] neg_lo:[1,0,0] neg_hi:[1,0,0]
	v_pk_fma_f32 v[46:47], v[66:67], v[250:251], v[46:47] op_sel:[1,0,0] op_sel_hi:[1,1,1] neg_lo:[1,0,0] neg_hi:[1,0,0]
	ds_read_b128 v[230:233], v176 offset:1584
	s_waitcnt lgkmcnt(5)
	v_pk_fma_f32 v[48:49], v[68:69], v[250:251], v[48:49] op_sel:[0,0,0] op_sel_hi:[0,1,1] neg_lo:[1,0,0] neg_hi:[1,0,0]
	v_pk_fma_f32 v[50:51], v[68:69], v[250:251], v[50:51] op_sel:[1,0,0] op_sel_hi:[1,1,1] neg_lo:[1,0,0] neg_hi:[1,0,0]
	v_pk_fma_f32 v[52:53], v[70:71], v[250:251], v[52:53] op_sel:[0,0,0] op_sel_hi:[0,1,1] neg_lo:[1,0,0] neg_hi:[1,0,0]
	v_pk_fma_f32 v[54:55], v[70:71], v[250:251], v[54:55] op_sel:[1,0,0] op_sel_hi:[1,1,1] neg_lo:[1,0,0] neg_hi:[1,0,0]
	ds_read_b128 v[64:67], v176 offset:1792
	s_waitcnt lgkmcnt(5)
	v_pk_fma_f32 v[56:57], v[108:109], v[250:251], v[56:57] op_sel:[0,0,0] op_sel_hi:[0,1,1] neg_lo:[1,0,0] neg_hi:[1,0,0]
	v_pk_fma_f32 v[58:59], v[108:109], v[250:251], v[58:59] op_sel:[1,0,0] op_sel_hi:[1,1,1] neg_lo:[1,0,0] neg_hi:[1,0,0]
	v_pk_fma_f32 v[60:61], v[110:111], v[250:251], v[60:61] op_sel:[0,0,0] op_sel_hi:[0,1,1] neg_lo:[1,0,0] neg_hi:[1,0,0]
	v_pk_fma_f32 v[62:63], v[110:111], v[250:251], v[62:63] op_sel:[1,0,0] op_sel_hi:[1,1,1] neg_lo:[1,0,0] neg_hi:[1,0,0]
	ds_read_b128 v[68:71], v176 offset:1808
	v_cvt_pk_bf16_f32 v252, v112, v250
	v_cvt_pk_bf16_f32 v254, v113, v251
	v_mov_b32_dpp v112, v34 quad_perm:[2,2,2,2] row_mask:0xf bank_mask:0xf
	v_mov_b32_dpp v113, v35 quad_perm:[2,2,2,2] row_mask:0xf bank_mask:0xf
	s_waitcnt lgkmcnt(5)
	v_pk_fma_f32 v[34:35], v[214:215], v[112:113], v[34:35] op_sel:[1,0,0] op_sel_hi:[1,1,1] neg_lo:[1,0,0] neg_hi:[1,0,0]
	v_pk_fma_f32 v[36:37], v[216:217], v[112:113], v[36:37] op_sel:[0,0,0] op_sel_hi:[0,1,1] neg_lo:[1,0,0] neg_hi:[1,0,0]
	v_pk_fma_f32 v[38:39], v[216:217], v[112:113], v[38:39] op_sel:[1,0,0] op_sel_hi:[1,1,1] neg_lo:[1,0,0] neg_hi:[1,0,0]
	ds_read_b128 v[108:111], v176 offset:1824
	s_waitcnt lgkmcnt(5)
	v_pk_fma_f32 v[40:41], v[218:219], v[112:113], v[40:41] op_sel:[0,0,0] op_sel_hi:[0,1,1] neg_lo:[1,0,0] neg_hi:[1,0,0]
	v_pk_fma_f32 v[42:43], v[218:219], v[112:113], v[42:43] op_sel:[1,0,0] op_sel_hi:[1,1,1] neg_lo:[1,0,0] neg_hi:[1,0,0]
	v_pk_fma_f32 v[44:45], v[220:221], v[112:113], v[44:45] op_sel:[0,0,0] op_sel_hi:[0,1,1] neg_lo:[1,0,0] neg_hi:[1,0,0]
	v_pk_fma_f32 v[46:47], v[220:221], v[112:113], v[46:47] op_sel:[1,0,0] op_sel_hi:[1,1,1] neg_lo:[1,0,0] neg_hi:[1,0,0]
	ds_read_b128 v[214:217], v176 offset:1840
	s_waitcnt lgkmcnt(5)
; #define LAS __attribute__((address_space(3)))
; template <int CTRL> __device__ __forceinline__ float dppf(float x) { return __builtin_bit_cast(float, __builtin_amdgcn_update_dpp(0, __builtin_bit_cast(int, x), CTRL, 0xf, 0xf, false)); }
; __device__ __forceinline__ u32x2 pack4(float a, float b, float c, float d) { u32x2 o; o.x = pk2(a, b); o.y = pk2(c, d); return o; }
; __device__ __forceinline__ void chunkA_item(const Args& A, LAS unsigned char* lds, int tid, int lane, int wave, int ci, int ci_next, HeadConstA& H) {
;     ...
;         for (int t = 0; t < 64; ++t) {
;             f32x2_t sa = {0.f, 0.f}, sb = {0.f, 0.f};
; #pragma unroll
;             for (int p = 0; p < ((t + 3) / 4 + 1) / 2; ++p) { const f32x2_t nv = *(const LAS f32x2_t*)(Np + t * 64 + 2 * p); sa += nv * xa[p]; sb += nv * xb[p]; }
;             float ua = sa.x + sa.y, ub = sb.x + sb.y;
;             ua += dppf<0xB1>(ua); ub += dppf<0xB1>(ub); ua += dppf<0x4E>(ua); ub += dppf<0x4E>(ub);
;             const float xta = Ra[t] - ua, xtb = Rb[t] - ub;
;             if (q == (t & 3)) { if ((t >> 2) & 1) { xa[t >> 3].y = xta; xb[t >> 3].y = xtb; } else { xa[t >> 3].x = xta; xb[t >> 3].x = xtb; } }
;             a4[t & 3] = xta; b4[t & 3] = xtb;
;             if ((t & 3) == 3 && q == 0) { *(LAS u32x2*)(lds + CA_XT + cp * 144 + (t - 3) * 2) = pack4(a4[0], a4[1], a4[2], a4[3]);
;                 *(LAS u32x2*)(lds + CA_XT + (64 + cp) * 144 + (t - 3) * 2) = pack4(b4[0], b4[1], b4[2], b4[3]); }
	v_pk_fma_f32 v[48:49], v[226:227], v[112:113], v[48:49] op_sel:[0,0,0] op_sel_hi:[0,1,1] neg_lo:[1,0,0] neg_hi:[1,0,0]
	v_pk_fma_f32 v[50:51], v[226:227], v[112:113], v[50:51] op_sel:[1,0,0] op_sel_hi:[1,1,1] neg_lo:[1,0,0] neg_hi:[1,0,0]
	v_pk_fma_f32 v[52:53], v[228:229], v[112:113], v[52:53] op_sel:[0,0,0] op_sel_hi:[0,1,1] neg_lo:[1,0,0] neg_hi:[1,0,0]
	v_pk_fma_f32 v[54:55], v[228:229], v[112:113], v[54:55] op_sel:[1,0,0] op_sel_hi:[1,1,1] neg_lo:[1,0,0] neg_hi:[1,0,0]
	ds_read_b128 v[218:221], v176 offset:2048
	s_waitcnt lgkmcnt(5)
	v_pk_fma_f32 v[56:57], v[230:231], v[112:113], v[56:57] op_sel:[0,0,0] op_sel_hi:[0,1,1] neg_lo:[1,0,0] neg_hi:[1,0,0]
	v_pk_fma_f32 v[58:59], v[230:231], v[112:113], v[58:59] op_sel:[1,0,0] op_sel_hi:[1,1,1] neg_lo:[1,0,0] neg_hi:[1,0,0]
	v_pk_fma_f32 v[60:61], v[232:233], v[112:113], v[60:61] op_sel:[0,0,0] op_sel_hi:[0,1,1] neg_lo:[1,0,0] neg_hi:[1,0,0]
	v_pk_fma_f32 v[62:63], v[232:233], v[112:113], v[62:63] op_sel:[1,0,0] op_sel_hi:[1,1,1] neg_lo:[1,0,0] neg_hi:[1,0,0]
	ds_read_b128 v[226:229], v176 offset:2064
	v_mov_b32_dpp v250, v34 quad_perm:[3,3,3,3] row_mask:0xf bank_mask:0xf
	v_mov_b32_dpp v251, v35 quad_perm:[3,3,3,3] row_mask:0xf bank_mask:0xf
	s_waitcnt lgkmcnt(5)
	v_pk_fma_f32 v[36:37], v[66:67], v[250:251], v[36:37] op_sel:[0,0,0] op_sel_hi:[0,1,1] neg_lo:[1,0,0] neg_hi:[1,0,0]
	v_pk_fma_f32 v[38:39], v[66:67], v[250:251], v[38:39] op_sel:[1,0,0] op_sel_hi:[1,1,1] neg_lo:[1,0,0] neg_hi:[1,0,0]
	ds_read_b128 v[230:233], v176 offset:2080
	s_waitcnt lgkmcnt(5)
	v_pk_fma_f32 v[40:41], v[68:69], v[250:251], v[40:41] op_sel:[0,0,0] op_sel_hi:[0,1,1] neg_lo:[1,0,0] neg_hi:[1,0,0]
	v_pk_fma_f32 v[42:43], v[68:69], v[250:251], v[42:43] op_sel:[1,0,0] op_sel_hi:[1,1,1] neg_lo:[1,0,0] neg_hi:[1,0,0]
	v_pk_fma_f32 v[44:45], v[70:71], v[250:251], v[44:45] op_sel:[0,0,0] op_sel_hi:[0,1,1] neg_lo:[1,0,0] neg_hi:[1,0,0]
	v_pk_fma_f32 v[46:47], v[70:71], v[250:251], v[46:47] op_sel:[1,0,0] op_sel_hi:[1,1,1] neg_lo:[1,0,0] neg_hi:[1,0,0]
	ds_read_b128 v[64:67], v176 offset:2096
	s_waitcnt lgkmcnt(5)
	v_pk_fma_f32 v[48:49], v[108:109], v[250:251], v[48:49] op_sel:[0,0,0] op_sel_hi:[0,1,1] neg_lo:[1,0,0] neg_hi:[1,0,0]
	v_pk_fma_f32 v[50:51], v[108:109], v[250:251], v[50:51] op_sel:[1,0,0] op_sel_hi:[1,1,1] neg_lo:[1,0,0] neg_hi:[1,0,0]
	v_pk_fma_f32 v[52:53], v[110:111], v[250:251], v[52:53] op_sel:[0,0,0] op_sel_hi:[0,1,1] neg_lo:[1,0,0] neg_hi:[1,0,0]
	v_pk_fma_f32 v[54:55], v[110:111], v[250:251], v[54:55] op_sel:[1,0,0] op_sel_hi:[1,1,1] neg_lo:[1,0,0] neg_hi:[1,0,0]
	ds_read_b128 v[68:71], v176 offset:2304
	s_waitcnt lgkmcnt(5)
	v_pk_fma_f32 v[56:57], v[214:215], v[250:251], v[56:57] op_sel:[0,0,0] op_sel_hi:[0,1,1] neg_lo:[1,0,0] neg_hi:[1,0,0]
	v_pk_fma_f32 v[58:59], v[214:215], v[250:251], v[58:59] op_sel:[1,0,0] op_sel_hi:[1,1,1] neg_lo:[1,0,0] neg_hi:[1,0,0]
	v_pk_fma_f32 v[60:61], v[216:217], v[250:251], v[60:61] op_sel:[0,0,0] op_sel_hi:[0,1,1] neg_lo:[1,0,0] neg_hi:[1,0,0]
	v_pk_fma_f32 v[62:63], v[216:217], v[250:251], v[62:63] op_sel:[1,0,0] op_sel_hi:[1,1,1] neg_lo:[1,0,0] neg_hi:[1,0,0]
	ds_read_b128 v[108:111], v176 offset:2320
	v_cvt_pk_bf16_f32 v253, v112, v250
	v_cvt_pk_bf16_f32 v255, v113, v251
	s_mov_b64 exec, s[54:55]
	ds_write_b64 v202, v[252:253] offset:8
	ds_write_b64 v202, v[254:255] offset:9224
	s_mov_b64 exec, -1
	v_mov_b32_dpp v112, v36 quad_perm:[0,0,0,0] row_mask:0xf bank_mask:0xf
	v_mov_b32_dpp v113, v37 quad_perm:[0,0,0,0] row_mask:0xf bank_mask:0xf
	s_waitcnt lgkmcnt(7)
	v_pk_fma_f32 v[36:37], v[220:221], v[112:113], v[36:37] op_sel:[0,0,0] op_sel_hi:[0,1,1] neg_lo:[1,0,0] neg_hi:[1,0,0]
	v_pk_fma_f32 v[38:39], v[220:221], v[112:113], v[38:39] op_sel:[1,0,0] op_sel_hi:[1,1,1] neg_lo:[1,0,0] neg_hi:[1,0,0]
	ds_read_b128 v[214:217], v176 offset:2336
	s_waitcnt lgkmcnt(7)
	v_pk_fma_f32 v[40:41], v[226:227], v[112:113], v[40:41] op_sel:[0,0,0] op_sel_hi:[0,1,1] neg_lo:[1,0,0] neg_hi:[1,0,0]
	v_pk_fma_f32 v[42:43], v[226:227], v[112:113], v[42:43] op_sel:[1,0,0] op_sel_hi:[1,1,1] neg_lo:[1,0,0] neg_hi:[1,0,0]
	v_pk_fma_f32 v[44:45], v[228:229], v[112:113], v[44:45] op_sel:[0,0,0] op_sel_hi:[0,1,1] neg_lo:[1,0,0] neg_hi:[1,0,0]
	v_pk_fma_f32 v[46:47], v[228:229], v[112:113], v[46:47] op_sel:[1,0,0] op_sel_hi:[1,1,1] neg_lo:[1,0,0] neg_hi:[1,0,0]
	ds_read_b128 v[218:221], v176 offset:2352
	s_waitcnt lgkmcnt(7)
	v_pk_fma_f32 v[48:49], v[230:231], v[112:113], v[48:49] op_sel:[0,0,0] op_sel_hi:[0,1,1] neg_lo:[1,0,0] neg_hi:[1,0,0]
	v_pk_fma_f32 v[50:51], v[230:231], v[112:113], v[50:51] op_sel:[1,0,0] op_sel_hi:[1,1,1] neg_lo:[1,0,0] neg_hi:[1,0,0]
	v_pk_fma_f32 v[52:53], v[232:233], v[112:113], v[52:53] op_sel:[0,0,0] op_sel_hi:[0,1,1] neg_lo:[1,0,0] neg_hi:[1,0,0]
	v_pk_fma_f32 v[54:55], v[232:233], v[112:113], v[54:55] op_sel:[1,0,0] op_sel_hi:[1,1,1] neg_lo:[1,0,0] neg_hi:[1,0,0]
	ds_read_b128 v[226:229], v176 offset:2560
	s_waitcnt lgkmcnt(7)
	v_pk_fma_f32 v[56:57], v[64:65], v[112:113], v[56:57] op_sel:[0,0,0] op_sel_hi:[0,1,1] neg_lo:[1,0,0] neg_hi:[1,0,0]
	v_pk_fma_f32 v[58:59], v[64:65], v[112:113], v[58:59] op_sel:[1,0,0] op_sel_hi:[1,1,1] neg_lo:[1,0,0] neg_hi:[1,0,0]
	v_pk_fma_f32 v[60:61], v[66:67], v[112:113], v[60:61] op_sel:[0,0,0] op_sel_hi:[0,1,1] neg_lo:[1,0,0] neg_hi:[1,0,0]
	v_pk_fma_f32 v[62:63], v[66:67], v[112:113], v[62:63] op_sel:[1,0,0] op_sel_hi:[1,1,1] neg_lo:[1,0,0] neg_hi:[1,0,0]
	ds_read_b128 v[230:233], v176 offset:2576
	v_mov_b32_dpp v250, v36 quad_perm:[1,1,1,1] row_mask:0xf bank_mask:0xf
	v_mov_b32_dpp v251, v37 quad_perm:[1,1,1,1] row_mask:0xf bank_mask:0xf
	s_waitcnt lgkmcnt(7)
; #define LAS __attribute__((address_space(3)))
; template <int CTRL> __device__ __forceinline__ float dppf(float x) { return __builtin_bit_cast(float, __builtin_amdgcn_update_dpp(0, __builtin_bit_cast(int, x), CTRL, 0xf, 0xf, false)); }
; __device__ __forceinline__ u32x2 pack4(float a, float b, float c, float d) { u32x2 o; o.x = pk2(a, b); o.y = pk2(c, d); return o; }
; __device__ __forceinline__ void chunkA_item(const Args& A, LAS unsigned char* lds, int tid, int lane, int wave, int ci, int ci_next, HeadConstA& H) {
;     ...
;         for (int t = 0; t < 64; ++t) {
;             f32x2_t sa = {0.f, 0.f}, sb = {0.f, 0.f};
; #pragma unroll
;             for (int p = 0; p < ((t + 3) / 4 + 1) / 2; ++p) { const f32x2_t nv = *(const LAS f32x2_t*)(Np + t * 64 + 2 * p); sa += nv * xa[p]; sb += nv * xb[p]; }
;             float ua = sa.x + sa.y, ub = sb.x + sb.y;
;             ua += dppf<0xB1>(ua); ub += dppf<0xB1>(ub); ua += dppf<0x4E>(ua); ub += dppf<0x4E>(ub);
;             const float xta = Ra[t] - ua, xtb = Rb[t] - ub;
;             if (q == (t & 3)) { if ((t >> 2) & 1) { xa[t >> 3].y = xta; xb[t >> 3].y = xtb; } else { xa[t >> 3].x = xta; xb[t >> 3].x = xtb; } }
;             a4[t & 3] = xta; b4[t & 3] = xtb;
;             if ((t & 3) == 3 && q == 0) { *(LAS u32x2*)(lds + CA_XT + cp * 144 + (t - 3) * 2) = pack4(a4[0], a4[1], a4[2], a4[3]);
;                 *(LAS u32x2*)(lds + CA_XT + (64 + cp) * 144 + (t - 3) * 2) = pack4(b4[0], b4[1], b4[2], b4[3]); }
	v_pk_fma_f32 v[36:37], v[70:71], v[250:251], v[36:37] op_sel:[0,0,0] op_sel_hi:[0,1,1] neg_lo:[1,0,0] neg_hi:[1,0,0]
	v_pk_fma_f32 v[38:39], v[70:71], v[250:251], v[38:39] op_sel:[1,0,0] op_sel_hi:[1,1,1] neg_lo:[1,0,0] neg_hi:[1,0,0]
	ds_read_b128 v[64:67], v176 offset:2592
	s_waitcnt lgkmcnt(7)
	v_pk_fma_f32 v[40:41], v[108:109], v[250:251], v[40:41] op_sel:[0,0,0] op_sel_hi:[0,1,1] neg_lo:[1,0,0] neg_hi:[1,0,0]
	v_pk_fma_f32 v[42:43], v[108:109], v[250:251], v[42:43] op_sel:[1,0,0] op_sel_hi:[1,1,1] neg_lo:[1,0,0] neg_hi:[1,0,0]
	v_pk_fma_f32 v[44:45], v[110:111], v[250:251], v[44:45] op_sel:[0,0,0] op_sel_hi:[0,1,1] neg_lo:[1,0,0] neg_hi:[1,0,0]
	v_pk_fma_f32 v[46:47], v[110:111], v[250:251], v[46:47] op_sel:[1,0,0] op_sel_hi:[1,1,1] neg_lo:[1,0,0] neg_hi:[1,0,0]
	ds_read_b128 v[68:71], v176 offset:2608
	s_waitcnt lgkmcnt(5)
	v_pk_fma_f32 v[48:49], v[214:215], v[250:251], v[48:49] op_sel:[0,0,0] op_sel_hi:[0,1,1] neg_lo:[1,0,0] neg_hi:[1,0,0]
	v_pk_fma_f32 v[50:51], v[214:215], v[250:251], v[50:51] op_sel:[1,0,0] op_sel_hi:[1,1,1] neg_lo:[1,0,0] neg_hi:[1,0,0]
	v_pk_fma_f32 v[52:53], v[216:217], v[250:251], v[52:53] op_sel:[0,0,0] op_sel_hi:[0,1,1] neg_lo:[1,0,0] neg_hi:[1,0,0]
	v_pk_fma_f32 v[54:55], v[216:217], v[250:251], v[54:55] op_sel:[1,0,0] op_sel_hi:[1,1,1] neg_lo:[1,0,0] neg_hi:[1,0,0]
	ds_read_b128 v[108:111], v176 offset:2816
	s_waitcnt lgkmcnt(5)
	v_pk_fma_f32 v[56:57], v[218:219], v[250:251], v[56:57] op_sel:[0,0,0] op_sel_hi:[0,1,1] neg_lo:[1,0,0] neg_hi:[1,0,0]
	v_pk_fma_f32 v[58:59], v[218:219], v[250:251], v[58:59] op_sel:[1,0,0] op_sel_hi:[1,1,1] neg_lo:[1,0,0] neg_hi:[1,0,0]
	v_pk_fma_f32 v[60:61], v[220:221], v[250:251], v[60:61] op_sel:[0,0,0] op_sel_hi:[0,1,1] neg_lo:[1,0,0] neg_hi:[1,0,0]
	v_pk_fma_f32 v[62:63], v[220:221], v[250:251], v[62:63] op_sel:[1,0,0] op_sel_hi:[1,1,1] neg_lo:[1,0,0] neg_hi:[1,0,0]
	ds_read_b128 v[214:217], v176 offset:2832
	v_cvt_pk_bf16_f32 v252, v112, v250
	v_cvt_pk_bf16_f32 v254, v113, v251
	v_mov_b32_dpp v112, v36 quad_perm:[2,2,2,2] row_mask:0xf bank_mask:0xf
	v_mov_b32_dpp v113, v37 quad_perm:[2,2,2,2] row_mask:0xf bank_mask:0xf
	s_waitcnt lgkmcnt(5)
	v_pk_fma_f32 v[36:37], v[228:229], v[112:113], v[36:37] op_sel:[0,0,0] op_sel_hi:[0,1,1] neg_lo:[1,0,0] neg_hi:[1,0,0]
	v_pk_fma_f32 v[38:39], v[228:229], v[112:113], v[38:39] op_sel:[1,0,0] op_sel_hi:[1,1,1] neg_lo:[1,0,0] neg_hi:[1,0,0]
	ds_read_b128 v[218:221], v176 offset:2848
	s_waitcnt lgkmcnt(5)
	v_pk_fma_f32 v[40:41], v[230:231], v[112:113], v[40:41] op_sel:[0,0,0] op_sel_hi:[0,1,1] neg_lo:[1,0,0] neg_hi:[1,0,0]
	v_pk_fma_f32 v[42:43], v[230:231], v[112:113], v[42:43] op_sel:[1,0,0] op_sel_hi:[1,1,1] neg_lo:[1,0,0] neg_hi:[1,0,0]
	v_pk_fma_f32 v[44:45], v[232:233], v[112:113], v[44:45] op_sel:[0,0,0] op_sel_hi:[0,1,1] neg_lo:[1,0,0] neg_hi:[1,0,0]
	v_pk_fma_f32 v[46:47], v[232:233], v[112:113], v[46:47] op_sel:[1,0,0] op_sel_hi:[1,1,1] neg_lo:[1,0,0] neg_hi:[1,0,0]
	ds_read_b128 v[226:229], v176 offset:2864
	s_waitcnt lgkmcnt(5)
	v_pk_fma_f32 v[48:49], v[64:65], v[112:113], v[48:49] op_sel:[0,0,0] op_sel_hi:[0,1,1] neg_lo:[1,0,0] neg_hi:[1,0,0]
	v_pk_fma_f32 v[50:51], v[64:65], v[112:113], v[50:51] op_sel:[1,0,0] op_sel_hi:[1,1,1] neg_lo:[1,0,0] neg_hi:[1,0,0]
	v_pk_fma_f32 v[52:53], v[66:67], v[112:113], v[52:53] op_sel:[0,0,0] op_sel_hi:[0,1,1] neg_lo:[1,0,0] neg_hi:[1,0,0]
	v_pk_fma_f32 v[54:55], v[66:67], v[112:113], v[54:55] op_sel:[1,0,0] op_sel_hi:[1,1,1] neg_lo:[1,0,0] neg_hi:[1,0,0]
	ds_read_b128 v[230:233], v176 offset:3072
	s_waitcnt lgkmcnt(5)
	v_pk_fma_f32 v[56:57], v[68:69], v[112:113], v[56:57] op_sel:[0,0,0] op_sel_hi:[0,1,1] neg_lo:[1,0,0] neg_hi:[1,0,0]
	v_pk_fma_f32 v[58:59], v[68:69], v[112:113], v[58:59] op_sel:[1,0,0] op_sel_hi:[1,1,1] neg_lo:[1,0,0] neg_hi:[1,0,0]
	v_pk_fma_f32 v[60:61], v[70:71], v[112:113], v[60:61] op_sel:[0,0,0] op_sel_hi:[0,1,1] neg_lo:[1,0,0] neg_hi:[1,0,0]
	v_pk_fma_f32 v[62:63], v[70:71], v[112:113], v[62:63] op_sel:[1,0,0] op_sel_hi:[1,1,1] neg_lo:[1,0,0] neg_hi:[1,0,0]
	ds_read_b128 v[64:67], v176 offset:3088
	v_mov_b32_dpp v250, v36 quad_perm:[3,3,3,3] row_mask:0xf bank_mask:0xf
	v_mov_b32_dpp v251, v37 quad_perm:[3,3,3,3] row_mask:0xf bank_mask:0xf
	s_waitcnt lgkmcnt(5)
	v_pk_fma_f32 v[38:39], v[110:111], v[250:251], v[38:39] op_sel:[1,0,0] op_sel_hi:[1,1,1] neg_lo:[1,0,0] neg_hi:[1,0,0]
	ds_read_b128 v[68:71], v176 offset:3104
	s_waitcnt lgkmcnt(5)
	v_pk_fma_f32 v[40:41], v[214:215], v[250:251], v[40:41] op_sel:[0,0,0] op_sel_hi:[0,1,1] neg_lo:[1,0,0] neg_hi:[1,0,0]
	v_pk_fma_f32 v[42:43], v[214:215], v[250:251], v[42:43] op_sel:[1,0,0] op_sel_hi:[1,1,1] neg_lo:[1,0,0] neg_hi:[1,0,0]
	v_pk_fma_f32 v[44:45], v[216:217], v[250:251], v[44:45] op_sel:[0,0,0] op_sel_hi:[0,1,1] neg_lo:[1,0,0] neg_hi:[1,0,0]
	v_pk_fma_f32 v[46:47], v[216:217], v[250:251], v[46:47] op_sel:[1,0,0] op_sel_hi:[1,1,1] neg_lo:[1,0,0] neg_hi:[1,0,0]
	ds_read_b128 v[108:111], v176 offset:3120
	s_waitcnt lgkmcnt(5)
	v_pk_fma_f32 v[48:49], v[218:219], v[250:251], v[48:49] op_sel:[0,0,0] op_sel_hi:[0,1,1] neg_lo:[1,0,0] neg_hi:[1,0,0]
	v_pk_fma_f32 v[50:51], v[218:219], v[250:251], v[50:51] op_sel:[1,0,0] op_sel_hi:[1,1,1] neg_lo:[1,0,0] neg_hi:[1,0,0]
	v_pk_fma_f32 v[52:53], v[220:221], v[250:251], v[52:53] op_sel:[0,0,0] op_sel_hi:[0,1,1] neg_lo:[1,0,0] neg_hi:[1,0,0]
	v_pk_fma_f32 v[54:55], v[220:221], v[250:251], v[54:55] op_sel:[1,0,0] op_sel_hi:[1,1,1] neg_lo:[1,0,0] neg_hi:[1,0,0]
	ds_read_b128 v[214:217], v176 offset:3328
	s_waitcnt lgkmcnt(5)
; #define LAS __attribute__((address_space(3)))
; template <int CTRL> __device__ __forceinline__ float dppf(float x) { return __builtin_bit_cast(float, __builtin_amdgcn_update_dpp(0, __builtin_bit_cast(int, x), CTRL, 0xf, 0xf, false)); }
; __device__ __forceinline__ u32x2 pack4(float a, float b, float c, float d) { u32x2 o; o.x = pk2(a, b); o.y = pk2(c, d); return o; }
; __device__ __forceinline__ void chunkA_item(const Args& A, LAS unsigned char* lds, int tid, int lane, int wave, int ci, int ci_next, HeadConstA& H) {
;     ...
;         for (int t = 0; t < 64; ++t) {
;             f32x2_t sa = {0.f, 0.f}, sb = {0.f, 0.f};
; #pragma unroll
;             for (int p = 0; p < ((t + 3) / 4 + 1) / 2; ++p) { const f32x2_t nv = *(const LAS f32x2_t*)(Np + t * 64 + 2 * p); sa += nv * xa[p]; sb += nv * xb[p]; }
;             float ua = sa.x + sa.y, ub = sb.x + sb.y;
;             ua += dppf<0xB1>(ua); ub += dppf<0xB1>(ub); ua += dppf<0x4E>(ua); ub += dppf<0x4E>(ub);
;             const float xta = Ra[t] - ua, xtb = Rb[t] - ub;
;             if (q == (t & 3)) { if ((t >> 2) & 1) { xa[t >> 3].y = xta; xb[t >> 3].y = xtb; } else { xa[t >> 3].x = xta; xb[t >> 3].x = xtb; } }
;             a4[t & 3] = xta; b4[t & 3] = xtb;
;             if ((t & 3) == 3 && q == 0) { *(LAS u32x2*)(lds + CA_XT + cp * 144 + (t - 3) * 2) = pack4(a4[0], a4[1], a4[2], a4[3]);
;                 *(LAS u32x2*)(lds + CA_XT + (64 + cp) * 144 + (t - 3) * 2) = pack4(b4[0], b4[1], b4[2], b4[3]); }
	v_pk_fma_f32 v[56:57], v[226:227], v[250:251], v[56:57] op_sel:[0,0,0] op_sel_hi:[0,1,1] neg_lo:[1,0,0] neg_hi:[1,0,0]
	v_pk_fma_f32 v[58:59], v[226:227], v[250:251], v[58:59] op_sel:[1,0,0] op_sel_hi:[1,1,1] neg_lo:[1,0,0] neg_hi:[1,0,0]
	v_pk_fma_f32 v[60:61], v[228:229], v[250:251], v[60:61] op_sel:[0,0,0] op_sel_hi:[0,1,1] neg_lo:[1,0,0] neg_hi:[1,0,0]
	v_pk_fma_f32 v[62:63], v[228:229], v[250:251], v[62:63] op_sel:[1,0,0] op_sel_hi:[1,1,1] neg_lo:[1,0,0] neg_hi:[1,0,0]
	ds_read_b128 v[218:221], v176 offset:3344
	v_cvt_pk_bf16_f32 v253, v112, v250
	v_cvt_pk_bf16_f32 v255, v113, v251
	s_mov_b64 exec, s[54:55]
	ds_write_b64 v202, v[252:253] offset:16
	ds_write_b64 v202, v[254:255] offset:9232
	s_mov_b64 exec, -1
	v_mov_b32_dpp v112, v38 quad_perm:[0,0,0,0] row_mask:0xf bank_mask:0xf
	v_mov_b32_dpp v113, v39 quad_perm:[0,0,0,0] row_mask:0xf bank_mask:0xf
	s_waitcnt lgkmcnt(7)
	v_pk_fma_f32 v[38:39], v[232:233], v[112:113], v[38:39] op_sel:[1,0,0] op_sel_hi:[1,1,1] neg_lo:[1,0,0] neg_hi:[1,0,0]
	ds_read_b128 v[226:229], v176 offset:3360
	s_waitcnt lgkmcnt(7)
	v_pk_fma_f32 v[40:41], v[64:65], v[112:113], v[40:41] op_sel:[0,0,0] op_sel_hi:[0,1,1] neg_lo:[1,0,0] neg_hi:[1,0,0]
	v_pk_fma_f32 v[42:43], v[64:65], v[112:113], v[42:43] op_sel:[1,0,0] op_sel_hi:[1,1,1] neg_lo:[1,0,0] neg_hi:[1,0,0]
	v_pk_fma_f32 v[44:45], v[66:67], v[112:113], v[44:45] op_sel:[0,0,0] op_sel_hi:[0,1,1] neg_lo:[1,0,0] neg_hi:[1,0,0]
	v_pk_fma_f32 v[46:47], v[66:67], v[112:113], v[46:47] op_sel:[1,0,0] op_sel_hi:[1,1,1] neg_lo:[1,0,0] neg_hi:[1,0,0]
	ds_read_b128 v[230:233], v176 offset:3376
	s_waitcnt lgkmcnt(7)
	v_pk_fma_f32 v[48:49], v[68:69], v[112:113], v[48:49] op_sel:[0,0,0] op_sel_hi:[0,1,1] neg_lo:[1,0,0] neg_hi:[1,0,0]
	v_pk_fma_f32 v[50:51], v[68:69], v[112:113], v[50:51] op_sel:[1,0,0] op_sel_hi:[1,1,1] neg_lo:[1,0,0] neg_hi:[1,0,0]
	v_pk_fma_f32 v[52:53], v[70:71], v[112:113], v[52:53] op_sel:[0,0,0] op_sel_hi:[0,1,1] neg_lo:[1,0,0] neg_hi:[1,0,0]
	v_pk_fma_f32 v[54:55], v[70:71], v[112:113], v[54:55] op_sel:[1,0,0] op_sel_hi:[1,1,1] neg_lo:[1,0,0] neg_hi:[1,0,0]
	ds_read_b128 v[64:67], v176 offset:3584
	s_waitcnt lgkmcnt(7)
	v_pk_fma_f32 v[56:57], v[108:109], v[112:113], v[56:57] op_sel:[0,0,0] op_sel_hi:[0,1,1] neg_lo:[1,0,0] neg_hi:[1,0,0]
	v_pk_fma_f32 v[58:59], v[108:109], v[112:113], v[58:59] op_sel:[1,0,0] op_sel_hi:[1,1,1] neg_lo:[1,0,0] neg_hi:[1,0,0]
	v_pk_fma_f32 v[60:61], v[110:111], v[112:113], v[60:61] op_sel:[0,0,0] op_sel_hi:[0,1,1] neg_lo:[1,0,0] neg_hi:[1,0,0]
	v_pk_fma_f32 v[62:63], v[110:111], v[112:113], v[62:63] op_sel:[1,0,0] op_sel_hi:[1,1,1] neg_lo:[1,0,0] neg_hi:[1,0,0]
	ds_read_b128 v[68:71], v176 offset:3600
	v_mov_b32_dpp v250, v38 quad_perm:[1,1,1,1] row_mask:0xf bank_mask:0xf
	v_mov_b32_dpp v251, v39 quad_perm:[1,1,1,1] row_mask:0xf bank_mask:0xf
	s_waitcnt lgkmcnt(7)
	v_pk_fma_f32 v[38:39], v[216:217], v[250:251], v[38:39] op_sel:[1,0,0] op_sel_hi:[1,1,1] neg_lo:[1,0,0] neg_hi:[1,0,0]
	ds_read_b128 v[108:111], v176 offset:3616
	s_waitcnt lgkmcnt(7)
	v_pk_fma_f32 v[40:41], v[218:219], v[250:251], v[40:41] op_sel:[0,0,0] op_sel_hi:[0,1,1] neg_lo:[1,0,0] neg_hi:[1,0,0]
	v_pk_fma_f32 v[42:43], v[218:219], v[250:251], v[42:43] op_sel:[1,0,0] op_sel_hi:[1,1,1] neg_lo:[1,0,0] neg_hi:[1,0,0]
	v_pk_fma_f32 v[44:45], v[220:221], v[250:251], v[44:45] op_sel:[0,0,0] op_sel_hi:[0,1,1] neg_lo:[1,0,0] neg_hi:[1,0,0]
	v_pk_fma_f32 v[46:47], v[220:221], v[250:251], v[46:47] op_sel:[1,0,0] op_sel_hi:[1,1,1] neg_lo:[1,0,0] neg_hi:[1,0,0]
	ds_read_b128 v[214:217], v176 offset:3632
	s_waitcnt lgkmcnt(5)
	v_pk_fma_f32 v[48:49], v[226:227], v[250:251], v[48:49] op_sel:[0,0,0] op_sel_hi:[0,1,1] neg_lo:[1,0,0] neg_hi:[1,0,0]
	v_pk_fma_f32 v[50:51], v[226:227], v[250:251], v[50:51] op_sel:[1,0,0] op_sel_hi:[1,1,1] neg_lo:[1,0,0] neg_hi:[1,0,0]
	v_pk_fma_f32 v[52:53], v[228:229], v[250:251], v[52:53] op_sel:[0,0,0] op_sel_hi:[0,1,1] neg_lo:[1,0,0] neg_hi:[1,0,0]
	v_pk_fma_f32 v[54:55], v[228:229], v[250:251], v[54:55] op_sel:[1,0,0] op_sel_hi:[1,1,1] neg_lo:[1,0,0] neg_hi:[1,0,0]
	ds_read_b128 v[218:221], v176 offset:3840
	s_waitcnt lgkmcnt(5)
	v_pk_fma_f32 v[56:57], v[230:231], v[250:251], v[56:57] op_sel:[0,0,0] op_sel_hi:[0,1,1] neg_lo:[1,0,0] neg_hi:[1,0,0]
	v_pk_fma_f32 v[58:59], v[230:231], v[250:251], v[58:59] op_sel:[1,0,0] op_sel_hi:[1,1,1] neg_lo:[1,0,0] neg_hi:[1,0,0]
	v_pk_fma_f32 v[60:61], v[232:233], v[250:251], v[60:61] op_sel:[0,0,0] op_sel_hi:[0,1,1] neg_lo:[1,0,0] neg_hi:[1,0,0]
	v_pk_fma_f32 v[62:63], v[232:233], v[250:251], v[62:63] op_sel:[1,0,0] op_sel_hi:[1,1,1] neg_lo:[1,0,0] neg_hi:[1,0,0]
	ds_read_b128 v[226:229], v176 offset:3856
	v_cvt_pk_bf16_f32 v252, v112, v250
	v_cvt_pk_bf16_f32 v254, v113, v251
	v_mov_b32_dpp v112, v38 quad_perm:[2,2,2,2] row_mask:0xf bank_mask:0xf
	v_mov_b32_dpp v113, v39 quad_perm:[2,2,2,2] row_mask:0xf bank_mask:0xf
	s_waitcnt lgkmcnt(5)
	v_pk_fma_f32 v[38:39], v[66:67], v[112:113], v[38:39] op_sel:[1,0,0] op_sel_hi:[1,1,1] neg_lo:[1,0,0] neg_hi:[1,0,0]
	ds_read_b128 v[230:233], v176 offset:3872
	s_waitcnt lgkmcnt(5)
	v_pk_fma_f32 v[40:41], v[68:69], v[112:113], v[40:41] op_sel:[0,0,0] op_sel_hi:[0,1,1] neg_lo:[1,0,0] neg_hi:[1,0,0]
	v_pk_fma_f32 v[42:43], v[68:69], v[112:113], v[42:43] op_sel:[1,0,0] op_sel_hi:[1,1,1] neg_lo:[1,0,0] neg_hi:[1,0,0]
	v_pk_fma_f32 v[44:45], v[70:71], v[112:113], v[44:45] op_sel:[0,0,0] op_sel_hi:[0,1,1] neg_lo:[1,0,0] neg_hi:[1,0,0]
	v_pk_fma_f32 v[46:47], v[70:71], v[112:113], v[46:47] op_sel:[1,0,0] op_sel_hi:[1,1,1] neg_lo:[1,0,0] neg_hi:[1,0,0]
	ds_read_b128 v[64:67], v176 offset:3888
	s_waitcnt lgkmcnt(5)
; #define LAS __attribute__((address_space(3)))
; template <int CTRL> __device__ __forceinline__ float dppf(float x) { return __builtin_bit_cast(float, __builtin_amdgcn_update_dpp(0, __builtin_bit_cast(int, x), CTRL, 0xf, 0xf, false)); }
; __device__ __forceinline__ u32x2 pack4(float a, float b, float c, float d) { u32x2 o; o.x = pk2(a, b); o.y = pk2(c, d); return o; }
; __device__ __forceinline__ void chunkA_item(const Args& A, LAS unsigned char* lds, int tid, int lane, int wave, int ci, int ci_next, HeadConstA& H) {
;     ...
;         for (int t = 0; t < 64; ++t) {
;             f32x2_t sa = {0.f, 0.f}, sb = {0.f, 0.f};
; #pragma unroll
;             for (int p = 0; p < ((t + 3) / 4 + 1) / 2; ++p) { const f32x2_t nv = *(const LAS f32x2_t*)(Np + t * 64 + 2 * p); sa += nv * xa[p]; sb += nv * xb[p]; }
;             float ua = sa.x + sa.y, ub = sb.x + sb.y;
;             ua += dppf<0xB1>(ua); ub += dppf<0xB1>(ub); ua += dppf<0x4E>(ua); ub += dppf<0x4E>(ub);
;             const float xta = Ra[t] - ua, xtb = Rb[t] - ub;
;             if (q == (t & 3)) { if ((t >> 2) & 1) { xa[t >> 3].y = xta; xb[t >> 3].y = xtb; } else { xa[t >> 3].x = xta; xb[t >> 3].x = xtb; } }
;             a4[t & 3] = xta; b4[t & 3] = xtb;
;             if ((t & 3) == 3 && q == 0) { *(LAS u32x2*)(lds + CA_XT + cp * 144 + (t - 3) * 2) = pack4(a4[0], a4[1], a4[2], a4[3]);
;                 *(LAS u32x2*)(lds + CA_XT + (64 + cp) * 144 + (t - 3) * 2) = pack4(b4[0], b4[1], b4[2], b4[3]); }
	v_pk_fma_f32 v[48:49], v[108:109], v[112:113], v[48:49] op_sel:[0,0,0] op_sel_hi:[0,1,1] neg_lo:[1,0,0] neg_hi:[1,0,0]
	v_pk_fma_f32 v[50:51], v[108:109], v[112:113], v[50:51] op_sel:[1,0,0] op_sel_hi:[1,1,1] neg_lo:[1,0,0] neg_hi:[1,0,0]
	v_pk_fma_f32 v[52:53], v[110:111], v[112:113], v[52:53] op_sel:[0,0,0] op_sel_hi:[0,1,1] neg_lo:[1,0,0] neg_hi:[1,0,0]
	v_pk_fma_f32 v[54:55], v[110:111], v[112:113], v[54:55] op_sel:[1,0,0] op_sel_hi:[1,1,1] neg_lo:[1,0,0] neg_hi:[1,0,0]
	ds_read_b128 v[68:71], v176 offset:4112
	s_waitcnt lgkmcnt(5)
	v_pk_fma_f32 v[56:57], v[214:215], v[112:113], v[56:57] op_sel:[0,0,0] op_sel_hi:[0,1,1] neg_lo:[1,0,0] neg_hi:[1,0,0]
	v_pk_fma_f32 v[58:59], v[214:215], v[112:113], v[58:59] op_sel:[1,0,0] op_sel_hi:[1,1,1] neg_lo:[1,0,0] neg_hi:[1,0,0]
	v_pk_fma_f32 v[60:61], v[216:217], v[112:113], v[60:61] op_sel:[0,0,0] op_sel_hi:[0,1,1] neg_lo:[1,0,0] neg_hi:[1,0,0]
	v_pk_fma_f32 v[62:63], v[216:217], v[112:113], v[62:63] op_sel:[1,0,0] op_sel_hi:[1,1,1] neg_lo:[1,0,0] neg_hi:[1,0,0]
	ds_read_b128 v[108:111], v176 offset:4128
	v_mov_b32_dpp v250, v38 quad_perm:[3,3,3,3] row_mask:0xf bank_mask:0xf
	v_mov_b32_dpp v251, v39 quad_perm:[3,3,3,3] row_mask:0xf bank_mask:0xf
	s_waitcnt lgkmcnt(5)
	ds_read_b128 v[214:217], v176 offset:4144
	s_waitcnt lgkmcnt(5)
	v_pk_fma_f32 v[40:41], v[226:227], v[250:251], v[40:41] op_sel:[0,0,0] op_sel_hi:[0,1,1] neg_lo:[1,0,0] neg_hi:[1,0,0]
	v_pk_fma_f32 v[42:43], v[226:227], v[250:251], v[42:43] op_sel:[1,0,0] op_sel_hi:[1,1,1] neg_lo:[1,0,0] neg_hi:[1,0,0]
	v_pk_fma_f32 v[44:45], v[228:229], v[250:251], v[44:45] op_sel:[0,0,0] op_sel_hi:[0,1,1] neg_lo:[1,0,0] neg_hi:[1,0,0]
	v_pk_fma_f32 v[46:47], v[228:229], v[250:251], v[46:47] op_sel:[1,0,0] op_sel_hi:[1,1,1] neg_lo:[1,0,0] neg_hi:[1,0,0]
	ds_read_b128 v[218:221], v176 offset:4368
	s_waitcnt lgkmcnt(5)
	v_pk_fma_f32 v[48:49], v[230:231], v[250:251], v[48:49] op_sel:[0,0,0] op_sel_hi:[0,1,1] neg_lo:[1,0,0] neg_hi:[1,0,0]
	v_pk_fma_f32 v[50:51], v[230:231], v[250:251], v[50:51] op_sel:[1,0,0] op_sel_hi:[1,1,1] neg_lo:[1,0,0] neg_hi:[1,0,0]
	v_pk_fma_f32 v[52:53], v[232:233], v[250:251], v[52:53] op_sel:[0,0,0] op_sel_hi:[0,1,1] neg_lo:[1,0,0] neg_hi:[1,0,0]
	v_pk_fma_f32 v[54:55], v[232:233], v[250:251], v[54:55] op_sel:[1,0,0] op_sel_hi:[1,1,1] neg_lo:[1,0,0] neg_hi:[1,0,0]
	ds_read_b128 v[226:229], v176 offset:4384
	s_waitcnt lgkmcnt(5)
	v_pk_fma_f32 v[56:57], v[64:65], v[250:251], v[56:57] op_sel:[0,0,0] op_sel_hi:[0,1,1] neg_lo:[1,0,0] neg_hi:[1,0,0]
	v_pk_fma_f32 v[58:59], v[64:65], v[250:251], v[58:59] op_sel:[1,0,0] op_sel_hi:[1,1,1] neg_lo:[1,0,0] neg_hi:[1,0,0]
	v_pk_fma_f32 v[60:61], v[66:67], v[250:251], v[60:61] op_sel:[0,0,0] op_sel_hi:[0,1,1] neg_lo:[1,0,0] neg_hi:[1,0,0]
	v_pk_fma_f32 v[62:63], v[66:67], v[250:251], v[62:63] op_sel:[1,0,0] op_sel_hi:[1,1,1] neg_lo:[1,0,0] neg_hi:[1,0,0]
	ds_read_b128 v[230:233], v176 offset:4400
	v_cvt_pk_bf16_f32 v253, v112, v250
	v_cvt_pk_bf16_f32 v255, v113, v251
	s_mov_b64 exec, s[54:55]
	ds_write_b64 v202, v[252:253] offset:24
	ds_write_b64 v202, v[254:255] offset:9240
	s_mov_b64 exec, -1
	v_mov_b32_dpp v112, v40 quad_perm:[0,0,0,0] row_mask:0xf bank_mask:0xf
	v_mov_b32_dpp v113, v41 quad_perm:[0,0,0,0] row_mask:0xf bank_mask:0xf
	s_waitcnt lgkmcnt(7)
	v_pk_fma_f32 v[40:41], v[68:69], v[112:113], v[40:41] op_sel:[0,0,0] op_sel_hi:[0,1,1] neg_lo:[1,0,0] neg_hi:[1,0,0]
	v_pk_fma_f32 v[42:43], v[68:69], v[112:113], v[42:43] op_sel:[1,0,0] op_sel_hi:[1,1,1] neg_lo:[1,0,0] neg_hi:[1,0,0]
	v_pk_fma_f32 v[44:45], v[70:71], v[112:113], v[44:45] op_sel:[0,0,0] op_sel_hi:[0,1,1] neg_lo:[1,0,0] neg_hi:[1,0,0]
	v_pk_fma_f32 v[46:47], v[70:71], v[112:113], v[46:47] op_sel:[1,0,0] op_sel_hi:[1,1,1] neg_lo:[1,0,0] neg_hi:[1,0,0]
	ds_read_b128 v[64:67], v176 offset:4624
	s_waitcnt lgkmcnt(7)
	v_pk_fma_f32 v[48:49], v[108:109], v[112:113], v[48:49] op_sel:[0,0,0] op_sel_hi:[0,1,1] neg_lo:[1,0,0] neg_hi:[1,0,0]
	v_pk_fma_f32 v[50:51], v[108:109], v[112:113], v[50:51] op_sel:[1,0,0] op_sel_hi:[1,1,1] neg_lo:[1,0,0] neg_hi:[1,0,0]
	v_pk_fma_f32 v[52:53], v[110:111], v[112:113], v[52:53] op_sel:[0,0,0] op_sel_hi:[0,1,1] neg_lo:[1,0,0] neg_hi:[1,0,0]
	v_pk_fma_f32 v[54:55], v[110:111], v[112:113], v[54:55] op_sel:[1,0,0] op_sel_hi:[1,1,1] neg_lo:[1,0,0] neg_hi:[1,0,0]
	ds_read_b128 v[68:71], v176 offset:4640
	s_waitcnt lgkmcnt(7)
	v_pk_fma_f32 v[56:57], v[214:215], v[112:113], v[56:57] op_sel:[0,0,0] op_sel_hi:[0,1,1] neg_lo:[1,0,0] neg_hi:[1,0,0]
	v_pk_fma_f32 v[58:59], v[214:215], v[112:113], v[58:59] op_sel:[1,0,0] op_sel_hi:[1,1,1] neg_lo:[1,0,0] neg_hi:[1,0,0]
	v_pk_fma_f32 v[60:61], v[216:217], v[112:113], v[60:61] op_sel:[0,0,0] op_sel_hi:[0,1,1] neg_lo:[1,0,0] neg_hi:[1,0,0]
	v_pk_fma_f32 v[62:63], v[216:217], v[112:113], v[62:63] op_sel:[1,0,0] op_sel_hi:[1,1,1] neg_lo:[1,0,0] neg_hi:[1,0,0]
	ds_read_b128 v[108:111], v176 offset:4656
	v_mov_b32_dpp v250, v40 quad_perm:[1,1,1,1] row_mask:0xf bank_mask:0xf
	v_mov_b32_dpp v251, v41 quad_perm:[1,1,1,1] row_mask:0xf bank_mask:0xf
	s_waitcnt lgkmcnt(7)
	v_pk_fma_f32 v[40:41], v[218:219], v[250:251], v[40:41] op_sel:[0,0,0] op_sel_hi:[0,1,1] neg_lo:[1,0,0] neg_hi:[1,0,0]
	v_pk_fma_f32 v[42:43], v[218:219], v[250:251], v[42:43] op_sel:[1,0,0] op_sel_hi:[1,1,1] neg_lo:[1,0,0] neg_hi:[1,0,0]
	v_pk_fma_f32 v[44:45], v[220:221], v[250:251], v[44:45] op_sel:[0,0,0] op_sel_hi:[0,1,1] neg_lo:[1,0,0] neg_hi:[1,0,0]
	v_pk_fma_f32 v[46:47], v[220:221], v[250:251], v[46:47] op_sel:[1,0,0] op_sel_hi:[1,1,1] neg_lo:[1,0,0] neg_hi:[1,0,0]
	ds_read_b128 v[214:217], v176 offset:4880
	s_waitcnt lgkmcnt(7)
; #define LAS __attribute__((address_space(3)))
; template <int CTRL> __device__ __forceinline__ float dppf(float x) { return __builtin_bit_cast(float, __builtin_amdgcn_update_dpp(0, __builtin_bit_cast(int, x), CTRL, 0xf, 0xf, false)); }
; __device__ __forceinline__ u32x2 pack4(float a, float b, float c, float d) { u32x2 o; o.x = pk2(a, b); o.y = pk2(c, d); return o; }
; __device__ __forceinline__ void chunkA_item(const Args& A, LAS unsigned char* lds, int tid, int lane, int wave, int ci, int ci_next, HeadConstA& H) {
;     ...
;         for (int t = 0; t < 64; ++t) {
;             f32x2_t sa = {0.f, 0.f}, sb = {0.f, 0.f};
; #pragma unroll
;             for (int p = 0; p < ((t + 3) / 4 + 1) / 2; ++p) { const f32x2_t nv = *(const LAS f32x2_t*)(Np + t * 64 + 2 * p); sa += nv * xa[p]; sb += nv * xb[p]; }
;             float ua = sa.x + sa.y, ub = sb.x + sb.y;
;             ua += dppf<0xB1>(ua); ub += dppf<0xB1>(ub); ua += dppf<0x4E>(ua); ub += dppf<0x4E>(ub);
;             const float xta = Ra[t] - ua, xtb = Rb[t] - ub;
;             if (q == (t & 3)) { if ((t >> 2) & 1) { xa[t >> 3].y = xta; xb[t >> 3].y = xtb; } else { xa[t >> 3].x = xta; xb[t >> 3].x = xtb; } }
;             a4[t & 3] = xta; b4[t & 3] = xtb;
;             if ((t & 3) == 3 && q == 0) { *(LAS u32x2*)(lds + CA_XT + cp * 144 + (t - 3) * 2) = pack4(a4[0], a4[1], a4[2], a4[3]);
;                 *(LAS u32x2*)(lds + CA_XT + (64 + cp) * 144 + (t - 3) * 2) = pack4(b4[0], b4[1], b4[2], b4[3]); }
	v_pk_fma_f32 v[48:49], v[226:227], v[250:251], v[48:49] op_sel:[0,0,0] op_sel_hi:[0,1,1] neg_lo:[1,0,0] neg_hi:[1,0,0]
	v_pk_fma_f32 v[50:51], v[226:227], v[250:251], v[50:51] op_sel:[1,0,0] op_sel_hi:[1,1,1] neg_lo:[1,0,0] neg_hi:[1,0,0]
	v_pk_fma_f32 v[52:53], v[228:229], v[250:251], v[52:53] op_sel:[0,0,0] op_sel_hi:[0,1,1] neg_lo:[1,0,0] neg_hi:[1,0,0]
	v_pk_fma_f32 v[54:55], v[228:229], v[250:251], v[54:55] op_sel:[1,0,0] op_sel_hi:[1,1,1] neg_lo:[1,0,0] neg_hi:[1,0,0]
	ds_read_b128 v[218:221], v176 offset:4896
	s_waitcnt lgkmcnt(7)
	v_pk_fma_f32 v[56:57], v[230:231], v[250:251], v[56:57] op_sel:[0,0,0] op_sel_hi:[0,1,1] neg_lo:[1,0,0] neg_hi:[1,0,0]
	v_pk_fma_f32 v[58:59], v[230:231], v[250:251], v[58:59] op_sel:[1,0,0] op_sel_hi:[1,1,1] neg_lo:[1,0,0] neg_hi:[1,0,0]
	v_pk_fma_f32 v[60:61], v[232:233], v[250:251], v[60:61] op_sel:[0,0,0] op_sel_hi:[0,1,1] neg_lo:[1,0,0] neg_hi:[1,0,0]
	v_pk_fma_f32 v[62:63], v[232:233], v[250:251], v[62:63] op_sel:[1,0,0] op_sel_hi:[1,1,1] neg_lo:[1,0,0] neg_hi:[1,0,0]
	ds_read_b128 v[226:229], v176 offset:4912
	v_cvt_pk_bf16_f32 v252, v112, v250
	v_cvt_pk_bf16_f32 v254, v113, v251
	v_mov_b32_dpp v112, v40 quad_perm:[2,2,2,2] row_mask:0xf bank_mask:0xf
	v_mov_b32_dpp v113, v41 quad_perm:[2,2,2,2] row_mask:0xf bank_mask:0xf
	s_waitcnt lgkmcnt(5)
	v_pk_fma_f32 v[40:41], v[64:65], v[112:113], v[40:41] op_sel:[0,0,0] op_sel_hi:[0,1,1] neg_lo:[1,0,0] neg_hi:[1,0,0]
	v_pk_fma_f32 v[42:43], v[64:65], v[112:113], v[42:43] op_sel:[1,0,0] op_sel_hi:[1,1,1] neg_lo:[1,0,0] neg_hi:[1,0,0]
	v_pk_fma_f32 v[44:45], v[66:67], v[112:113], v[44:45] op_sel:[0,0,0] op_sel_hi:[0,1,1] neg_lo:[1,0,0] neg_hi:[1,0,0]
	v_pk_fma_f32 v[46:47], v[66:67], v[112:113], v[46:47] op_sel:[1,0,0] op_sel_hi:[1,1,1] neg_lo:[1,0,0] neg_hi:[1,0,0]
	ds_read_b128 v[230:233], v176 offset:5136
	s_waitcnt lgkmcnt(5)
	v_pk_fma_f32 v[48:49], v[68:69], v[112:113], v[48:49] op_sel:[0,0,0] op_sel_hi:[0,1,1] neg_lo:[1,0,0] neg_hi:[1,0,0]
	v_pk_fma_f32 v[50:51], v[68:69], v[112:113], v[50:51] op_sel:[1,0,0] op_sel_hi:[1,1,1] neg_lo:[1,0,0] neg_hi:[1,0,0]
	v_pk_fma_f32 v[52:53], v[70:71], v[112:113], v[52:53] op_sel:[0,0,0] op_sel_hi:[0,1,1] neg_lo:[1,0,0] neg_hi:[1,0,0]
	v_pk_fma_f32 v[54:55], v[70:71], v[112:113], v[54:55] op_sel:[1,0,0] op_sel_hi:[1,1,1] neg_lo:[1,0,0] neg_hi:[1,0,0]
	ds_read_b128 v[64:67], v176 offset:5152
	s_waitcnt lgkmcnt(5)
	v_pk_fma_f32 v[56:57], v[108:109], v[112:113], v[56:57] op_sel:[0,0,0] op_sel_hi:[0,1,1] neg_lo:[1,0,0] neg_hi:[1,0,0]
	v_pk_fma_f32 v[58:59], v[108:109], v[112:113], v[58:59] op_sel:[1,0,0] op_sel_hi:[1,1,1] neg_lo:[1,0,0] neg_hi:[1,0,0]
	v_pk_fma_f32 v[60:61], v[110:111], v[112:113], v[60:61] op_sel:[0,0,0] op_sel_hi:[0,1,1] neg_lo:[1,0,0] neg_hi:[1,0,0]
	v_pk_fma_f32 v[62:63], v[110:111], v[112:113], v[62:63] op_sel:[1,0,0] op_sel_hi:[1,1,1] neg_lo:[1,0,0] neg_hi:[1,0,0]
	ds_read_b128 v[68:71], v176 offset:5168
	v_mov_b32_dpp v250, v40 quad_perm:[3,3,3,3] row_mask:0xf bank_mask:0xf
	v_mov_b32_dpp v251, v41 quad_perm:[3,3,3,3] row_mask:0xf bank_mask:0xf
	s_waitcnt lgkmcnt(5)
	v_pk_fma_f32 v[42:43], v[214:215], v[250:251], v[42:43] op_sel:[1,0,0] op_sel_hi:[1,1,1] neg_lo:[1,0,0] neg_hi:[1,0,0]
	v_pk_fma_f32 v[44:45], v[216:217], v[250:251], v[44:45] op_sel:[0,0,0] op_sel_hi:[0,1,1] neg_lo:[1,0,0] neg_hi:[1,0,0]
	v_pk_fma_f32 v[46:47], v[216:217], v[250:251], v[46:47] op_sel:[1,0,0] op_sel_hi:[1,1,1] neg_lo:[1,0,0] neg_hi:[1,0,0]
	ds_read_b128 v[108:111], v176 offset:5392
	s_waitcnt lgkmcnt(5)
	v_pk_fma_f32 v[48:49], v[218:219], v[250:251], v[48:49] op_sel:[0,0,0] op_sel_hi:[0,1,1] neg_lo:[1,0,0] neg_hi:[1,0,0]
	v_pk_fma_f32 v[50:51], v[218:219], v[250:251], v[50:51] op_sel:[1,0,0] op_sel_hi:[1,1,1] neg_lo:[1,0,0] neg_hi:[1,0,0]
	v_pk_fma_f32 v[52:53], v[220:221], v[250:251], v[52:53] op_sel:[0,0,0] op_sel_hi:[0,1,1] neg_lo:[1,0,0] neg_hi:[1,0,0]
	v_pk_fma_f32 v[54:55], v[220:221], v[250:251], v[54:55] op_sel:[1,0,0] op_sel_hi:[1,1,1] neg_lo:[1,0,0] neg_hi:[1,0,0]
	ds_read_b128 v[214:217], v176 offset:5408
	s_waitcnt lgkmcnt(5)
	v_pk_fma_f32 v[56:57], v[226:227], v[250:251], v[56:57] op_sel:[0,0,0] op_sel_hi:[0,1,1] neg_lo:[1,0,0] neg_hi:[1,0,0]
	v_pk_fma_f32 v[58:59], v[226:227], v[250:251], v[58:59] op_sel:[1,0,0] op_sel_hi:[1,1,1] neg_lo:[1,0,0] neg_hi:[1,0,0]
	v_pk_fma_f32 v[60:61], v[228:229], v[250:251], v[60:61] op_sel:[0,0,0] op_sel_hi:[0,1,1] neg_lo:[1,0,0] neg_hi:[1,0,0]
	v_pk_fma_f32 v[62:63], v[228:229], v[250:251], v[62:63] op_sel:[1,0,0] op_sel_hi:[1,1,1] neg_lo:[1,0,0] neg_hi:[1,0,0]
	ds_read_b128 v[218:221], v176 offset:5424
	v_cvt_pk_bf16_f32 v253, v112, v250
	v_cvt_pk_bf16_f32 v255, v113, v251
	s_mov_b64 exec, s[54:55]
	ds_write_b64 v202, v[252:253] offset:32
	ds_write_b64 v202, v[254:255] offset:9248
	s_mov_b64 exec, -1
	v_mov_b32_dpp v112, v42 quad_perm:[0,0,0,0] row_mask:0xf bank_mask:0xf
	v_mov_b32_dpp v113, v43 quad_perm:[0,0,0,0] row_mask:0xf bank_mask:0xf
	s_waitcnt lgkmcnt(7)
	v_pk_fma_f32 v[42:43], v[230:231], v[112:113], v[42:43] op_sel:[1,0,0] op_sel_hi:[1,1,1] neg_lo:[1,0,0] neg_hi:[1,0,0]
	v_pk_fma_f32 v[44:45], v[232:233], v[112:113], v[44:45] op_sel:[0,0,0] op_sel_hi:[0,1,1] neg_lo:[1,0,0] neg_hi:[1,0,0]
	v_pk_fma_f32 v[46:47], v[232:233], v[112:113], v[46:47] op_sel:[1,0,0] op_sel_hi:[1,1,1] neg_lo:[1,0,0] neg_hi:[1,0,0]
	ds_read_b128 v[226:229], v176 offset:5648
	s_waitcnt lgkmcnt(7)
	v_pk_fma_f32 v[48:49], v[64:65], v[112:113], v[48:49] op_sel:[0,0,0] op_sel_hi:[0,1,1] neg_lo:[1,0,0] neg_hi:[1,0,0]
	v_pk_fma_f32 v[50:51], v[64:65], v[112:113], v[50:51] op_sel:[1,0,0] op_sel_hi:[1,1,1] neg_lo:[1,0,0] neg_hi:[1,0,0]
	v_pk_fma_f32 v[52:53], v[66:67], v[112:113], v[52:53] op_sel:[0,0,0] op_sel_hi:[0,1,1] neg_lo:[1,0,0] neg_hi:[1,0,0]
	v_pk_fma_f32 v[54:55], v[66:67], v[112:113], v[54:55] op_sel:[1,0,0] op_sel_hi:[1,1,1] neg_lo:[1,0,0] neg_hi:[1,0,0]
	ds_read_b128 v[230:233], v176 offset:5664
	s_waitcnt lgkmcnt(7)
; #define LAS __attribute__((address_space(3)))
; template <int CTRL> __device__ __forceinline__ float dppf(float x) { return __builtin_bit_cast(float, __builtin_amdgcn_update_dpp(0, __builtin_bit_cast(int, x), CTRL, 0xf, 0xf, false)); }
; __device__ __forceinline__ u32x2 pack4(float a, float b, float c, float d) { u32x2 o; o.x = pk2(a, b); o.y = pk2(c, d); return o; }
; __device__ __forceinline__ void chunkA_item(const Args& A, LAS unsigned char* lds, int tid, int lane, int wave, int ci, int ci_next, HeadConstA& H) {
;     ...
;         for (int t = 0; t < 64; ++t) {
;             f32x2_t sa = {0.f, 0.f}, sb = {0.f, 0.f};
; #pragma unroll
;             for (int p = 0; p < ((t + 3) / 4 + 1) / 2; ++p) { const f32x2_t nv = *(const LAS f32x2_t*)(Np + t * 64 + 2 * p); sa += nv * xa[p]; sb += nv * xb[p]; }
;             float ua = sa.x + sa.y, ub = sb.x + sb.y;
;             ua += dppf<0xB1>(ua); ub += dppf<0xB1>(ub); ua += dppf<0x4E>(ua); ub += dppf<0x4E>(ub);
;             const float xta = Ra[t] - ua, xtb = Rb[t] - ub;
;             if (q == (t & 3)) { if ((t >> 2) & 1) { xa[t >> 3].y = xta; xb[t >> 3].y = xtb; } else { xa[t >> 3].x = xta; xb[t >> 3].x = xtb; } }
;             a4[t & 3] = xta; b4[t & 3] = xtb;
;             if ((t & 3) == 3 && q == 0) { *(LAS u32x2*)(lds + CA_XT + cp * 144 + (t - 3) * 2) = pack4(a4[0], a4[1], a4[2], a4[3]);
;                 *(LAS u32x2*)(lds + CA_XT + (64 + cp) * 144 + (t - 3) * 2) = pack4(b4[0], b4[1], b4[2], b4[3]); }
	v_pk_fma_f32 v[56:57], v[68:69], v[112:113], v[56:57] op_sel:[0,0,0] op_sel_hi:[0,1,1] neg_lo:[1,0,0] neg_hi:[1,0,0]
	v_pk_fma_f32 v[58:59], v[68:69], v[112:113], v[58:59] op_sel:[1,0,0] op_sel_hi:[1,1,1] neg_lo:[1,0,0] neg_hi:[1,0,0]
	v_pk_fma_f32 v[60:61], v[70:71], v[112:113], v[60:61] op_sel:[0,0,0] op_sel_hi:[0,1,1] neg_lo:[1,0,0] neg_hi:[1,0,0]
	v_pk_fma_f32 v[62:63], v[70:71], v[112:113], v[62:63] op_sel:[1,0,0] op_sel_hi:[1,1,1] neg_lo:[1,0,0] neg_hi:[1,0,0]
	ds_read_b128 v[64:67], v176 offset:5680
	v_mov_b32_dpp v250, v42 quad_perm:[1,1,1,1] row_mask:0xf bank_mask:0xf
	v_mov_b32_dpp v251, v43 quad_perm:[1,1,1,1] row_mask:0xf bank_mask:0xf
	s_waitcnt lgkmcnt(7)
	v_pk_fma_f32 v[42:43], v[108:109], v[250:251], v[42:43] op_sel:[1,0,0] op_sel_hi:[1,1,1] neg_lo:[1,0,0] neg_hi:[1,0,0]
	v_pk_fma_f32 v[44:45], v[110:111], v[250:251], v[44:45] op_sel:[0,0,0] op_sel_hi:[0,1,1] neg_lo:[1,0,0] neg_hi:[1,0,0]
	v_pk_fma_f32 v[46:47], v[110:111], v[250:251], v[46:47] op_sel:[1,0,0] op_sel_hi:[1,1,1] neg_lo:[1,0,0] neg_hi:[1,0,0]
	ds_read_b128 v[68:71], v176 offset:5904
	s_waitcnt lgkmcnt(7)
	v_pk_fma_f32 v[48:49], v[214:215], v[250:251], v[48:49] op_sel:[0,0,0] op_sel_hi:[0,1,1] neg_lo:[1,0,0] neg_hi:[1,0,0]
	v_pk_fma_f32 v[50:51], v[214:215], v[250:251], v[50:51] op_sel:[1,0,0] op_sel_hi:[1,1,1] neg_lo:[1,0,0] neg_hi:[1,0,0]
	v_pk_fma_f32 v[52:53], v[216:217], v[250:251], v[52:53] op_sel:[0,0,0] op_sel_hi:[0,1,1] neg_lo:[1,0,0] neg_hi:[1,0,0]
	v_pk_fma_f32 v[54:55], v[216:217], v[250:251], v[54:55] op_sel:[1,0,0] op_sel_hi:[1,1,1] neg_lo:[1,0,0] neg_hi:[1,0,0]
	ds_read_b128 v[108:111], v176 offset:5920
	s_waitcnt lgkmcnt(7)
	v_pk_fma_f32 v[56:57], v[218:219], v[250:251], v[56:57] op_sel:[0,0,0] op_sel_hi:[0,1,1] neg_lo:[1,0,0] neg_hi:[1,0,0]
	v_pk_fma_f32 v[58:59], v[218:219], v[250:251], v[58:59] op_sel:[1,0,0] op_sel_hi:[1,1,1] neg_lo:[1,0,0] neg_hi:[1,0,0]
	v_pk_fma_f32 v[60:61], v[220:221], v[250:251], v[60:61] op_sel:[0,0,0] op_sel_hi:[0,1,1] neg_lo:[1,0,0] neg_hi:[1,0,0]
	v_pk_fma_f32 v[62:63], v[220:221], v[250:251], v[62:63] op_sel:[1,0,0] op_sel_hi:[1,1,1] neg_lo:[1,0,0] neg_hi:[1,0,0]
	ds_read_b128 v[214:217], v176 offset:5936
	v_cvt_pk_bf16_f32 v252, v112, v250
	v_cvt_pk_bf16_f32 v254, v113, v251
	v_mov_b32_dpp v112, v42 quad_perm:[2,2,2,2] row_mask:0xf bank_mask:0xf
	v_mov_b32_dpp v113, v43 quad_perm:[2,2,2,2] row_mask:0xf bank_mask:0xf
	s_waitcnt lgkmcnt(5)
	v_pk_fma_f32 v[42:43], v[226:227], v[112:113], v[42:43] op_sel:[1,0,0] op_sel_hi:[1,1,1] neg_lo:[1,0,0] neg_hi:[1,0,0]
	v_pk_fma_f32 v[44:45], v[228:229], v[112:113], v[44:45] op_sel:[0,0,0] op_sel_hi:[0,1,1] neg_lo:[1,0,0] neg_hi:[1,0,0]
	v_pk_fma_f32 v[46:47], v[228:229], v[112:113], v[46:47] op_sel:[1,0,0] op_sel_hi:[1,1,1] neg_lo:[1,0,0] neg_hi:[1,0,0]
	ds_read_b128 v[218:221], v176 offset:6160
	s_waitcnt lgkmcnt(5)
	v_pk_fma_f32 v[48:49], v[230:231], v[112:113], v[48:49] op_sel:[0,0,0] op_sel_hi:[0,1,1] neg_lo:[1,0,0] neg_hi:[1,0,0]
	v_pk_fma_f32 v[50:51], v[230:231], v[112:113], v[50:51] op_sel:[1,0,0] op_sel_hi:[1,1,1] neg_lo:[1,0,0] neg_hi:[1,0,0]
	v_pk_fma_f32 v[52:53], v[232:233], v[112:113], v[52:53] op_sel:[0,0,0] op_sel_hi:[0,1,1] neg_lo:[1,0,0] neg_hi:[1,0,0]
	v_pk_fma_f32 v[54:55], v[232:233], v[112:113], v[54:55] op_sel:[1,0,0] op_sel_hi:[1,1,1] neg_lo:[1,0,0] neg_hi:[1,0,0]
	ds_read_b128 v[226:229], v176 offset:6176
	s_waitcnt lgkmcnt(5)
	v_pk_fma_f32 v[56:57], v[64:65], v[112:113], v[56:57] op_sel:[0,0,0] op_sel_hi:[0,1,1] neg_lo:[1,0,0] neg_hi:[1,0,0]
	v_pk_fma_f32 v[58:59], v[64:65], v[112:113], v[58:59] op_sel:[1,0,0] op_sel_hi:[1,1,1] neg_lo:[1,0,0] neg_hi:[1,0,0]
	v_pk_fma_f32 v[60:61], v[66:67], v[112:113], v[60:61] op_sel:[0,0,0] op_sel_hi:[0,1,1] neg_lo:[1,0,0] neg_hi:[1,0,0]
	v_pk_fma_f32 v[62:63], v[66:67], v[112:113], v[62:63] op_sel:[1,0,0] op_sel_hi:[1,1,1] neg_lo:[1,0,0] neg_hi:[1,0,0]
	ds_read_b128 v[230:233], v176 offset:6192
	v_mov_b32_dpp v250, v42 quad_perm:[3,3,3,3] row_mask:0xf bank_mask:0xf
	v_mov_b32_dpp v251, v43 quad_perm:[3,3,3,3] row_mask:0xf bank_mask:0xf
	s_waitcnt lgkmcnt(5)
	v_pk_fma_f32 v[44:45], v[70:71], v[250:251], v[44:45] op_sel:[0,0,0] op_sel_hi:[0,1,1] neg_lo:[1,0,0] neg_hi:[1,0,0]
	v_pk_fma_f32 v[46:47], v[70:71], v[250:251], v[46:47] op_sel:[1,0,0] op_sel_hi:[1,1,1] neg_lo:[1,0,0] neg_hi:[1,0,0]
	ds_read_b128 v[64:67], v176 offset:6416
	s_waitcnt lgkmcnt(5)
	v_pk_fma_f32 v[48:49], v[108:109], v[250:251], v[48:49] op_sel:[0,0,0] op_sel_hi:[0,1,1] neg_lo:[1,0,0] neg_hi:[1,0,0]
	v_pk_fma_f32 v[50:51], v[108:109], v[250:251], v[50:51] op_sel:[1,0,0] op_sel_hi:[1,1,1] neg_lo:[1,0,0] neg_hi:[1,0,0]
	v_pk_fma_f32 v[52:53], v[110:111], v[250:251], v[52:53] op_sel:[0,0,0] op_sel_hi:[0,1,1] neg_lo:[1,0,0] neg_hi:[1,0,0]
	v_pk_fma_f32 v[54:55], v[110:111], v[250:251], v[54:55] op_sel:[1,0,0] op_sel_hi:[1,1,1] neg_lo:[1,0,0] neg_hi:[1,0,0]
	ds_read_b128 v[68:71], v176 offset:6432
	s_waitcnt lgkmcnt(5)
	v_pk_fma_f32 v[56:57], v[214:215], v[250:251], v[56:57] op_sel:[0,0,0] op_sel_hi:[0,1,1] neg_lo:[1,0,0] neg_hi:[1,0,0]
	v_pk_fma_f32 v[58:59], v[214:215], v[250:251], v[58:59] op_sel:[1,0,0] op_sel_hi:[1,1,1] neg_lo:[1,0,0] neg_hi:[1,0,0]
	v_pk_fma_f32 v[60:61], v[216:217], v[250:251], v[60:61] op_sel:[0,0,0] op_sel_hi:[0,1,1] neg_lo:[1,0,0] neg_hi:[1,0,0]
	v_pk_fma_f32 v[62:63], v[216:217], v[250:251], v[62:63] op_sel:[1,0,0] op_sel_hi:[1,1,1] neg_lo:[1,0,0] neg_hi:[1,0,0]
	ds_read_b128 v[108:111], v176 offset:6448
	v_cvt_pk_bf16_f32 v253, v112, v250
	v_cvt_pk_bf16_f32 v255, v113, v251
	s_mov_b64 exec, s[54:55]
	ds_write_b64 v202, v[252:253] offset:40
	ds_write_b64 v202, v[254:255] offset:9256
	s_mov_b64 exec, -1
	v_mov_b32_dpp v112, v44 quad_perm:[0,0,0,0] row_mask:0xf bank_mask:0xf
	v_mov_b32_dpp v113, v45 quad_perm:[0,0,0,0] row_mask:0xf bank_mask:0xf
	s_waitcnt lgkmcnt(7)
; #define LAS __attribute__((address_space(3)))
; template <int CTRL> __device__ __forceinline__ float dppf(float x) { return __builtin_bit_cast(float, __builtin_amdgcn_update_dpp(0, __builtin_bit_cast(int, x), CTRL, 0xf, 0xf, false)); }
; __device__ __forceinline__ u32x2 pack4(float a, float b, float c, float d) { u32x2 o; o.x = pk2(a, b); o.y = pk2(c, d); return o; }
; __device__ __forceinline__ void chunkA_item(const Args& A, LAS unsigned char* lds, int tid, int lane, int wave, int ci, int ci_next, HeadConstA& H) {
;     ...
;         for (int t = 0; t < 64; ++t) {
;             f32x2_t sa = {0.f, 0.f}, sb = {0.f, 0.f};
; #pragma unroll
;             for (int p = 0; p < ((t + 3) / 4 + 1) / 2; ++p) { const f32x2_t nv = *(const LAS f32x2_t*)(Np + t * 64 + 2 * p); sa += nv * xa[p]; sb += nv * xb[p]; }
;             float ua = sa.x + sa.y, ub = sb.x + sb.y;
;             ua += dppf<0xB1>(ua); ub += dppf<0xB1>(ub); ua += dppf<0x4E>(ua); ub += dppf<0x4E>(ub);
;             const float xta = Ra[t] - ua, xtb = Rb[t] - ub;
;             if (q == (t & 3)) { if ((t >> 2) & 1) { xa[t >> 3].y = xta; xb[t >> 3].y = xtb; } else { xa[t >> 3].x = xta; xb[t >> 3].x = xtb; } }
;             a4[t & 3] = xta; b4[t & 3] = xtb;
;             if ((t & 3) == 3 && q == 0) { *(LAS u32x2*)(lds + CA_XT + cp * 144 + (t - 3) * 2) = pack4(a4[0], a4[1], a4[2], a4[3]);
;                 *(LAS u32x2*)(lds + CA_XT + (64 + cp) * 144 + (t - 3) * 2) = pack4(b4[0], b4[1], b4[2], b4[3]); }
	v_pk_fma_f32 v[44:45], v[220:221], v[112:113], v[44:45] op_sel:[0,0,0] op_sel_hi:[0,1,1] neg_lo:[1,0,0] neg_hi:[1,0,0]
	v_pk_fma_f32 v[46:47], v[220:221], v[112:113], v[46:47] op_sel:[1,0,0] op_sel_hi:[1,1,1] neg_lo:[1,0,0] neg_hi:[1,0,0]
	ds_read_b128 v[214:217], v176 offset:6672
	s_waitcnt lgkmcnt(7)
	v_pk_fma_f32 v[48:49], v[226:227], v[112:113], v[48:49] op_sel:[0,0,0] op_sel_hi:[0,1,1] neg_lo:[1,0,0] neg_hi:[1,0,0]
	v_pk_fma_f32 v[50:51], v[226:227], v[112:113], v[50:51] op_sel:[1,0,0] op_sel_hi:[1,1,1] neg_lo:[1,0,0] neg_hi:[1,0,0]
	v_pk_fma_f32 v[52:53], v[228:229], v[112:113], v[52:53] op_sel:[0,0,0] op_sel_hi:[0,1,1] neg_lo:[1,0,0] neg_hi:[1,0,0]
	v_pk_fma_f32 v[54:55], v[228:229], v[112:113], v[54:55] op_sel:[1,0,0] op_sel_hi:[1,1,1] neg_lo:[1,0,0] neg_hi:[1,0,0]
	ds_read_b128 v[218:221], v176 offset:6688
	s_waitcnt lgkmcnt(7)
	v_pk_fma_f32 v[56:57], v[230:231], v[112:113], v[56:57] op_sel:[0,0,0] op_sel_hi:[0,1,1] neg_lo:[1,0,0] neg_hi:[1,0,0]
	v_pk_fma_f32 v[58:59], v[230:231], v[112:113], v[58:59] op_sel:[1,0,0] op_sel_hi:[1,1,1] neg_lo:[1,0,0] neg_hi:[1,0,0]
	v_pk_fma_f32 v[60:61], v[232:233], v[112:113], v[60:61] op_sel:[0,0,0] op_sel_hi:[0,1,1] neg_lo:[1,0,0] neg_hi:[1,0,0]
	v_pk_fma_f32 v[62:63], v[232:233], v[112:113], v[62:63] op_sel:[1,0,0] op_sel_hi:[1,1,1] neg_lo:[1,0,0] neg_hi:[1,0,0]
	ds_read_b128 v[226:229], v176 offset:6704
	v_mov_b32_dpp v250, v44 quad_perm:[1,1,1,1] row_mask:0xf bank_mask:0xf
	v_mov_b32_dpp v251, v45 quad_perm:[1,1,1,1] row_mask:0xf bank_mask:0xf
	s_waitcnt lgkmcnt(7)
	v_pk_fma_f32 v[44:45], v[66:67], v[250:251], v[44:45] op_sel:[0,0,0] op_sel_hi:[0,1,1] neg_lo:[1,0,0] neg_hi:[1,0,0]
	v_pk_fma_f32 v[46:47], v[66:67], v[250:251], v[46:47] op_sel:[1,0,0] op_sel_hi:[1,1,1] neg_lo:[1,0,0] neg_hi:[1,0,0]
	ds_read_b128 v[230:233], v176 offset:6928
	s_waitcnt lgkmcnt(7)
	v_pk_fma_f32 v[48:49], v[68:69], v[250:251], v[48:49] op_sel:[0,0,0] op_sel_hi:[0,1,1] neg_lo:[1,0,0] neg_hi:[1,0,0]
	v_pk_fma_f32 v[50:51], v[68:69], v[250:251], v[50:51] op_sel:[1,0,0] op_sel_hi:[1,1,1] neg_lo:[1,0,0] neg_hi:[1,0,0]
	v_pk_fma_f32 v[52:53], v[70:71], v[250:251], v[52:53] op_sel:[0,0,0] op_sel_hi:[0,1,1] neg_lo:[1,0,0] neg_hi:[1,0,0]
	v_pk_fma_f32 v[54:55], v[70:71], v[250:251], v[54:55] op_sel:[1,0,0] op_sel_hi:[1,1,1] neg_lo:[1,0,0] neg_hi:[1,0,0]
	ds_read_b128 v[64:67], v176 offset:6944
	s_waitcnt lgkmcnt(7)
	v_pk_fma_f32 v[56:57], v[108:109], v[250:251], v[56:57] op_sel:[0,0,0] op_sel_hi:[0,1,1] neg_lo:[1,0,0] neg_hi:[1,0,0]
	v_pk_fma_f32 v[58:59], v[108:109], v[250:251], v[58:59] op_sel:[1,0,0] op_sel_hi:[1,1,1] neg_lo:[1,0,0] neg_hi:[1,0,0]
	v_pk_fma_f32 v[60:61], v[110:111], v[250:251], v[60:61] op_sel:[0,0,0] op_sel_hi:[0,1,1] neg_lo:[1,0,0] neg_hi:[1,0,0]
	v_pk_fma_f32 v[62:63], v[110:111], v[250:251], v[62:63] op_sel:[1,0,0] op_sel_hi:[1,1,1] neg_lo:[1,0,0] neg_hi:[1,0,0]
	ds_read_b128 v[68:71], v176 offset:6960
	v_cvt_pk_bf16_f32 v252, v112, v250
	v_cvt_pk_bf16_f32 v254, v113, v251
	v_mov_b32_dpp v112, v44 quad_perm:[2,2,2,2] row_mask:0xf bank_mask:0xf
	v_mov_b32_dpp v113, v45 quad_perm:[2,2,2,2] row_mask:0xf bank_mask:0xf
	s_waitcnt lgkmcnt(5)
	v_pk_fma_f32 v[44:45], v[216:217], v[112:113], v[44:45] op_sel:[0,0,0] op_sel_hi:[0,1,1] neg_lo:[1,0,0] neg_hi:[1,0,0]
	v_pk_fma_f32 v[46:47], v[216:217], v[112:113], v[46:47] op_sel:[1,0,0] op_sel_hi:[1,1,1] neg_lo:[1,0,0] neg_hi:[1,0,0]
	ds_read_b128 v[108:111], v176 offset:7184
	s_waitcnt lgkmcnt(5)
	v_pk_fma_f32 v[48:49], v[218:219], v[112:113], v[48:49] op_sel:[0,0,0] op_sel_hi:[0,1,1] neg_lo:[1,0,0] neg_hi:[1,0,0]
	v_pk_fma_f32 v[50:51], v[218:219], v[112:113], v[50:51] op_sel:[1,0,0] op_sel_hi:[1,1,1] neg_lo:[1,0,0] neg_hi:[1,0,0]
	v_pk_fma_f32 v[52:53], v[220:221], v[112:113], v[52:53] op_sel:[0,0,0] op_sel_hi:[0,1,1] neg_lo:[1,0,0] neg_hi:[1,0,0]
	v_pk_fma_f32 v[54:55], v[220:221], v[112:113], v[54:55] op_sel:[1,0,0] op_sel_hi:[1,1,1] neg_lo:[1,0,0] neg_hi:[1,0,0]
	ds_read_b128 v[214:217], v176 offset:7200
	s_waitcnt lgkmcnt(5)
	v_pk_fma_f32 v[56:57], v[226:227], v[112:113], v[56:57] op_sel:[0,0,0] op_sel_hi:[0,1,1] neg_lo:[1,0,0] neg_hi:[1,0,0]
	v_pk_fma_f32 v[58:59], v[226:227], v[112:113], v[58:59] op_sel:[1,0,0] op_sel_hi:[1,1,1] neg_lo:[1,0,0] neg_hi:[1,0,0]
	v_pk_fma_f32 v[60:61], v[228:229], v[112:113], v[60:61] op_sel:[0,0,0] op_sel_hi:[0,1,1] neg_lo:[1,0,0] neg_hi:[1,0,0]
	v_pk_fma_f32 v[62:63], v[228:229], v[112:113], v[62:63] op_sel:[1,0,0] op_sel_hi:[1,1,1] neg_lo:[1,0,0] neg_hi:[1,0,0]
	ds_read_b128 v[218:221], v176 offset:7216
	v_mov_b32_dpp v250, v44 quad_perm:[3,3,3,3] row_mask:0xf bank_mask:0xf
	v_mov_b32_dpp v251, v45 quad_perm:[3,3,3,3] row_mask:0xf bank_mask:0xf
	s_waitcnt lgkmcnt(5)
	v_pk_fma_f32 v[46:47], v[232:233], v[250:251], v[46:47] op_sel:[1,0,0] op_sel_hi:[1,1,1] neg_lo:[1,0,0] neg_hi:[1,0,0]
	ds_read_b128 v[226:229], v176 offset:7440
	s_waitcnt lgkmcnt(5)
	v_pk_fma_f32 v[48:49], v[64:65], v[250:251], v[48:49] op_sel:[0,0,0] op_sel_hi:[0,1,1] neg_lo:[1,0,0] neg_hi:[1,0,0]
	v_pk_fma_f32 v[50:51], v[64:65], v[250:251], v[50:51] op_sel:[1,0,0] op_sel_hi:[1,1,1] neg_lo:[1,0,0] neg_hi:[1,0,0]
	v_pk_fma_f32 v[52:53], v[66:67], v[250:251], v[52:53] op_sel:[0,0,0] op_sel_hi:[0,1,1] neg_lo:[1,0,0] neg_hi:[1,0,0]
	v_pk_fma_f32 v[54:55], v[66:67], v[250:251], v[54:55] op_sel:[1,0,0] op_sel_hi:[1,1,1] neg_lo:[1,0,0] neg_hi:[1,0,0]
	ds_read_b128 v[230:233], v176 offset:7456
	s_waitcnt lgkmcnt(5)
; #define LAS __attribute__((address_space(3)))
; template <int CTRL> __device__ __forceinline__ float dppf(float x) { return __builtin_bit_cast(float, __builtin_amdgcn_update_dpp(0, __builtin_bit_cast(int, x), CTRL, 0xf, 0xf, false)); }
; __device__ __forceinline__ u32x2 pack4(float a, float b, float c, float d) { u32x2 o; o.x = pk2(a, b); o.y = pk2(c, d); return o; }
; __device__ __forceinline__ void chunkA_item(const Args& A, LAS unsigned char* lds, int tid, int lane, int wave, int ci, int ci_next, HeadConstA& H) {
;     ...
;         for (int t = 0; t < 64; ++t) {
;             f32x2_t sa = {0.f, 0.f}, sb = {0.f, 0.f};
; #pragma unroll
;             for (int p = 0; p < ((t + 3) / 4 + 1) / 2; ++p) { const f32x2_t nv = *(const LAS f32x2_t*)(Np + t * 64 + 2 * p); sa += nv * xa[p]; sb += nv * xb[p]; }
;             float ua = sa.x + sa.y, ub = sb.x + sb.y;
;             ua += dppf<0xB1>(ua); ub += dppf<0xB1>(ub); ua += dppf<0x4E>(ua); ub += dppf<0x4E>(ub);
;             const float xta = Ra[t] - ua, xtb = Rb[t] - ub;
;             if (q == (t & 3)) { if ((t >> 2) & 1) { xa[t >> 3].y = xta; xb[t >> 3].y = xtb; } else { xa[t >> 3].x = xta; xb[t >> 3].x = xtb; } }
;             a4[t & 3] = xta; b4[t & 3] = xtb;
;             if ((t & 3) == 3 && q == 0) { *(LAS u32x2*)(lds + CA_XT + cp * 144 + (t - 3) * 2) = pack4(a4[0], a4[1], a4[2], a4[3]);
;                 *(LAS u32x2*)(lds + CA_XT + (64 + cp) * 144 + (t - 3) * 2) = pack4(b4[0], b4[1], b4[2], b4[3]); }
	v_pk_fma_f32 v[56:57], v[68:69], v[250:251], v[56:57] op_sel:[0,0,0] op_sel_hi:[0,1,1] neg_lo:[1,0,0] neg_hi:[1,0,0]
	v_pk_fma_f32 v[58:59], v[68:69], v[250:251], v[58:59] op_sel:[1,0,0] op_sel_hi:[1,1,1] neg_lo:[1,0,0] neg_hi:[1,0,0]
	v_pk_fma_f32 v[60:61], v[70:71], v[250:251], v[60:61] op_sel:[0,0,0] op_sel_hi:[0,1,1] neg_lo:[1,0,0] neg_hi:[1,0,0]
	v_pk_fma_f32 v[62:63], v[70:71], v[250:251], v[62:63] op_sel:[1,0,0] op_sel_hi:[1,1,1] neg_lo:[1,0,0] neg_hi:[1,0,0]
	ds_read_b128 v[64:67], v176 offset:7472
	v_cvt_pk_bf16_f32 v253, v112, v250
	v_cvt_pk_bf16_f32 v255, v113, v251
	s_mov_b64 exec, s[54:55]
	ds_write_b64 v202, v[252:253] offset:48
	ds_write_b64 v202, v[254:255] offset:9264
	s_mov_b64 exec, -1
	v_mov_b32_dpp v112, v46 quad_perm:[0,0,0,0] row_mask:0xf bank_mask:0xf
	v_mov_b32_dpp v113, v47 quad_perm:[0,0,0,0] row_mask:0xf bank_mask:0xf
	s_waitcnt lgkmcnt(7)
	v_pk_fma_f32 v[46:47], v[110:111], v[112:113], v[46:47] op_sel:[1,0,0] op_sel_hi:[1,1,1] neg_lo:[1,0,0] neg_hi:[1,0,0]
	ds_read_b128 v[68:71], v176 offset:7696
	s_waitcnt lgkmcnt(7)
	v_pk_fma_f32 v[48:49], v[214:215], v[112:113], v[48:49] op_sel:[0,0,0] op_sel_hi:[0,1,1] neg_lo:[1,0,0] neg_hi:[1,0,0]
	v_pk_fma_f32 v[50:51], v[214:215], v[112:113], v[50:51] op_sel:[1,0,0] op_sel_hi:[1,1,1] neg_lo:[1,0,0] neg_hi:[1,0,0]
	v_pk_fma_f32 v[52:53], v[216:217], v[112:113], v[52:53] op_sel:[0,0,0] op_sel_hi:[0,1,1] neg_lo:[1,0,0] neg_hi:[1,0,0]
	v_pk_fma_f32 v[54:55], v[216:217], v[112:113], v[54:55] op_sel:[1,0,0] op_sel_hi:[1,1,1] neg_lo:[1,0,0] neg_hi:[1,0,0]
	ds_read_b128 v[108:111], v176 offset:7712
	s_waitcnt lgkmcnt(7)
	v_pk_fma_f32 v[56:57], v[218:219], v[112:113], v[56:57] op_sel:[0,0,0] op_sel_hi:[0,1,1] neg_lo:[1,0,0] neg_hi:[1,0,0]
	v_pk_fma_f32 v[58:59], v[218:219], v[112:113], v[58:59] op_sel:[1,0,0] op_sel_hi:[1,1,1] neg_lo:[1,0,0] neg_hi:[1,0,0]
	v_pk_fma_f32 v[60:61], v[220:221], v[112:113], v[60:61] op_sel:[0,0,0] op_sel_hi:[0,1,1] neg_lo:[1,0,0] neg_hi:[1,0,0]
	v_pk_fma_f32 v[62:63], v[220:221], v[112:113], v[62:63] op_sel:[1,0,0] op_sel_hi:[1,1,1] neg_lo:[1,0,0] neg_hi:[1,0,0]
	ds_read_b128 v[214:217], v176 offset:7728
	v_mov_b32_dpp v250, v46 quad_perm:[1,1,1,1] row_mask:0xf bank_mask:0xf
	v_mov_b32_dpp v251, v47 quad_perm:[1,1,1,1] row_mask:0xf bank_mask:0xf
	s_waitcnt lgkmcnt(7)
	v_pk_fma_f32 v[46:47], v[228:229], v[250:251], v[46:47] op_sel:[1,0,0] op_sel_hi:[1,1,1] neg_lo:[1,0,0] neg_hi:[1,0,0]
	ds_read_b128 v[218:221], v176 offset:7952
	s_waitcnt lgkmcnt(7)
	v_pk_fma_f32 v[48:49], v[230:231], v[250:251], v[48:49] op_sel:[0,0,0] op_sel_hi:[0,1,1] neg_lo:[1,0,0] neg_hi:[1,0,0]
	v_pk_fma_f32 v[50:51], v[230:231], v[250:251], v[50:51] op_sel:[1,0,0] op_sel_hi:[1,1,1] neg_lo:[1,0,0] neg_hi:[1,0,0]
	v_pk_fma_f32 v[52:53], v[232:233], v[250:251], v[52:53] op_sel:[0,0,0] op_sel_hi:[0,1,1] neg_lo:[1,0,0] neg_hi:[1,0,0]
	v_pk_fma_f32 v[54:55], v[232:233], v[250:251], v[54:55] op_sel:[1,0,0] op_sel_hi:[1,1,1] neg_lo:[1,0,0] neg_hi:[1,0,0]
	ds_read_b128 v[226:229], v176 offset:7968
	s_waitcnt lgkmcnt(7)
	v_pk_fma_f32 v[56:57], v[64:65], v[250:251], v[56:57] op_sel:[0,0,0] op_sel_hi:[0,1,1] neg_lo:[1,0,0] neg_hi:[1,0,0]
	v_pk_fma_f32 v[58:59], v[64:65], v[250:251], v[58:59] op_sel:[1,0,0] op_sel_hi:[1,1,1] neg_lo:[1,0,0] neg_hi:[1,0,0]
	v_pk_fma_f32 v[60:61], v[66:67], v[250:251], v[60:61] op_sel:[0,0,0] op_sel_hi:[0,1,1] neg_lo:[1,0,0] neg_hi:[1,0,0]
	v_pk_fma_f32 v[62:63], v[66:67], v[250:251], v[62:63] op_sel:[1,0,0] op_sel_hi:[1,1,1] neg_lo:[1,0,0] neg_hi:[1,0,0]
	ds_read_b128 v[230:233], v176 offset:7984
	v_cvt_pk_bf16_f32 v252, v112, v250
	v_cvt_pk_bf16_f32 v254, v113, v251
	v_mov_b32_dpp v112, v46 quad_perm:[2,2,2,2] row_mask:0xf bank_mask:0xf
	v_mov_b32_dpp v113, v47 quad_perm:[2,2,2,2] row_mask:0xf bank_mask:0xf
	s_waitcnt lgkmcnt(5)
	v_pk_fma_f32 v[46:47], v[70:71], v[112:113], v[46:47] op_sel:[1,0,0] op_sel_hi:[1,1,1] neg_lo:[1,0,0] neg_hi:[1,0,0]
	ds_read_b128 v[64:67], v176 offset:8224
	s_waitcnt lgkmcnt(5)
	v_pk_fma_f32 v[48:49], v[108:109], v[112:113], v[48:49] op_sel:[0,0,0] op_sel_hi:[0,1,1] neg_lo:[1,0,0] neg_hi:[1,0,0]
	v_pk_fma_f32 v[50:51], v[108:109], v[112:113], v[50:51] op_sel:[1,0,0] op_sel_hi:[1,1,1] neg_lo:[1,0,0] neg_hi:[1,0,0]
	v_pk_fma_f32 v[52:53], v[110:111], v[112:113], v[52:53] op_sel:[0,0,0] op_sel_hi:[0,1,1] neg_lo:[1,0,0] neg_hi:[1,0,0]
	v_pk_fma_f32 v[54:55], v[110:111], v[112:113], v[54:55] op_sel:[1,0,0] op_sel_hi:[1,1,1] neg_lo:[1,0,0] neg_hi:[1,0,0]
	ds_read_b128 v[68:71], v176 offset:8240
	s_waitcnt lgkmcnt(5)
	v_pk_fma_f32 v[56:57], v[214:215], v[112:113], v[56:57] op_sel:[0,0,0] op_sel_hi:[0,1,1] neg_lo:[1,0,0] neg_hi:[1,0,0]
	v_pk_fma_f32 v[58:59], v[214:215], v[112:113], v[58:59] op_sel:[1,0,0] op_sel_hi:[1,1,1] neg_lo:[1,0,0] neg_hi:[1,0,0]
	v_pk_fma_f32 v[60:61], v[216:217], v[112:113], v[60:61] op_sel:[0,0,0] op_sel_hi:[0,1,1] neg_lo:[1,0,0] neg_hi:[1,0,0]
	v_pk_fma_f32 v[62:63], v[216:217], v[112:113], v[62:63] op_sel:[1,0,0] op_sel_hi:[1,1,1] neg_lo:[1,0,0] neg_hi:[1,0,0]
	ds_read_b128 v[108:111], v176 offset:8480
	v_mov_b32_dpp v250, v46 quad_perm:[3,3,3,3] row_mask:0xf bank_mask:0xf
	v_mov_b32_dpp v251, v47 quad_perm:[3,3,3,3] row_mask:0xf bank_mask:0xf
	s_waitcnt lgkmcnt(5)
	ds_read_b128 v[214:217], v176 offset:8496
	s_waitcnt lgkmcnt(5)
	v_pk_fma_f32 v[48:49], v[226:227], v[250:251], v[48:49] op_sel:[0,0,0] op_sel_hi:[0,1,1] neg_lo:[1,0,0] neg_hi:[1,0,0]
	v_pk_fma_f32 v[50:51], v[226:227], v[250:251], v[50:51] op_sel:[1,0,0] op_sel_hi:[1,1,1] neg_lo:[1,0,0] neg_hi:[1,0,0]
	v_pk_fma_f32 v[52:53], v[228:229], v[250:251], v[52:53] op_sel:[0,0,0] op_sel_hi:[0,1,1] neg_lo:[1,0,0] neg_hi:[1,0,0]
	v_pk_fma_f32 v[54:55], v[228:229], v[250:251], v[54:55] op_sel:[1,0,0] op_sel_hi:[1,1,1] neg_lo:[1,0,0] neg_hi:[1,0,0]
	ds_read_b128 v[218:221], v176 offset:8736
	s_waitcnt lgkmcnt(5)
; #define LAS __attribute__((address_space(3)))
; template <int CTRL> __device__ __forceinline__ float dppf(float x) { return __builtin_bit_cast(float, __builtin_amdgcn_update_dpp(0, __builtin_bit_cast(int, x), CTRL, 0xf, 0xf, false)); }
; __device__ __forceinline__ u32x2 pack4(float a, float b, float c, float d) { u32x2 o; o.x = pk2(a, b); o.y = pk2(c, d); return o; }
; __device__ __forceinline__ void chunkA_item(const Args& A, LAS unsigned char* lds, int tid, int lane, int wave, int ci, int ci_next, HeadConstA& H) {
;     ...
;         for (int t = 0; t < 64; ++t) {
;             f32x2_t sa = {0.f, 0.f}, sb = {0.f, 0.f};
; #pragma unroll
;             for (int p = 0; p < ((t + 3) / 4 + 1) / 2; ++p) { const f32x2_t nv = *(const LAS f32x2_t*)(Np + t * 64 + 2 * p); sa += nv * xa[p]; sb += nv * xb[p]; }
;             float ua = sa.x + sa.y, ub = sb.x + sb.y;
;             ua += dppf<0xB1>(ua); ub += dppf<0xB1>(ub); ua += dppf<0x4E>(ua); ub += dppf<0x4E>(ub);
;             const float xta = Ra[t] - ua, xtb = Rb[t] - ub;
;             if (q == (t & 3)) { if ((t >> 2) & 1) { xa[t >> 3].y = xta; xb[t >> 3].y = xtb; } else { xa[t >> 3].x = xta; xb[t >> 3].x = xtb; } }
;             a4[t & 3] = xta; b4[t & 3] = xtb;
;             if ((t & 3) == 3 && q == 0) { *(LAS u32x2*)(lds + CA_XT + cp * 144 + (t - 3) * 2) = pack4(a4[0], a4[1], a4[2], a4[3]);
;                 *(LAS u32x2*)(lds + CA_XT + (64 + cp) * 144 + (t - 3) * 2) = pack4(b4[0], b4[1], b4[2], b4[3]); }
	v_pk_fma_f32 v[56:57], v[230:231], v[250:251], v[56:57] op_sel:[0,0,0] op_sel_hi:[0,1,1] neg_lo:[1,0,0] neg_hi:[1,0,0]
	v_pk_fma_f32 v[58:59], v[230:231], v[250:251], v[58:59] op_sel:[1,0,0] op_sel_hi:[1,1,1] neg_lo:[1,0,0] neg_hi:[1,0,0]
	v_pk_fma_f32 v[60:61], v[232:233], v[250:251], v[60:61] op_sel:[0,0,0] op_sel_hi:[0,1,1] neg_lo:[1,0,0] neg_hi:[1,0,0]
	v_pk_fma_f32 v[62:63], v[232:233], v[250:251], v[62:63] op_sel:[1,0,0] op_sel_hi:[1,1,1] neg_lo:[1,0,0] neg_hi:[1,0,0]
	ds_read_b128 v[226:229], v176 offset:8752
	v_cvt_pk_bf16_f32 v253, v112, v250
	v_cvt_pk_bf16_f32 v255, v113, v251
	s_mov_b64 exec, s[54:55]
	ds_write_b64 v202, v[252:253] offset:56
	ds_write_b64 v202, v[254:255] offset:9272
	s_mov_b64 exec, -1
	v_mov_b32_dpp v112, v48 quad_perm:[0,0,0,0] row_mask:0xf bank_mask:0xf
	v_mov_b32_dpp v113, v49 quad_perm:[0,0,0,0] row_mask:0xf bank_mask:0xf
	s_waitcnt lgkmcnt(7)
	v_pk_fma_f32 v[48:49], v[64:65], v[112:113], v[48:49] op_sel:[0,0,0] op_sel_hi:[0,1,1] neg_lo:[1,0,0] neg_hi:[1,0,0]
	v_pk_fma_f32 v[50:51], v[64:65], v[112:113], v[50:51] op_sel:[1,0,0] op_sel_hi:[1,1,1] neg_lo:[1,0,0] neg_hi:[1,0,0]
	v_pk_fma_f32 v[52:53], v[66:67], v[112:113], v[52:53] op_sel:[0,0,0] op_sel_hi:[0,1,1] neg_lo:[1,0,0] neg_hi:[1,0,0]
	v_pk_fma_f32 v[54:55], v[66:67], v[112:113], v[54:55] op_sel:[1,0,0] op_sel_hi:[1,1,1] neg_lo:[1,0,0] neg_hi:[1,0,0]
	ds_read_b128 v[230:233], v176 offset:8992
	s_waitcnt lgkmcnt(7)
	v_pk_fma_f32 v[56:57], v[68:69], v[112:113], v[56:57] op_sel:[0,0,0] op_sel_hi:[0,1,1] neg_lo:[1,0,0] neg_hi:[1,0,0]
	v_pk_fma_f32 v[58:59], v[68:69], v[112:113], v[58:59] op_sel:[1,0,0] op_sel_hi:[1,1,1] neg_lo:[1,0,0] neg_hi:[1,0,0]
	v_pk_fma_f32 v[60:61], v[70:71], v[112:113], v[60:61] op_sel:[0,0,0] op_sel_hi:[0,1,1] neg_lo:[1,0,0] neg_hi:[1,0,0]
	v_pk_fma_f32 v[62:63], v[70:71], v[112:113], v[62:63] op_sel:[1,0,0] op_sel_hi:[1,1,1] neg_lo:[1,0,0] neg_hi:[1,0,0]
	ds_read_b128 v[64:67], v176 offset:9008
	v_mov_b32_dpp v250, v48 quad_perm:[1,1,1,1] row_mask:0xf bank_mask:0xf
	v_mov_b32_dpp v251, v49 quad_perm:[1,1,1,1] row_mask:0xf bank_mask:0xf
	s_waitcnt lgkmcnt(7)
	v_pk_fma_f32 v[48:49], v[108:109], v[250:251], v[48:49] op_sel:[0,0,0] op_sel_hi:[0,1,1] neg_lo:[1,0,0] neg_hi:[1,0,0]
	v_pk_fma_f32 v[50:51], v[108:109], v[250:251], v[50:51] op_sel:[1,0,0] op_sel_hi:[1,1,1] neg_lo:[1,0,0] neg_hi:[1,0,0]
	v_pk_fma_f32 v[52:53], v[110:111], v[250:251], v[52:53] op_sel:[0,0,0] op_sel_hi:[0,1,1] neg_lo:[1,0,0] neg_hi:[1,0,0]
	v_pk_fma_f32 v[54:55], v[110:111], v[250:251], v[54:55] op_sel:[1,0,0] op_sel_hi:[1,1,1] neg_lo:[1,0,0] neg_hi:[1,0,0]
	ds_read_b128 v[68:71], v176 offset:9248
	s_waitcnt lgkmcnt(7)
	v_pk_fma_f32 v[56:57], v[214:215], v[250:251], v[56:57] op_sel:[0,0,0] op_sel_hi:[0,1,1] neg_lo:[1,0,0] neg_hi:[1,0,0]
	v_pk_fma_f32 v[58:59], v[214:215], v[250:251], v[58:59] op_sel:[1,0,0] op_sel_hi:[1,1,1] neg_lo:[1,0,0] neg_hi:[1,0,0]
	v_pk_fma_f32 v[60:61], v[216:217], v[250:251], v[60:61] op_sel:[0,0,0] op_sel_hi:[0,1,1] neg_lo:[1,0,0] neg_hi:[1,0,0]
	v_pk_fma_f32 v[62:63], v[216:217], v[250:251], v[62:63] op_sel:[1,0,0] op_sel_hi:[1,1,1] neg_lo:[1,0,0] neg_hi:[1,0,0]
	ds_read_b128 v[108:111], v176 offset:9264
	v_cvt_pk_bf16_f32 v252, v112, v250
	v_cvt_pk_bf16_f32 v254, v113, v251
	v_mov_b32_dpp v112, v48 quad_perm:[2,2,2,2] row_mask:0xf bank_mask:0xf
	v_mov_b32_dpp v113, v49 quad_perm:[2,2,2,2] row_mask:0xf bank_mask:0xf
	s_waitcnt lgkmcnt(7)
	v_pk_fma_f32 v[48:49], v[218:219], v[112:113], v[48:49] op_sel:[0,0,0] op_sel_hi:[0,1,1] neg_lo:[1,0,0] neg_hi:[1,0,0]
	v_pk_fma_f32 v[50:51], v[218:219], v[112:113], v[50:51] op_sel:[1,0,0] op_sel_hi:[1,1,1] neg_lo:[1,0,0] neg_hi:[1,0,0]
	v_pk_fma_f32 v[52:53], v[220:221], v[112:113], v[52:53] op_sel:[0,0,0] op_sel_hi:[0,1,1] neg_lo:[1,0,0] neg_hi:[1,0,0]
	v_pk_fma_f32 v[54:55], v[220:221], v[112:113], v[54:55] op_sel:[1,0,0] op_sel_hi:[1,1,1] neg_lo:[1,0,0] neg_hi:[1,0,0]
	ds_read_b128 v[214:217], v176 offset:9504
	s_waitcnt lgkmcnt(7)
	v_pk_fma_f32 v[56:57], v[226:227], v[112:113], v[56:57] op_sel:[0,0,0] op_sel_hi:[0,1,1] neg_lo:[1,0,0] neg_hi:[1,0,0]
	v_pk_fma_f32 v[58:59], v[226:227], v[112:113], v[58:59] op_sel:[1,0,0] op_sel_hi:[1,1,1] neg_lo:[1,0,0] neg_hi:[1,0,0]
	v_pk_fma_f32 v[60:61], v[228:229], v[112:113], v[60:61] op_sel:[0,0,0] op_sel_hi:[0,1,1] neg_lo:[1,0,0] neg_hi:[1,0,0]
	v_pk_fma_f32 v[62:63], v[228:229], v[112:113], v[62:63] op_sel:[1,0,0] op_sel_hi:[1,1,1] neg_lo:[1,0,0] neg_hi:[1,0,0]
	ds_read_b128 v[218:221], v176 offset:9520
	v_mov_b32_dpp v250, v48 quad_perm:[3,3,3,3] row_mask:0xf bank_mask:0xf
	v_mov_b32_dpp v251, v49 quad_perm:[3,3,3,3] row_mask:0xf bank_mask:0xf
	s_waitcnt lgkmcnt(5)
	v_pk_fma_f32 v[50:51], v[230:231], v[250:251], v[50:51] op_sel:[1,0,0] op_sel_hi:[1,1,1] neg_lo:[1,0,0] neg_hi:[1,0,0]
	v_pk_fma_f32 v[52:53], v[232:233], v[250:251], v[52:53] op_sel:[0,0,0] op_sel_hi:[0,1,1] neg_lo:[1,0,0] neg_hi:[1,0,0]
	v_pk_fma_f32 v[54:55], v[232:233], v[250:251], v[54:55] op_sel:[1,0,0] op_sel_hi:[1,1,1] neg_lo:[1,0,0] neg_hi:[1,0,0]
	ds_read_b128 v[226:229], v176 offset:9760
	s_waitcnt lgkmcnt(5)
	v_pk_fma_f32 v[56:57], v[64:65], v[250:251], v[56:57] op_sel:[0,0,0] op_sel_hi:[0,1,1] neg_lo:[1,0,0] neg_hi:[1,0,0]
	v_pk_fma_f32 v[58:59], v[64:65], v[250:251], v[58:59] op_sel:[1,0,0] op_sel_hi:[1,1,1] neg_lo:[1,0,0] neg_hi:[1,0,0]
	v_pk_fma_f32 v[60:61], v[66:67], v[250:251], v[60:61] op_sel:[0,0,0] op_sel_hi:[0,1,1] neg_lo:[1,0,0] neg_hi:[1,0,0]
	v_pk_fma_f32 v[62:63], v[66:67], v[250:251], v[62:63] op_sel:[1,0,0] op_sel_hi:[1,1,1] neg_lo:[1,0,0] neg_hi:[1,0,0]
	ds_read_b128 v[230:233], v176 offset:9776
	v_cvt_pk_bf16_f32 v253, v112, v250
	v_cvt_pk_bf16_f32 v255, v113, v251
	s_mov_b64 exec, s[54:55]
	ds_write_b64 v202, v[252:253] offset:64
	ds_write_b64 v202, v[254:255] offset:9280
	s_mov_b64 exec, -1
	v_mov_b32_dpp v112, v50 quad_perm:[0,0,0,0] row_mask:0xf bank_mask:0xf
	v_mov_b32_dpp v113, v51 quad_perm:[0,0,0,0] row_mask:0xf bank_mask:0xf
	s_waitcnt lgkmcnt(7)
; #define LAS __attribute__((address_space(3)))
; template <int CTRL> __device__ __forceinline__ float dppf(float x) { return __builtin_bit_cast(float, __builtin_amdgcn_update_dpp(0, __builtin_bit_cast(int, x), CTRL, 0xf, 0xf, false)); }
; __device__ __forceinline__ u32x2 pack4(float a, float b, float c, float d) { u32x2 o; o.x = pk2(a, b); o.y = pk2(c, d); return o; }
; __device__ __forceinline__ void chunkA_item(const Args& A, LAS unsigned char* lds, int tid, int lane, int wave, int ci, int ci_next, HeadConstA& H) {
;     ...
;         for (int t = 0; t < 64; ++t) {
;             f32x2_t sa = {0.f, 0.f}, sb = {0.f, 0.f};
; #pragma unroll
;             for (int p = 0; p < ((t + 3) / 4 + 1) / 2; ++p) { const f32x2_t nv = *(const LAS f32x2_t*)(Np + t * 64 + 2 * p); sa += nv * xa[p]; sb += nv * xb[p]; }
;             float ua = sa.x + sa.y, ub = sb.x + sb.y;
;             ua += dppf<0xB1>(ua); ub += dppf<0xB1>(ub); ua += dppf<0x4E>(ua); ub += dppf<0x4E>(ub);
;             const float xta = Ra[t] - ua, xtb = Rb[t] - ub;
;             if (q == (t & 3)) { if ((t >> 2) & 1) { xa[t >> 3].y = xta; xb[t >> 3].y = xtb; } else { xa[t >> 3].x = xta; xb[t >> 3].x = xtb; } }
;             a4[t & 3] = xta; b4[t & 3] = xtb;
;             if ((t & 3) == 3 && q == 0) { *(LAS u32x2*)(lds + CA_XT + cp * 144 + (t - 3) * 2) = pack4(a4[0], a4[1], a4[2], a4[3]);
;                 *(LAS u32x2*)(lds + CA_XT + (64 + cp) * 144 + (t - 3) * 2) = pack4(b4[0], b4[1], b4[2], b4[3]); }
	v_pk_fma_f32 v[50:51], v[68:69], v[112:113], v[50:51] op_sel:[1,0,0] op_sel_hi:[1,1,1] neg_lo:[1,0,0] neg_hi:[1,0,0]
	v_pk_fma_f32 v[52:53], v[70:71], v[112:113], v[52:53] op_sel:[0,0,0] op_sel_hi:[0,1,1] neg_lo:[1,0,0] neg_hi:[1,0,0]
	v_pk_fma_f32 v[54:55], v[70:71], v[112:113], v[54:55] op_sel:[1,0,0] op_sel_hi:[1,1,1] neg_lo:[1,0,0] neg_hi:[1,0,0]
	ds_read_b128 v[64:67], v176 offset:10016
	s_waitcnt lgkmcnt(7)
	v_pk_fma_f32 v[56:57], v[108:109], v[112:113], v[56:57] op_sel:[0,0,0] op_sel_hi:[0,1,1] neg_lo:[1,0,0] neg_hi:[1,0,0]
	v_pk_fma_f32 v[58:59], v[108:109], v[112:113], v[58:59] op_sel:[1,0,0] op_sel_hi:[1,1,1] neg_lo:[1,0,0] neg_hi:[1,0,0]
	v_pk_fma_f32 v[60:61], v[110:111], v[112:113], v[60:61] op_sel:[0,0,0] op_sel_hi:[0,1,1] neg_lo:[1,0,0] neg_hi:[1,0,0]
	v_pk_fma_f32 v[62:63], v[110:111], v[112:113], v[62:63] op_sel:[1,0,0] op_sel_hi:[1,1,1] neg_lo:[1,0,0] neg_hi:[1,0,0]
	ds_read_b128 v[68:71], v176 offset:10032
	v_mov_b32_dpp v250, v50 quad_perm:[1,1,1,1] row_mask:0xf bank_mask:0xf
	v_mov_b32_dpp v251, v51 quad_perm:[1,1,1,1] row_mask:0xf bank_mask:0xf
	s_waitcnt lgkmcnt(7)
	v_pk_fma_f32 v[50:51], v[214:215], v[250:251], v[50:51] op_sel:[1,0,0] op_sel_hi:[1,1,1] neg_lo:[1,0,0] neg_hi:[1,0,0]
	v_pk_fma_f32 v[52:53], v[216:217], v[250:251], v[52:53] op_sel:[0,0,0] op_sel_hi:[0,1,1] neg_lo:[1,0,0] neg_hi:[1,0,0]
	v_pk_fma_f32 v[54:55], v[216:217], v[250:251], v[54:55] op_sel:[1,0,0] op_sel_hi:[1,1,1] neg_lo:[1,0,0] neg_hi:[1,0,0]
	ds_read_b128 v[108:111], v176 offset:10272
	s_waitcnt lgkmcnt(7)
	v_pk_fma_f32 v[56:57], v[218:219], v[250:251], v[56:57] op_sel:[0,0,0] op_sel_hi:[0,1,1] neg_lo:[1,0,0] neg_hi:[1,0,0]
	v_pk_fma_f32 v[58:59], v[218:219], v[250:251], v[58:59] op_sel:[1,0,0] op_sel_hi:[1,1,1] neg_lo:[1,0,0] neg_hi:[1,0,0]
	v_pk_fma_f32 v[60:61], v[220:221], v[250:251], v[60:61] op_sel:[0,0,0] op_sel_hi:[0,1,1] neg_lo:[1,0,0] neg_hi:[1,0,0]
	v_pk_fma_f32 v[62:63], v[220:221], v[250:251], v[62:63] op_sel:[1,0,0] op_sel_hi:[1,1,1] neg_lo:[1,0,0] neg_hi:[1,0,0]
	ds_read_b128 v[214:217], v176 offset:10288
	v_cvt_pk_bf16_f32 v252, v112, v250
	v_cvt_pk_bf16_f32 v254, v113, v251
	v_mov_b32_dpp v112, v50 quad_perm:[2,2,2,2] row_mask:0xf bank_mask:0xf
	v_mov_b32_dpp v113, v51 quad_perm:[2,2,2,2] row_mask:0xf bank_mask:0xf
	s_waitcnt lgkmcnt(7)
	v_pk_fma_f32 v[50:51], v[226:227], v[112:113], v[50:51] op_sel:[1,0,0] op_sel_hi:[1,1,1] neg_lo:[1,0,0] neg_hi:[1,0,0]
	v_pk_fma_f32 v[52:53], v[228:229], v[112:113], v[52:53] op_sel:[0,0,0] op_sel_hi:[0,1,1] neg_lo:[1,0,0] neg_hi:[1,0,0]
	v_pk_fma_f32 v[54:55], v[228:229], v[112:113], v[54:55] op_sel:[1,0,0] op_sel_hi:[1,1,1] neg_lo:[1,0,0] neg_hi:[1,0,0]
	ds_read_b128 v[218:221], v176 offset:10528
	s_waitcnt lgkmcnt(7)
	v_pk_fma_f32 v[56:57], v[230:231], v[112:113], v[56:57] op_sel:[0,0,0] op_sel_hi:[0,1,1] neg_lo:[1,0,0] neg_hi:[1,0,0]
	v_pk_fma_f32 v[58:59], v[230:231], v[112:113], v[58:59] op_sel:[1,0,0] op_sel_hi:[1,1,1] neg_lo:[1,0,0] neg_hi:[1,0,0]
	v_pk_fma_f32 v[60:61], v[232:233], v[112:113], v[60:61] op_sel:[0,0,0] op_sel_hi:[0,1,1] neg_lo:[1,0,0] neg_hi:[1,0,0]
	v_pk_fma_f32 v[62:63], v[232:233], v[112:113], v[62:63] op_sel:[1,0,0] op_sel_hi:[1,1,1] neg_lo:[1,0,0] neg_hi:[1,0,0]
	ds_read_b128 v[226:229], v176 offset:10544
	v_mov_b32_dpp v250, v50 quad_perm:[3,3,3,3] row_mask:0xf bank_mask:0xf
	v_mov_b32_dpp v251, v51 quad_perm:[3,3,3,3] row_mask:0xf bank_mask:0xf
	s_waitcnt lgkmcnt(5)
	v_pk_fma_f32 v[52:53], v[66:67], v[250:251], v[52:53] op_sel:[0,0,0] op_sel_hi:[0,1,1] neg_lo:[1,0,0] neg_hi:[1,0,0]
	v_pk_fma_f32 v[54:55], v[66:67], v[250:251], v[54:55] op_sel:[1,0,0] op_sel_hi:[1,1,1] neg_lo:[1,0,0] neg_hi:[1,0,0]
	ds_read_b128 v[230:233], v176 offset:10784
	s_waitcnt lgkmcnt(5)
	v_pk_fma_f32 v[56:57], v[68:69], v[250:251], v[56:57] op_sel:[0,0,0] op_sel_hi:[0,1,1] neg_lo:[1,0,0] neg_hi:[1,0,0]
	v_pk_fma_f32 v[58:59], v[68:69], v[250:251], v[58:59] op_sel:[1,0,0] op_sel_hi:[1,1,1] neg_lo:[1,0,0] neg_hi:[1,0,0]
	v_pk_fma_f32 v[60:61], v[70:71], v[250:251], v[60:61] op_sel:[0,0,0] op_sel_hi:[0,1,1] neg_lo:[1,0,0] neg_hi:[1,0,0]
	v_pk_fma_f32 v[62:63], v[70:71], v[250:251], v[62:63] op_sel:[1,0,0] op_sel_hi:[1,1,1] neg_lo:[1,0,0] neg_hi:[1,0,0]
	ds_read_b128 v[64:67], v176 offset:10800
	v_cvt_pk_bf16_f32 v253, v112, v250
	v_cvt_pk_bf16_f32 v255, v113, v251
	s_mov_b64 exec, s[54:55]
	ds_write_b64 v202, v[252:253] offset:72
	ds_write_b64 v202, v[254:255] offset:9288
	s_mov_b64 exec, -1
	v_mov_b32_dpp v112, v52 quad_perm:[0,0,0,0] row_mask:0xf bank_mask:0xf
	v_mov_b32_dpp v113, v53 quad_perm:[0,0,0,0] row_mask:0xf bank_mask:0xf
	s_waitcnt lgkmcnt(7)
	v_pk_fma_f32 v[52:53], v[110:111], v[112:113], v[52:53] op_sel:[0,0,0] op_sel_hi:[0,1,1] neg_lo:[1,0,0] neg_hi:[1,0,0]
	v_pk_fma_f32 v[54:55], v[110:111], v[112:113], v[54:55] op_sel:[1,0,0] op_sel_hi:[1,1,1] neg_lo:[1,0,0] neg_hi:[1,0,0]
	ds_read_b128 v[68:71], v176 offset:11040
	s_waitcnt lgkmcnt(7)
	v_pk_fma_f32 v[56:57], v[214:215], v[112:113], v[56:57] op_sel:[0,0,0] op_sel_hi:[0,1,1] neg_lo:[1,0,0] neg_hi:[1,0,0]
	v_pk_fma_f32 v[58:59], v[214:215], v[112:113], v[58:59] op_sel:[1,0,0] op_sel_hi:[1,1,1] neg_lo:[1,0,0] neg_hi:[1,0,0]
	v_pk_fma_f32 v[60:61], v[216:217], v[112:113], v[60:61] op_sel:[0,0,0] op_sel_hi:[0,1,1] neg_lo:[1,0,0] neg_hi:[1,0,0]
	v_pk_fma_f32 v[62:63], v[216:217], v[112:113], v[62:63] op_sel:[1,0,0] op_sel_hi:[1,1,1] neg_lo:[1,0,0] neg_hi:[1,0,0]
	ds_read_b128 v[108:111], v176 offset:11056
	v_mov_b32_dpp v250, v52 quad_perm:[1,1,1,1] row_mask:0xf bank_mask:0xf
	v_mov_b32_dpp v251, v53 quad_perm:[1,1,1,1] row_mask:0xf bank_mask:0xf
	s_waitcnt lgkmcnt(7)
; #define LAS __attribute__((address_space(3)))
; template <int CTRL> __device__ __forceinline__ float dppf(float x) { return __builtin_bit_cast(float, __builtin_amdgcn_update_dpp(0, __builtin_bit_cast(int, x), CTRL, 0xf, 0xf, false)); }
; __device__ __forceinline__ u32x2 pack4(float a, float b, float c, float d) { u32x2 o; o.x = pk2(a, b); o.y = pk2(c, d); return o; }
; __device__ __forceinline__ void chunkA_item(const Args& A, LAS unsigned char* lds, int tid, int lane, int wave, int ci, int ci_next, HeadConstA& H) {
;     ...
;         for (int t = 0; t < 64; ++t) {
;             f32x2_t sa = {0.f, 0.f}, sb = {0.f, 0.f};
; #pragma unroll
;             for (int p = 0; p < ((t + 3) / 4 + 1) / 2; ++p) { const f32x2_t nv = *(const LAS f32x2_t*)(Np + t * 64 + 2 * p); sa += nv * xa[p]; sb += nv * xb[p]; }
;             float ua = sa.x + sa.y, ub = sb.x + sb.y;
;             ua += dppf<0xB1>(ua); ub += dppf<0xB1>(ub); ua += dppf<0x4E>(ua); ub += dppf<0x4E>(ub);
;             const float xta = Ra[t] - ua, xtb = Rb[t] - ub;
;             if (q == (t & 3)) { if ((t >> 2) & 1) { xa[t >> 3].y = xta; xb[t >> 3].y = xtb; } else { xa[t >> 3].x = xta; xb[t >> 3].x = xtb; } }
;             a4[t & 3] = xta; b4[t & 3] = xtb;
;             if ((t & 3) == 3 && q == 0) { *(LAS u32x2*)(lds + CA_XT + cp * 144 + (t - 3) * 2) = pack4(a4[0], a4[1], a4[2], a4[3]);
;                 *(LAS u32x2*)(lds + CA_XT + (64 + cp) * 144 + (t - 3) * 2) = pack4(b4[0], b4[1], b4[2], b4[3]); }
	v_pk_fma_f32 v[52:53], v[220:221], v[250:251], v[52:53] op_sel:[0,0,0] op_sel_hi:[0,1,1] neg_lo:[1,0,0] neg_hi:[1,0,0]
	v_pk_fma_f32 v[54:55], v[220:221], v[250:251], v[54:55] op_sel:[1,0,0] op_sel_hi:[1,1,1] neg_lo:[1,0,0] neg_hi:[1,0,0]
	ds_read_b128 v[214:217], v176 offset:11296
	s_waitcnt lgkmcnt(7)
	v_pk_fma_f32 v[56:57], v[226:227], v[250:251], v[56:57] op_sel:[0,0,0] op_sel_hi:[0,1,1] neg_lo:[1,0,0] neg_hi:[1,0,0]
	v_pk_fma_f32 v[58:59], v[226:227], v[250:251], v[58:59] op_sel:[1,0,0] op_sel_hi:[1,1,1] neg_lo:[1,0,0] neg_hi:[1,0,0]
	v_pk_fma_f32 v[60:61], v[228:229], v[250:251], v[60:61] op_sel:[0,0,0] op_sel_hi:[0,1,1] neg_lo:[1,0,0] neg_hi:[1,0,0]
	v_pk_fma_f32 v[62:63], v[228:229], v[250:251], v[62:63] op_sel:[1,0,0] op_sel_hi:[1,1,1] neg_lo:[1,0,0] neg_hi:[1,0,0]
	ds_read_b128 v[218:221], v176 offset:11312
	v_cvt_pk_bf16_f32 v252, v112, v250
	v_cvt_pk_bf16_f32 v254, v113, v251
	v_mov_b32_dpp v112, v52 quad_perm:[2,2,2,2] row_mask:0xf bank_mask:0xf
	v_mov_b32_dpp v113, v53 quad_perm:[2,2,2,2] row_mask:0xf bank_mask:0xf
	s_waitcnt lgkmcnt(7)
	v_pk_fma_f32 v[52:53], v[232:233], v[112:113], v[52:53] op_sel:[0,0,0] op_sel_hi:[0,1,1] neg_lo:[1,0,0] neg_hi:[1,0,0]
	v_pk_fma_f32 v[54:55], v[232:233], v[112:113], v[54:55] op_sel:[1,0,0] op_sel_hi:[1,1,1] neg_lo:[1,0,0] neg_hi:[1,0,0]
	ds_read_b128 v[226:229], v176 offset:11552
	s_waitcnt lgkmcnt(7)
	v_pk_fma_f32 v[56:57], v[64:65], v[112:113], v[56:57] op_sel:[0,0,0] op_sel_hi:[0,1,1] neg_lo:[1,0,0] neg_hi:[1,0,0]
	v_pk_fma_f32 v[58:59], v[64:65], v[112:113], v[58:59] op_sel:[1,0,0] op_sel_hi:[1,1,1] neg_lo:[1,0,0] neg_hi:[1,0,0]
	v_pk_fma_f32 v[60:61], v[66:67], v[112:113], v[60:61] op_sel:[0,0,0] op_sel_hi:[0,1,1] neg_lo:[1,0,0] neg_hi:[1,0,0]
	v_pk_fma_f32 v[62:63], v[66:67], v[112:113], v[62:63] op_sel:[1,0,0] op_sel_hi:[1,1,1] neg_lo:[1,0,0] neg_hi:[1,0,0]
	ds_read_b128 v[230:233], v176 offset:11568
	v_mov_b32_dpp v250, v52 quad_perm:[3,3,3,3] row_mask:0xf bank_mask:0xf
	v_mov_b32_dpp v251, v53 quad_perm:[3,3,3,3] row_mask:0xf bank_mask:0xf
	s_waitcnt lgkmcnt(5)
	v_pk_fma_f32 v[54:55], v[70:71], v[250:251], v[54:55] op_sel:[1,0,0] op_sel_hi:[1,1,1] neg_lo:[1,0,0] neg_hi:[1,0,0]
	ds_read_b128 v[64:67], v176 offset:11808
	s_waitcnt lgkmcnt(5)
	v_pk_fma_f32 v[56:57], v[108:109], v[250:251], v[56:57] op_sel:[0,0,0] op_sel_hi:[0,1,1] neg_lo:[1,0,0] neg_hi:[1,0,0]
	v_pk_fma_f32 v[58:59], v[108:109], v[250:251], v[58:59] op_sel:[1,0,0] op_sel_hi:[1,1,1] neg_lo:[1,0,0] neg_hi:[1,0,0]
	v_pk_fma_f32 v[60:61], v[110:111], v[250:251], v[60:61] op_sel:[0,0,0] op_sel_hi:[0,1,1] neg_lo:[1,0,0] neg_hi:[1,0,0]
	v_pk_fma_f32 v[62:63], v[110:111], v[250:251], v[62:63] op_sel:[1,0,0] op_sel_hi:[1,1,1] neg_lo:[1,0,0] neg_hi:[1,0,0]
	ds_read_b128 v[68:71], v176 offset:11824
	v_cvt_pk_bf16_f32 v253, v112, v250
	v_cvt_pk_bf16_f32 v255, v113, v251
	s_mov_b64 exec, s[54:55]
	ds_write_b64 v202, v[252:253] offset:80
	ds_write_b64 v202, v[254:255] offset:9296
	s_mov_b64 exec, -1
	v_mov_b32_dpp v112, v54 quad_perm:[0,0,0,0] row_mask:0xf bank_mask:0xf
	v_mov_b32_dpp v113, v55 quad_perm:[0,0,0,0] row_mask:0xf bank_mask:0xf
	s_waitcnt lgkmcnt(7)
	v_pk_fma_f32 v[54:55], v[216:217], v[112:113], v[54:55] op_sel:[1,0,0] op_sel_hi:[1,1,1] neg_lo:[1,0,0] neg_hi:[1,0,0]
	ds_read_b128 v[108:111], v176 offset:12064
	s_waitcnt lgkmcnt(7)
	v_pk_fma_f32 v[56:57], v[218:219], v[112:113], v[56:57] op_sel:[0,0,0] op_sel_hi:[0,1,1] neg_lo:[1,0,0] neg_hi:[1,0,0]
	v_pk_fma_f32 v[58:59], v[218:219], v[112:113], v[58:59] op_sel:[1,0,0] op_sel_hi:[1,1,1] neg_lo:[1,0,0] neg_hi:[1,0,0]
	v_pk_fma_f32 v[60:61], v[220:221], v[112:113], v[60:61] op_sel:[0,0,0] op_sel_hi:[0,1,1] neg_lo:[1,0,0] neg_hi:[1,0,0]
	v_pk_fma_f32 v[62:63], v[220:221], v[112:113], v[62:63] op_sel:[1,0,0] op_sel_hi:[1,1,1] neg_lo:[1,0,0] neg_hi:[1,0,0]
	ds_read_b128 v[214:217], v176 offset:12080
	v_mov_b32_dpp v250, v54 quad_perm:[1,1,1,1] row_mask:0xf bank_mask:0xf
	v_mov_b32_dpp v251, v55 quad_perm:[1,1,1,1] row_mask:0xf bank_mask:0xf
	s_waitcnt lgkmcnt(7)
	v_pk_fma_f32 v[54:55], v[228:229], v[250:251], v[54:55] op_sel:[1,0,0] op_sel_hi:[1,1,1] neg_lo:[1,0,0] neg_hi:[1,0,0]
	ds_read_b128 v[218:221], v176 offset:12336
	s_waitcnt lgkmcnt(7)
	v_pk_fma_f32 v[56:57], v[230:231], v[250:251], v[56:57] op_sel:[0,0,0] op_sel_hi:[0,1,1] neg_lo:[1,0,0] neg_hi:[1,0,0]
	v_pk_fma_f32 v[58:59], v[230:231], v[250:251], v[58:59] op_sel:[1,0,0] op_sel_hi:[1,1,1] neg_lo:[1,0,0] neg_hi:[1,0,0]
	v_pk_fma_f32 v[60:61], v[232:233], v[250:251], v[60:61] op_sel:[0,0,0] op_sel_hi:[0,1,1] neg_lo:[1,0,0] neg_hi:[1,0,0]
	v_pk_fma_f32 v[62:63], v[232:233], v[250:251], v[62:63] op_sel:[1,0,0] op_sel_hi:[1,1,1] neg_lo:[1,0,0] neg_hi:[1,0,0]
	ds_read_b128 v[226:229], v176 offset:12592
	v_cvt_pk_bf16_f32 v252, v112, v250
	v_cvt_pk_bf16_f32 v254, v113, v251
	v_mov_b32_dpp v112, v54 quad_perm:[2,2,2,2] row_mask:0xf bank_mask:0xf
	v_mov_b32_dpp v113, v55 quad_perm:[2,2,2,2] row_mask:0xf bank_mask:0xf
	s_waitcnt lgkmcnt(7)
	v_pk_fma_f32 v[54:55], v[66:67], v[112:113], v[54:55] op_sel:[1,0,0] op_sel_hi:[1,1,1] neg_lo:[1,0,0] neg_hi:[1,0,0]
	ds_read_b128 v[230:233], v176 offset:12848
	s_waitcnt lgkmcnt(7)
	v_pk_fma_f32 v[56:57], v[68:69], v[112:113], v[56:57] op_sel:[0,0,0] op_sel_hi:[0,1,1] neg_lo:[1,0,0] neg_hi:[1,0,0]
	v_pk_fma_f32 v[58:59], v[68:69], v[112:113], v[58:59] op_sel:[1,0,0] op_sel_hi:[1,1,1] neg_lo:[1,0,0] neg_hi:[1,0,0]
	v_pk_fma_f32 v[60:61], v[70:71], v[112:113], v[60:61] op_sel:[0,0,0] op_sel_hi:[0,1,1] neg_lo:[1,0,0] neg_hi:[1,0,0]
	v_pk_fma_f32 v[62:63], v[70:71], v[112:113], v[62:63] op_sel:[1,0,0] op_sel_hi:[1,1,1] neg_lo:[1,0,0] neg_hi:[1,0,0]
	ds_read_b128 v[64:67], v176 offset:13104
	v_mov_b32_dpp v250, v54 quad_perm:[3,3,3,3] row_mask:0xf bank_mask:0xf
	v_mov_b32_dpp v251, v55 quad_perm:[3,3,3,3] row_mask:0xf bank_mask:0xf
	s_waitcnt lgkmcnt(5)
; #define LAS __attribute__((address_space(3)))
; template <int CTRL> __device__ __forceinline__ float dppf(float x) { return __builtin_bit_cast(float, __builtin_amdgcn_update_dpp(0, __builtin_bit_cast(int, x), CTRL, 0xf, 0xf, false)); }
; __device__ __forceinline__ u32x2 pack4(float a, float b, float c, float d) { u32x2 o; o.x = pk2(a, b); o.y = pk2(c, d); return o; }
; __device__ __forceinline__ void chunkA_item(const Args& A, LAS unsigned char* lds, int tid, int lane, int wave, int ci, int ci_next, HeadConstA& H) {
;     ...
;         for (int t = 0; t < 64; ++t) {
;             f32x2_t sa = {0.f, 0.f}, sb = {0.f, 0.f};
; #pragma unroll
;             for (int p = 0; p < ((t + 3) / 4 + 1) / 2; ++p) { const f32x2_t nv = *(const LAS f32x2_t*)(Np + t * 64 + 2 * p); sa += nv * xa[p]; sb += nv * xb[p]; }
;             float ua = sa.x + sa.y, ub = sb.x + sb.y;
;             ua += dppf<0xB1>(ua); ub += dppf<0xB1>(ub); ua += dppf<0x4E>(ua); ub += dppf<0x4E>(ub);
;             const float xta = Ra[t] - ua, xtb = Rb[t] - ub;
;             if (q == (t & 3)) { if ((t >> 2) & 1) { xa[t >> 3].y = xta; xb[t >> 3].y = xtb; } else { xa[t >> 3].x = xta; xb[t >> 3].x = xtb; } }
;             a4[t & 3] = xta; b4[t & 3] = xtb;
;             if ((t & 3) == 3 && q == 0) { *(LAS u32x2*)(lds + CA_XT + cp * 144 + (t - 3) * 2) = pack4(a4[0], a4[1], a4[2], a4[3]);
;                 *(LAS u32x2*)(lds + CA_XT + (64 + cp) * 144 + (t - 3) * 2) = pack4(b4[0], b4[1], b4[2], b4[3]); }
	ds_read_b128 v[68:71], v176 offset:13360
	s_waitcnt lgkmcnt(5)
	v_pk_fma_f32 v[56:57], v[214:215], v[250:251], v[56:57] op_sel:[0,0,0] op_sel_hi:[0,1,1] neg_lo:[1,0,0] neg_hi:[1,0,0]
	v_pk_fma_f32 v[58:59], v[214:215], v[250:251], v[58:59] op_sel:[1,0,0] op_sel_hi:[1,1,1] neg_lo:[1,0,0] neg_hi:[1,0,0]
	v_pk_fma_f32 v[60:61], v[216:217], v[250:251], v[60:61] op_sel:[0,0,0] op_sel_hi:[0,1,1] neg_lo:[1,0,0] neg_hi:[1,0,0]
	v_pk_fma_f32 v[62:63], v[216:217], v[250:251], v[62:63] op_sel:[1,0,0] op_sel_hi:[1,1,1] neg_lo:[1,0,0] neg_hi:[1,0,0]
	ds_read_b128 v[108:111], v176 offset:13616
	v_cvt_pk_bf16_f32 v253, v112, v250
	v_cvt_pk_bf16_f32 v255, v113, v251
	s_mov_b64 exec, s[54:55]
	ds_write_b64 v202, v[252:253] offset:88
	ds_write_b64 v202, v[254:255] offset:9304
	s_mov_b64 exec, -1
	v_mov_b32_dpp v112, v56 quad_perm:[0,0,0,0] row_mask:0xf bank_mask:0xf
	v_mov_b32_dpp v113, v57 quad_perm:[0,0,0,0] row_mask:0xf bank_mask:0xf
	s_waitcnt lgkmcnt(7)
	v_pk_fma_f32 v[56:57], v[218:219], v[112:113], v[56:57] op_sel:[0,0,0] op_sel_hi:[0,1,1] neg_lo:[1,0,0] neg_hi:[1,0,0]
	v_pk_fma_f32 v[58:59], v[218:219], v[112:113], v[58:59] op_sel:[1,0,0] op_sel_hi:[1,1,1] neg_lo:[1,0,0] neg_hi:[1,0,0]
	v_pk_fma_f32 v[60:61], v[220:221], v[112:113], v[60:61] op_sel:[0,0,0] op_sel_hi:[0,1,1] neg_lo:[1,0,0] neg_hi:[1,0,0]
	v_pk_fma_f32 v[62:63], v[220:221], v[112:113], v[62:63] op_sel:[1,0,0] op_sel_hi:[1,1,1] neg_lo:[1,0,0] neg_hi:[1,0,0]
	ds_read_b128 v[214:217], v176 offset:13872
	v_mov_b32_dpp v250, v56 quad_perm:[1,1,1,1] row_mask:0xf bank_mask:0xf
	v_mov_b32_dpp v251, v57 quad_perm:[1,1,1,1] row_mask:0xf bank_mask:0xf
	s_waitcnt lgkmcnt(7)
	v_pk_fma_f32 v[56:57], v[226:227], v[250:251], v[56:57] op_sel:[0,0,0] op_sel_hi:[0,1,1] neg_lo:[1,0,0] neg_hi:[1,0,0]
	v_pk_fma_f32 v[58:59], v[226:227], v[250:251], v[58:59] op_sel:[1,0,0] op_sel_hi:[1,1,1] neg_lo:[1,0,0] neg_hi:[1,0,0]
	v_pk_fma_f32 v[60:61], v[228:229], v[250:251], v[60:61] op_sel:[0,0,0] op_sel_hi:[0,1,1] neg_lo:[1,0,0] neg_hi:[1,0,0]
	v_pk_fma_f32 v[62:63], v[228:229], v[250:251], v[62:63] op_sel:[1,0,0] op_sel_hi:[1,1,1] neg_lo:[1,0,0] neg_hi:[1,0,0]
	ds_read_b128 v[218:221], v176 offset:14128
	v_cvt_pk_bf16_f32 v252, v112, v250
	v_cvt_pk_bf16_f32 v254, v113, v251
	v_mov_b32_dpp v112, v56 quad_perm:[2,2,2,2] row_mask:0xf bank_mask:0xf
	v_mov_b32_dpp v113, v57 quad_perm:[2,2,2,2] row_mask:0xf bank_mask:0xf
	s_waitcnt lgkmcnt(7)
	v_pk_fma_f32 v[56:57], v[230:231], v[112:113], v[56:57] op_sel:[0,0,0] op_sel_hi:[0,1,1] neg_lo:[1,0,0] neg_hi:[1,0,0]
	v_pk_fma_f32 v[58:59], v[230:231], v[112:113], v[58:59] op_sel:[1,0,0] op_sel_hi:[1,1,1] neg_lo:[1,0,0] neg_hi:[1,0,0]
	v_pk_fma_f32 v[60:61], v[232:233], v[112:113], v[60:61] op_sel:[0,0,0] op_sel_hi:[0,1,1] neg_lo:[1,0,0] neg_hi:[1,0,0]
	v_pk_fma_f32 v[62:63], v[232:233], v[112:113], v[62:63] op_sel:[1,0,0] op_sel_hi:[1,1,1] neg_lo:[1,0,0] neg_hi:[1,0,0]
	ds_read_b128 v[226:229], v176 offset:14384
	v_mov_b32_dpp v250, v56 quad_perm:[3,3,3,3] row_mask:0xf bank_mask:0xf
	v_mov_b32_dpp v251, v57 quad_perm:[3,3,3,3] row_mask:0xf bank_mask:0xf
	s_waitcnt lgkmcnt(7)
	v_pk_fma_f32 v[58:59], v[64:65], v[250:251], v[58:59] op_sel:[1,0,0] op_sel_hi:[1,1,1] neg_lo:[1,0,0] neg_hi:[1,0,0]
	v_pk_fma_f32 v[60:61], v[66:67], v[250:251], v[60:61] op_sel:[0,0,0] op_sel_hi:[0,1,1] neg_lo:[1,0,0] neg_hi:[1,0,0]
	v_pk_fma_f32 v[62:63], v[66:67], v[250:251], v[62:63] op_sel:[1,0,0] op_sel_hi:[1,1,1] neg_lo:[1,0,0] neg_hi:[1,0,0]
	ds_read_b128 v[230:233], v176 offset:14640
	v_cvt_pk_bf16_f32 v253, v112, v250
	v_cvt_pk_bf16_f32 v255, v113, v251
	s_mov_b64 exec, s[54:55]
	ds_write_b64 v202, v[252:253] offset:96
	ds_write_b64 v202, v[254:255] offset:9312
	s_mov_b64 exec, -1
	v_mov_b32_dpp v112, v58 quad_perm:[0,0,0,0] row_mask:0xf bank_mask:0xf
	v_mov_b32_dpp v113, v59 quad_perm:[0,0,0,0] row_mask:0xf bank_mask:0xf
	s_waitcnt lgkmcnt(9)
	v_pk_fma_f32 v[58:59], v[68:69], v[112:113], v[58:59] op_sel:[1,0,0] op_sel_hi:[1,1,1] neg_lo:[1,0,0] neg_hi:[1,0,0]
	v_pk_fma_f32 v[60:61], v[70:71], v[112:113], v[60:61] op_sel:[0,0,0] op_sel_hi:[0,1,1] neg_lo:[1,0,0] neg_hi:[1,0,0]
	v_pk_fma_f32 v[62:63], v[70:71], v[112:113], v[62:63] op_sel:[1,0,0] op_sel_hi:[1,1,1] neg_lo:[1,0,0] neg_hi:[1,0,0]
	ds_read_b128 v[64:67], v176 offset:14896
	v_mov_b32_dpp v250, v58 quad_perm:[1,1,1,1] row_mask:0xf bank_mask:0xf
	v_mov_b32_dpp v251, v59 quad_perm:[1,1,1,1] row_mask:0xf bank_mask:0xf
	s_waitcnt lgkmcnt(9)
; #define LAS __attribute__((address_space(3)))
; template <int CTRL> __device__ __forceinline__ float dppf(float x) { return __builtin_bit_cast(float, __builtin_amdgcn_update_dpp(0, __builtin_bit_cast(int, x), CTRL, 0xf, 0xf, false)); }
; __device__ __forceinline__ u32x2 pack4(float a, float b, float c, float d) { u32x2 o; o.x = pk2(a, b); o.y = pk2(c, d); return o; }
; __device__ __forceinline__ void chunkA_item(const Args& A, LAS unsigned char* lds, int tid, int lane, int wave, int ci, int ci_next, HeadConstA& H) {
;     ...
;         for (int t = 0; t < 64; ++t) {
;             f32x2_t sa = {0.f, 0.f}, sb = {0.f, 0.f};
; #pragma unroll
;             for (int p = 0; p < ((t + 3) / 4 + 1) / 2; ++p) { const f32x2_t nv = *(const LAS f32x2_t*)(Np + t * 64 + 2 * p); sa += nv * xa[p]; sb += nv * xb[p]; }
;             float ua = sa.x + sa.y, ub = sb.x + sb.y;
;             ua += dppf<0xB1>(ua); ub += dppf<0xB1>(ub); ua += dppf<0x4E>(ua); ub += dppf<0x4E>(ub);
;             const float xta = Ra[t] - ua, xtb = Rb[t] - ub;
;             if (q == (t & 3)) { if ((t >> 2) & 1) { xa[t >> 3].y = xta; xb[t >> 3].y = xtb; } else { xa[t >> 3].x = xta; xb[t >> 3].x = xtb; } }
;             a4[t & 3] = xta; b4[t & 3] = xtb;
;             if ((t & 3) == 3 && q == 0) { *(LAS u32x2*)(lds + CA_XT + cp * 144 + (t - 3) * 2) = pack4(a4[0], a4[1], a4[2], a4[3]);
;                 *(LAS u32x2*)(lds + CA_XT + (64 + cp) * 144 + (t - 3) * 2) = pack4(b4[0], b4[1], b4[2], b4[3]); }
;         }
	v_pk_fma_f32 v[58:59], v[108:109], v[250:251], v[58:59] op_sel:[1,0,0] op_sel_hi:[1,1,1] neg_lo:[1,0,0] neg_hi:[1,0,0]
	v_pk_fma_f32 v[60:61], v[110:111], v[250:251], v[60:61] op_sel:[0,0,0] op_sel_hi:[0,1,1] neg_lo:[1,0,0] neg_hi:[1,0,0]
	v_pk_fma_f32 v[62:63], v[110:111], v[250:251], v[62:63] op_sel:[1,0,0] op_sel_hi:[1,1,1] neg_lo:[1,0,0] neg_hi:[1,0,0]
	ds_read_b128 v[68:71], v176 offset:15152
	v_cvt_pk_bf16_f32 v252, v112, v250
	v_cvt_pk_bf16_f32 v254, v113, v251
	v_mov_b32_dpp v112, v58 quad_perm:[2,2,2,2] row_mask:0xf bank_mask:0xf
	v_mov_b32_dpp v113, v59 quad_perm:[2,2,2,2] row_mask:0xf bank_mask:0xf
	s_waitcnt lgkmcnt(7)
	v_pk_fma_f32 v[58:59], v[214:215], v[112:113], v[58:59] op_sel:[1,0,0] op_sel_hi:[1,1,1] neg_lo:[1,0,0] neg_hi:[1,0,0]
	v_pk_fma_f32 v[60:61], v[216:217], v[112:113], v[60:61] op_sel:[0,0,0] op_sel_hi:[0,1,1] neg_lo:[1,0,0] neg_hi:[1,0,0]
	v_pk_fma_f32 v[62:63], v[216:217], v[112:113], v[62:63] op_sel:[1,0,0] op_sel_hi:[1,1,1] neg_lo:[1,0,0] neg_hi:[1,0,0]
	ds_read_b128 v[108:111], v176 offset:15408
	v_mov_b32_dpp v250, v58 quad_perm:[3,3,3,3] row_mask:0xf bank_mask:0xf
	v_mov_b32_dpp v251, v59 quad_perm:[3,3,3,3] row_mask:0xf bank_mask:0xf
	s_waitcnt lgkmcnt(7)
	v_pk_fma_f32 v[60:61], v[220:221], v[250:251], v[60:61] op_sel:[0,0,0] op_sel_hi:[0,1,1] neg_lo:[1,0,0] neg_hi:[1,0,0]
	v_pk_fma_f32 v[62:63], v[220:221], v[250:251], v[62:63] op_sel:[1,0,0] op_sel_hi:[1,1,1] neg_lo:[1,0,0] neg_hi:[1,0,0]
	ds_read_b128 v[214:217], v176 offset:15664
	v_cvt_pk_bf16_f32 v253, v112, v250
	v_cvt_pk_bf16_f32 v255, v113, v251
	s_mov_b64 exec, s[54:55]
	ds_write_b64 v202, v[252:253] offset:104
	ds_write_b64 v202, v[254:255] offset:9320
	s_mov_b64 exec, -1
	v_mov_b32_dpp v112, v60 quad_perm:[0,0,0,0] row_mask:0xf bank_mask:0xf
	v_mov_b32_dpp v113, v61 quad_perm:[0,0,0,0] row_mask:0xf bank_mask:0xf
	s_waitcnt lgkmcnt(9)
	v_pk_fma_f32 v[60:61], v[228:229], v[112:113], v[60:61] op_sel:[0,0,0] op_sel_hi:[0,1,1] neg_lo:[1,0,0] neg_hi:[1,0,0]
	v_pk_fma_f32 v[62:63], v[228:229], v[112:113], v[62:63] op_sel:[1,0,0] op_sel_hi:[1,1,1] neg_lo:[1,0,0] neg_hi:[1,0,0]
	ds_read_b128 v[218:221], v176 offset:15920
	v_mov_b32_dpp v250, v60 quad_perm:[1,1,1,1] row_mask:0xf bank_mask:0xf
	v_mov_b32_dpp v251, v61 quad_perm:[1,1,1,1] row_mask:0xf bank_mask:0xf
	s_waitcnt lgkmcnt(9)
	v_pk_fma_f32 v[60:61], v[232:233], v[250:251], v[60:61] op_sel:[0,0,0] op_sel_hi:[0,1,1] neg_lo:[1,0,0] neg_hi:[1,0,0]
	v_pk_fma_f32 v[62:63], v[232:233], v[250:251], v[62:63] op_sel:[1,0,0] op_sel_hi:[1,1,1] neg_lo:[1,0,0] neg_hi:[1,0,0]
	v_cvt_pk_bf16_f32 v252, v112, v250
	v_cvt_pk_bf16_f32 v254, v113, v251
	v_mov_b32_dpp v112, v60 quad_perm:[2,2,2,2] row_mask:0xf bank_mask:0xf
	v_mov_b32_dpp v113, v61 quad_perm:[2,2,2,2] row_mask:0xf bank_mask:0xf
	s_waitcnt lgkmcnt(6)
	v_pk_fma_f32 v[60:61], v[66:67], v[112:113], v[60:61] op_sel:[0,0,0] op_sel_hi:[0,1,1] neg_lo:[1,0,0] neg_hi:[1,0,0]
	v_pk_fma_f32 v[62:63], v[66:67], v[112:113], v[62:63] op_sel:[1,0,0] op_sel_hi:[1,1,1] neg_lo:[1,0,0] neg_hi:[1,0,0]
	s_nop 0
	v_mov_b32_dpp v250, v60 quad_perm:[3,3,3,3] row_mask:0xf bank_mask:0xf
	v_mov_b32_dpp v251, v61 quad_perm:[3,3,3,3] row_mask:0xf bank_mask:0xf
	s_waitcnt lgkmcnt(5)
	v_pk_fma_f32 v[62:63], v[70:71], v[250:251], v[62:63] op_sel:[1,0,0] op_sel_hi:[1,1,1] neg_lo:[1,0,0] neg_hi:[1,0,0]
	v_cvt_pk_bf16_f32 v253, v112, v250
	v_cvt_pk_bf16_f32 v255, v113, v251
	s_mov_b64 exec, s[54:55]
	ds_write_b64 v202, v[252:253] offset:112
	ds_write_b64 v202, v[254:255] offset:9328
	s_mov_b64 exec, -1
	v_mov_b32_dpp v112, v62 quad_perm:[0,0,0,0] row_mask:0xf bank_mask:0xf
	v_mov_b32_dpp v113, v63 quad_perm:[0,0,0,0] row_mask:0xf bank_mask:0xf
	s_waitcnt lgkmcnt(6)
	v_pk_fma_f32 v[62:63], v[110:111], v[112:113], v[62:63] op_sel:[1,0,0] op_sel_hi:[1,1,1] neg_lo:[1,0,0] neg_hi:[1,0,0]
	s_nop 1
	v_mov_b32_dpp v250, v62 quad_perm:[1,1,1,1] row_mask:0xf bank_mask:0xf
	v_mov_b32_dpp v251, v63 quad_perm:[1,1,1,1] row_mask:0xf bank_mask:0xf
	s_waitcnt lgkmcnt(5)
	v_pk_fma_f32 v[62:63], v[216:217], v[250:251], v[62:63] op_sel:[1,0,0] op_sel_hi:[1,1,1] neg_lo:[1,0,0] neg_hi:[1,0,0]
	v_cvt_pk_bf16_f32 v252, v112, v250
	v_cvt_pk_bf16_f32 v254, v113, v251
	v_mov_b32_dpp v112, v62 quad_perm:[2,2,2,2] row_mask:0xf bank_mask:0xf
	v_mov_b32_dpp v113, v63 quad_perm:[2,2,2,2] row_mask:0xf bank_mask:0xf
	s_waitcnt lgkmcnt(2)
	v_pk_fma_f32 v[62:63], v[220:221], v[112:113], v[62:63] op_sel:[1,0,0] op_sel_hi:[1,1,1] neg_lo:[1,0,0] neg_hi:[1,0,0]
	s_nop 1
	v_mov_b32_dpp v250, v62 quad_perm:[3,3,3,3] row_mask:0xf bank_mask:0xf
	v_mov_b32_dpp v251, v63 quad_perm:[3,3,3,3] row_mask:0xf bank_mask:0xf
	v_cvt_pk_bf16_f32 v253, v112, v250
	v_cvt_pk_bf16_f32 v255, v113, v251
	s_mov_b64 exec, s[54:55]
	ds_write_b64 v202, v[252:253] offset:120
	ds_write_b64 v202, v[254:255] offset:9336
	s_mov_b64 exec, -1
	s_branch .LBB0_146

; #define LAS __attribute__((address_space(3)))
; __global__ void __launch_bounds__(512, 2) hymba_fwd(Args A) {
;     extern __shared__ __attribute__((aligned(16))) unsigned char lds_raw[];
;     LAS unsigned char* lds = (LAS unsigned char*)lds_raw;
;     cg::grid_group grid = cg::this_grid();
;     const int tid = threadIdx.x, lane = tid & 63, wave = __builtin_amdgcn_readfirstlane(tid >> 6);
	.amdhsa_kernel _Z9hymba_fwd4Args
		.amdhsa_group_segment_fixed_size 0
		.amdhsa_private_segment_fixed_size 0
		.amdhsa_kernarg_size 480
		.amdhsa_user_sgpr_count 2
		.amdhsa_user_sgpr_dispatch_ptr 0
		.amdhsa_user_sgpr_queue_ptr 0
		.amdhsa_user_sgpr_kernarg_segment_ptr 1
		.amdhsa_user_sgpr_dispatch_id 0
		.amdhsa_user_sgpr_kernarg_preload_length 0
		.amdhsa_user_sgpr_kernarg_preload_offset 0
		.amdhsa_user_sgpr_private_segment_size 0
		.amdhsa_uses_dynamic_stack 0
		.amdhsa_enable_private_segment 0
		.amdhsa_system_sgpr_workgroup_id_x 1
		.amdhsa_system_sgpr_workgroup_id_y 0
		.amdhsa_system_sgpr_workgroup_id_z 0
		.amdhsa_system_sgpr_workgroup_info 0
		.amdhsa_system_vgpr_workitem_id 2
		.amdhsa_next_free_vgpr 256
		.amdhsa_next_free_sgpr 98
		.amdhsa_accum_offset 256
		.amdhsa_reserve_vcc 1
		.amdhsa_float_round_mode_32 0
		.amdhsa_float_round_mode_16_64 0
		.amdhsa_float_denorm_mode_32 3
		.amdhsa_float_denorm_mode_16_64 3
		.amdhsa_dx10_clamp 1
		.amdhsa_ieee_mode 1
		.amdhsa_fp16_overflow 0
		.amdhsa_tg_split 0
		.amdhsa_exception_fp_ieee_invalid_op 0
		.amdhsa_exception_fp_denorm_src 0
		.amdhsa_exception_fp_ieee_div_zero 0
		.amdhsa_exception_fp_ieee_overflow 0
		.amdhsa_exception_fp_ieee_underflow 0
		.amdhsa_exception_fp_ieee_inexact 0
		.amdhsa_exception_int_div_zero 0
	.end_amdhsa_kernel

; #define LAS __attribute__((address_space(3)))
; __global__ void __launch_bounds__(512, 2) hymba_fwd(Args A) {
;     extern __shared__ __attribute__((aligned(16))) unsigned char lds_raw[];
;     LAS unsigned char* lds = (LAS unsigned char*)lds_raw;
;     cg::grid_group grid = cg::this_grid();
;     const int tid = threadIdx.x, lane = tid & 63, wave = __builtin_amdgcn_readfirstlane(tid >> 6);
.Lfunc_end0:
	.size	_Z9hymba_fwd4Args, .Lfunc_end0-_Z9hymba_fwd4Args
	.set _Z9hymba_fwd4Args.num_vgpr, 256
	.set _Z9hymba_fwd4Args.num_agpr, 0
	.set _Z9hymba_fwd4Args.numbered_sgpr, 98
	.set _Z9hymba_fwd4Args.num_named_barrier, 0
	.set _Z9hymba_fwd4Args.private_seg_size, 0
	.set _Z9hymba_fwd4Args.uses_vcc, 1
	.set _Z9hymba_fwd4Args.uses_flat_scratch, 0
	.set _Z9hymba_fwd4Args.has_dyn_sized_stack, 0
	.set _Z9hymba_fwd4Args.has_recursion, 0
	.set _Z9hymba_fwd4Args.has_indirect_call, 0

; #define LAS __attribute__((address_space(3)))
; __global__ void __launch_bounds__(512, 2) hymba_fwd(Args A) {
;     extern __shared__ __attribute__((aligned(16))) unsigned char lds_raw[];
;     LAS unsigned char* lds = (LAS unsigned char*)lds_raw;
;     cg::grid_group grid = cg::this_grid();
;     const int tid = threadIdx.x, lane = tid & 63, wave = __builtin_amdgcn_readfirstlane(tid >> 6);
amdhsa.kernels:
  - .agpr_count:     0
    .args:
      - .offset:         0
        .size:           224
        .value_kind:     by_value
      - .offset:         224
        .size:           4
        .value_kind:     hidden_block_count_x
      - .offset:         228
        .size:           4
        .value_kind:     hidden_block_count_y
      - .offset:         232
        .size:           4
        .value_kind:     hidden_block_count_z
      - .offset:         236
        .size:           2
        .value_kind:     hidden_group_size_x
      - .offset:         238
        .size:           2
        .value_kind:     hidden_group_size_y
      - .offset:         240
        .size:           2
        .value_kind:     hidden_group_size_z
      - .offset:         242
        .size:           2
        .value_kind:     hidden_remainder_x
      - .offset:         244
        .size:           2
        .value_kind:     hidden_remainder_y
      - .offset:         246
        .size:           2
        .value_kind:     hidden_remainder_z
      - .offset:         264
        .size:           8
        .value_kind:     hidden_global_offset_x
      - .offset:         272
        .size:           8
        .value_kind:     hidden_global_offset_y
      - .offset:         280
        .size:           8
        .value_kind:     hidden_global_offset_z
      - .offset:         288
        .size:           2
        .value_kind:     hidden_grid_dims
      - .offset:         312
        .size:           8
        .value_kind:     hidden_multigrid_sync_arg
      - .offset:         344
        .size:           4
        .value_kind:     hidden_dynamic_lds_size
    .group_segment_fixed_size: 0
    .kernarg_segment_align: 8
    .kernarg_segment_size: 480
    .language:       OpenCL C
    .language_version:
      - 2
      - 0
    .max_flat_workgroup_size: 512
    .name:           _Z9hymba_fwd4Args
    .private_segment_fixed_size: 0
    .sgpr_count:     104
    .sgpr_spill_count: 105
    .symbol:         _Z9hymba_fwd4Args.kd
    .uniform_work_group_size: 1
    .uses_dynamic_stack: false
    .vgpr_count:     256
    .vgpr_spill_count: 0
    .wavefront_size: 64
